# gMLP units moved to the workgroups with the lighter attention share (two units each), dead m0 save/restore removed around LDS-DMA loads, on top of the EpiUp and attention-prefetch changes
# speedup vs baseline: 1.0286x; 1.0045x over previous
; #define PG8_BAR __builtin_amdgcn_s_barrier()
;     __device__ bool next(int i, Unit& u) const {
;         const long L = (long)i * G + c; if (L >= (long)nwg * rep) return false;
;         int wgid = (int)(L % nwg); { const int q = nwg / NXCD, r = nwg % NXCD, xcd = wgid % NXCD, off = wgid / NXCD; wgid = (xcd < r ? xcd * (q + 1) : r * (q + 1) + (xcd - r) * q) + off; }
;         const int nig = WGM * nN, gid = wgid / nig, fm = gid * WGM, gsz = (nM - fm) < WGM ? (nM - fm) : WGM;
;         u.pm = pm0 + fm + ((wgid % nig) % gsz); u.pn = (wgid % nig) / gsz; return true;
;     }
; template <class Epi, class Sched>
; __device__ __forceinline__ void gemm_phase(LAS unsigned char* lds, const Gemm g, const Sched& S, const Epi& E) {
;     ...
;     for (int i = 0; i < 2; ++i) { int R, C; stage_rc(tid * 16 + i * 8192, R, C);
;         const int Ra = 128 * (R >> 6) + (R & 63);
;         const int Rb = Epi::HEADPERM ? (64 * (R >> 5) + perm32(R & 31)) : ((R & ~31) + perm32(R & 31));
;         voffA[i] = (unsigned)(Ra * g.lda + C) * 2u; voffB[i] = (unsigned)(Rb * K + C) * 2u; }
;     const size_t kstep = (size_t)(BK * 2);
;     const size_t hstepA = (size_t)64 * g.lda * 2, kstepA = (size_t)g.kstepA;
;     const size_t hstepB = (size_t)(Epi::HEADPERM ? 32 : 128) * K * 2;
;     const size_t tstep = (size_t)256 * K * 2;
;     const unsigned ldsw = (unsigned)wid * 1024u;
;     const unsigned lds_u32 = (unsigned)(size_t)lds;
;     const int aoff = lds_byte(wr * 64 + fr, fq * 8), boff = lds_byte(wc * 32 + fr, fq * 8);
;     ...
;     Unit cur, nxt; int ui = 0;
;     if (!S.next(0, cur)) return;
;     f32x4 acc[2][2][4][2];
; #pragma unroll
;     for (int a = 0; a < 2; ++a)
; #pragma unroll
;         for (int b = 0; b < 2; ++b)
; #pragma unroll
;             for (int m = 0; m < 4; ++m)
; #pragma unroll
;                 for (int n = 0; n < 2; ++n) acc[a][b][m][n] = (f32x4){0.f, 0.f, 0.f, 0.f};
;     bf16x8 At[4][2], B0[2][2], B1[2][2];
;     const char* cA = (const char*)g.A + (size_t)cur.pm * tstep; const char* cB = (const char*)g.Bt + (size_t)cur.pn * tstep;
;     PG8_STAGE(PG8_SB(0, 0), cB, voffB); PG8_STAGE(PG8_SB(0, 1), cB + hstepB, voffB); PG8_STAGE(PG8_SA(0, 0), cA, voffA); PG8_STAGE(PG8_SA(0, 1), cA + hstepA, voffA);
;     if (wr == 1) PG8_BAR;
.LBB0_86:
	s_or_b64 exec, exec, s[0:1]
	s_add_u32 s42, s84, 0x2000000
	s_addc_u32 s43, s85, 0
	s_add_u32 s46, s84, 0x6000000
	s_addc_u32 s47, s85, 0
	s_add_u32 s50, s84, 0x8000000
	s_addc_u32 s51, s85, 0
	s_add_u32 s52, s84, 0xa000000
	s_addc_u32 s53, s85, 0
	s_waitcnt lgkmcnt(0)
	v_mov_b32_e32 v2, v0
	s_ashr_i32 s33, s2, 31
	s_barrier
	s_cmpk_gt_i32 s2, 0x4ff
	v_readfirstlane_b32 s5, v2
	s_cbranch_scc1 .LBB0_112
	v_bfe_i32 v5, v2, 27, 1
	v_lshlrev_b32_e32 v3, 4, v2
	v_lshrrev_b32_e32 v5, 22, v5
	v_add_u32_e32 v5, v3, v5
	v_and_b32_e32 v5, 0xfffffc00, v5
	v_sub_u32_e32 v5, v3, v5
	v_ashrrev_i32_e32 v4, 31, v2
	v_lshrrev_b32_e32 v6, 4, v5
	v_lshrrev_b32_e32 v4, 26, v4
	v_bitop3_b32 v5, v6, v5, 32 bitop3:0x6c
	v_add_u32_e32 v4, v2, v4
	v_ashrrev_i32_e32 v7, 31, v5
	v_ashrrev_i32_e32 v4, 6, v4
	v_lshrrev_b32_e32 v7, 26, v7
	v_lshlrev_b32_e32 v6, 3, v4
	v_add_u32_e32 v7, v5, v7
	v_and_b32_e32 v6, -16, v6
	v_ashrrev_i32_e32 v8, 6, v7
	v_and_b32_e32 v7, 0xc0, v7
	v_add_u32_e32 v6, v8, v6
	v_sub_u32_e32 v5, v5, v7
	v_mov_b32_e32 v7, 1
	v_lshlrev_b32_e32 v4, 5, v4
	v_ashrrev_i16_sdwa v5, v7, sext(v5) dst_sel:DWORD dst_unused:UNUSED_PAD src0_sel:DWORD src1_sel:BYTE_0
	v_lshlrev_b32_e32 v9, 1, v6
	v_and_b32_e32 v10, 63, v6
	s_mov_b32 s0, 0x1fff80
	v_lshrrev_b32_e32 v6, 2, v6
	v_and_b32_e32 v4, 32, v4
	v_bfe_i32 v5, v5, 0, 16
	v_and_or_b32 v10, v9, s0, v10
	v_and_b32_e32 v6, 4, v6
	v_and_b32_e32 v8, 3, v8
	v_and_b32_e32 v9, 0x1fffd8, v9
	v_or3_b32 v6, v8, v6, v9
	v_add_lshl_u32 v4, v4, v5, 1
	v_add_u32_e32 v3, 0x2000, v3
	v_lshl_add_u32 v131, v10, 11, v4
	v_lshl_add_u32 v144, v6, 11, v4
	v_ashrrev_i32_e32 v4, 31, v3
	v_lshrrev_b32_e32 v4, 22, v4
	v_add_u32_e32 v4, v3, v4
	v_ashrrev_i32_e32 v4, 10, v4
	v_mul_i32_i24_e32 v5, 0x400, v4
	v_sub_u32_e32 v3, v3, v5
	v_lshrrev_b32_e32 v5, 4, v3
	v_bitop3_b32 v3, v5, v3, 32 bitop3:0x6c
	v_ashrrev_i32_e32 v6, 31, v3
	v_lshrrev_b32_e32 v6, 26, v6
	v_lshlrev_b32_e32 v5, 3, v4
	v_add_u32_e32 v6, v3, v6
	v_and_b32_e32 v5, -16, v5
	v_ashrrev_i32_e32 v8, 6, v6
	v_and_b32_e32 v6, 0xc0, v6
	v_add_u32_e32 v5, v8, v5
	v_sub_u32_e32 v3, v3, v6
	v_ashrrev_i16_sdwa v3, v7, sext(v3) dst_sel:DWORD dst_unused:UNUSED_PAD src0_sel:DWORD src1_sel:BYTE_0
	v_lshlrev_b32_e32 v6, 1, v5
	v_and_b32_e32 v7, 63, v5
	v_and_or_b32 v7, v6, s0, v7
	s_mul_hi_i32 s0, s2, 0x66666667
	s_lshr_b32 s1, s0, 31
	s_lshr_b32 s0, s0, 9
	s_add_i32 s0, s0, s1
	s_mulk_i32 s0, 0x500
	s_sub_i32 s0, s2, s0
	s_sext_i32_i16 s1, s0
	s_bfe_u32 s1, s1, 0x3001c
	s_add_i32 s1, s0, s1
	s_sext_i32_i16 s4, s1
	s_and_b32 s1, s1, 0xfff8
	s_ashr_i32 s8, s5, 6
	s_sub_i32 s0, s0, s1
	s_ashr_i32 s11, s5, 8
	s_lshl_b32 s10, s8, 10
	s_ashr_i32 s4, s4, 3
	s_sext_i32_i16 s1, s0
	s_cmp_lt_i32 s1, 0
	s_movk_i32 s21, 0xa1
	s_cselect_b32 s1, s21, 0xa0
	s_mul_i32 s0, s0, s1
	s_add_i32 s0, s0, s4
	s_sext_i32_i16 s1, s0
	s_mulk_i32 s1, 0x6667
	s_lshr_b32 s4, s1, 31
	s_ashr_i32 s1, s1, 21
	s_add_i32 s1, s1, s4
	s_lshl_b32 s9, s1, 3
	s_mulk_i32 s1, 0x50
	s_sub_i32 s0, s0, s1
	s_bfe_i32 s1, s0, 0x80000
	s_bfe_u32 s1, s1, 0x3000c
	s_add_i32 s1, s0, s1
	s_bfe_i32 s4, s1, 0x80000
	s_and_b32 s1, s1, 0xf8
	s_sub_i32 s0, s0, s1
	s_sext_i32_i16 s4, s4
	s_sext_i32_i8 s0, s0
	s_lshr_b32 s4, s4, 3
	s_add_i32 s18, s9, s0
	s_ashr_i32 s19, s18, 31
	s_bfe_i64 s[12:13], s[4:5], 0x100000
	s_lshl_b64 s[0:1], s[18:19], 19
	s_lshl_b64 s[12:13], s[12:13], 19
	v_lshlrev_b32_e32 v4, 5, v4
	v_lshrrev_b32_e32 v5, 2, v5
	s_add_u32 s26, s6, s12
	v_and_b32_e32 v4, 32, v4
	v_bfe_i32 v3, v3, 0, 16
	v_and_b32_e32 v5, 4, v5
	v_and_b32_e32 v8, 3, v8
	v_and_b32_e32 v6, 0x1fffd8, v6
	s_addc_u32 s27, s7, s13
	s_add_i32 s12, s10, 0
	v_or3_b32 v5, v8, v5, v6
	v_add_lshl_u32 v3, v4, v3, 1
	s_add_i32 s13, s12, 0x10000
	s_mov_b32 m0, s13
	s_nop 0
	global_load_lds_dwordx4 v144, s[26:27]
	s_add_i32 s14, s12, 0x12000
	s_add_i32 s15, s12, 0x14000
	v_lshl_add_u32 v146, v5, 11, v3
	s_mov_b32 m0, s14
	s_nop 0
	global_load_lds_dwordx4 v146, s[26:27]
	s_add_u32 s24, s26, 0x10000
	s_addc_u32 s25, s27, 0
	s_mov_b32 m0, s15
	s_nop 0
	global_load_lds_dwordx4 v144, s[24:25]
	s_add_i32 s16, s12, 0x16000
	s_mov_b32 m0, s16
	s_nop 0
	global_load_lds_dwordx4 v146, s[24:25]
	s_add_u32 s24, s42, s0
	s_addc_u32 s25, s43, s1
	s_mov_b32 m0, s12
	s_nop 0
	global_load_lds_dwordx4 v131, s[24:25]
	s_add_i32 s17, s12, 0x2000
	s_add_i32 s19, s12, 0x4000
	v_lshl_add_u32 v145, v7, 11, v3
	s_mov_b32 m0, s17
	s_nop 0
	global_load_lds_dwordx4 v145, s[24:25]
	s_add_u32 s30, s24, 0x20000
	s_addc_u32 s31, s25, 0
	s_mov_b32 m0, s19
	s_nop 0
	global_load_lds_dwordx4 v131, s[30:31]
	s_add_i32 s28, s12, 0x6000
	s_mov_b32 m0, s28
	s_nop 0
	global_load_lds_dwordx4 v145, s[30:31]
	s_cmp_eq_u32 s11, 1
	s_mov_b32 s20, 0
	s_mov_b32 s22, 0x10000
	s_mov_b32 s23, 0x14000
	s_movk_i32 s36, 0x4000
	s_cselect_b64 s[0:1], -1, 0
	s_cmp_lg_u32 s11, 1
	s_cbranch_scc1 .LBB0_89
	s_barrier
; #define PG8_WAIT_V(n) asm volatile("s_waitcnt vmcnt(" #n ")" ::: "memory")
; #define PG8_BAR __builtin_amdgcn_s_barrier()
; template <class Epi, class Sched>
; __device__ __forceinline__ void gemm_phase(LAS unsigned char* lds, const Gemm g, const Sched& S, const Epi& E) {
;     ...
;     const unsigned ldsw = (unsigned)wid * 1024u;
;     const unsigned lds_u32 = (unsigned)(size_t)lds;
;     const int aoff = lds_byte(wr * 64 + fr, fq * 8), boff = lds_byte(wc * 32 + fr, fq * 8);
;     ...
;     PG8_WAIT_V(2); PG8_BAR;
;     PG8_STAGE(PG8_SB(1, 0), cB + kstep, voffB); PG8_STAGE(PG8_SA(1, 0), cA + kstepA, voffA); PG8_STAGE(PG8_SB(1, 1), cB + hstepB + kstep, voffB);
;     PG8_WAIT_V(6); PG8_BAR;
.LBB0_89:
	v_bfe_u32 v5, v2, 4, 2
	v_and_b32_e32 v4, 15, v2
	v_lshlrev_b32_e32 v3, 4, v5
	v_lshlrev_b32_e32 v2, 2, v2
	s_sext_i32_i8 s60, s4
	s_and_b32 s37, s8, 3
	v_lshl_or_b32 v3, v4, 6, v3
	s_lshl_b32 s4, s11, 13
	v_and_b32_e32 v2, 32, v2
	v_bitop3_b32 v6, v3, s4, v2 bitop3:0xde
	s_lshl_b32 s4, s37, 12
	v_bitop3_b32 v7, v3, s4, v2 bitop3:0xde
	s_add_i32 s4, s12, 0x18000
	s_add_u32 s8, s26, 0x80
	s_waitcnt vmcnt(2)
	s_barrier
	s_addc_u32 s9, s27, 0
	v_mov_b32_e32 v147, s4
	s_mov_b32 m0, s4
	s_nop 0
	global_load_lds_dwordx4 v144, s[8:9]
	s_add_i32 s4, s12, 0x1a000
	v_mov_b32_e32 v148, s4
	s_mov_b32 m0, s4
	s_nop 0
	global_load_lds_dwordx4 v146, s[8:9]
	s_add_i32 s4, s12, 0x8000
	s_add_u32 s8, s24, 0x80
	s_addc_u32 s9, s25, 0
	v_mov_b32_e32 v149, s4
	s_mov_b32 m0, s4
	s_nop 0
	global_load_lds_dwordx4 v131, s[8:9]
	s_add_i32 s4, s12, 0xa000
	v_mov_b32_e32 v150, s4
	s_mov_b32 m0, s4
	s_nop 0
	global_load_lds_dwordx4 v145, s[8:9]
	s_add_i32 s4, s12, 0x1c000
	s_add_u32 s8, s26, 0x10080
	s_addc_u32 s9, s27, 0
	v_mov_b32_e32 v151, s4
	s_mov_b32 m0, s4
	s_nop 0
	global_load_lds_dwordx4 v144, s[8:9]
	s_add_i32 s4, s12, 0x1e000
	v_mov_b32_e32 v152, s4
	s_mov_b32 m0, s4
	s_nop 0
	global_load_lds_dwordx4 v146, s[8:9]
	s_add_i32 s4, s12, 0xc000
	s_cmpk_lt_u32 s5, 0x100
	s_cselect_b64 s[8:9], -1, 0
	s_lshl_b32 s5, s11, 7
	v_lshlrev_b32_e32 v2, 10, v4
	s_ashr_i32 s29, s5, 31
	v_lshlrev_b32_e32 v130, 3, v5
	s_waitcnt vmcnt(6)
	v_lshl_add_u32 v153, s11, 6, v2
	v_or_b32_e32 v2, s5, v4
	v_mov_b32_e32 v3, s29
	v_mov_b32_e32 v133, 0
	v_lshlrev_b64 v[134:135], 10, v[2:3]
	v_lshlrev_b32_e32 v132, 7, v5
	v_lshl_or_b32 v2, s37, 6, v130
	v_add_u32_e32 v3, 0, v7
	s_mov_b32 s38, 0x18000
	s_mov_b32 s39, 0x8000
	s_mov_b32 s48, 0x1c000
	s_mov_b32 s49, 0xc000
	v_lshlrev_b32_e32 v154, 7, v4
	s_lshl_b32 s58, s11, 3
	s_ashr_i32 s59, s3, 31
	v_lshl_add_u64 v[136:137], s[52:53], 0, v[132:133]
	v_mov_b64_e32 v[138:139], 0x500
	v_mov_b64_e32 v[140:141], 0x4ff
	v_add_u32_e32 v155, 0x10000, v3
	v_add_u32_e32 v156, 0x14000, v3
	v_add_u32_e32 v157, 0, v6
	v_mov_b32_e32 v158, s4
	v_mov_b32_e32 v159, s10
	v_mov_b32_e32 v160, s13
	v_mov_b32_e32 v161, s14
	v_mov_b32_e32 v162, s15
	v_mov_b32_e32 v163, s16
	v_mov_b32_e32 v164, s12
	v_mov_b32_e32 v165, s17
	v_add_u32_e32 v166, 0x18000, v3
	v_add_u32_e32 v167, 0x1c000, v3
	v_mov_b32_e32 v168, s19
	v_mov_b32_e32 v169, s28
	v_lshlrev_b32_e32 v170, 1, v2
	v_mov_b32_e32 v171, 0x358637bd
	v_mov_b32_e32 v172, 0x3e38aa3b
	s_barrier
	s_branch .LBB0_92

; #define PG8_LDA(dst, b, h) do { _Pragma("unroll") for (int m = 0; m < 4; ++m) _Pragma("unroll") for (int k = 0; k < 2; ++k) dst[m][k] = *(const LAS bf16x8*)(lds + PG8_SA(b, h) + aoff + m * 2048 + k * 1024); } while (0)
; #define PG8_LDB(dst, b, h) do { _Pragma("unroll") for (int n = 0; n < 2; ++n) _Pragma("unroll") for (int k = 0; k < 2; ++k) dst[n][k] = *(const LAS bf16x8*)(lds + PG8_SB(b, h) + boff + n * 2048 + k * 1024); } while (0)
; #define PG8_MMA(ai, bj, At, Bt) do { __builtin_amdgcn_s_setprio(1); _Pragma("unroll") for (int m = 0; m < 4; ++m) _Pragma("unroll") for (int n = 0; n < 2; ++n) _Pragma("unroll") for (int k = 0; k < 2; ++k) \
;         acc[ai][bj][m][n] = __builtin_amdgcn_mfma_f32_16x16x32_bf16(Bt[n][k], At[m][k], acc[ai][bj][m][n], 0, 0, 0); __builtin_amdgcn_s_setprio(0); } while (0)
; #define PG8_WAIT_V(n) asm volatile("s_waitcnt vmcnt(" #n ")" ::: "memory")
; #define PG8_WAIT_L(n) asm volatile("s_waitcnt lgkmcnt(" #n ")" ::: "memory")
; #define PG8_BAR __builtin_amdgcn_s_barrier()
; #define PG8_SCHED __builtin_amdgcn_sched_barrier(0)
; template <class Epi, class Sched>
; __device__ __forceinline__ void gemm_phase(LAS unsigned char* lds, const Gemm g, const Sched& S, const Epi& E) {
;     ...
;         for (int t = 0; t < nt; t += 2) {
;             const bool last = (t == nt - 2);
;             if constexpr (Epi::MID) { if (t == nt / 2) E.mid(acc, cur, wr, wc, fr, fq); }
;             const char* a1 = cA + (size_t)(t + 1) * kstepA;
;             const char* a2 = last ? nA : cA + (size_t)(t + 2) * kstepA; const char* b2 = last ? nB : cB + (size_t)(t + 2) * kstep;
;             const char* a3 = a2 + kstepA; const char* b3 = b2 + kstep;
;             PG8_LDB(B0, 0, 0); PG8_LDB(B1, 0, 1); PG8_SCHED; PG8_LDA(At, 0, 0); PG8_STAGE(PG8_SA(1, 1), a1 + hstepA, voffA);
;             PG8_WAIT_V(8); PG8_WAIT_L(0); PG8_BAR; PG8_MMA(0, 0, At, B0); PG8_MMA(0, 1, At, B1); PG8_BAR; PG8_SCHED;
;             PG8_LDA(At, 0, 1); PG8_STAGE(PG8_SB(0, 0), b2, voffB); PG8_STAGE(PG8_SB(0, 1), b2 + hstepB, voffB); PG8_STAGE(PG8_SA(0, 0), a2, voffA);
;             PG8_WAIT_V(8); PG8_WAIT_L(0); PG8_BAR; PG8_MMA(1, 0, At, B0); PG8_MMA(1, 1, At, B1); PG8_BAR; PG8_SCHED;
.LBB0_95:
	ds_read_b128 v[174:177], v155
	ds_read_b128 v[178:181], v155 offset:1024
	ds_read_b128 v[182:185], v155 offset:2048
	ds_read_b128 v[186:189], v155 offset:3072
	ds_read_b128 v[190:193], v156
	ds_read_b128 v[194:197], v156 offset:1024
	ds_read_b128 v[202:205], v156 offset:2048
	ds_read_b128 v[206:209], v156 offset:3072
	s_add_u32 s26, s24, 0x100
	s_addc_u32 s27, s25, 0
	s_cmp_eq_u32 s62, 12
	s_cselect_b32 s34, s19, s26
	s_cselect_b32 s35, s11, s27
	s_cselect_b32 s30, s56, s57
	s_cselect_b32 s31, s13, s61
	s_add_u32 s28, s34, 0x80
	s_addc_u32 s29, s35, 0
	ds_read_b128 v[210:213], v157
	ds_read_b128 v[214:217], v157 offset:1024
	ds_read_b128 v[218:221], v157 offset:2048
	ds_read_b128 v[222:225], v157 offset:3072
	ds_read_b128 v[226:229], v157 offset:4096
	ds_read_b128 v[230:233], v157 offset:5120
	ds_read_b128 v[234:237], v157 offset:6144
	ds_read_b128 v[238:241], v157 offset:7168
	s_add_u32 s24, s24, 0x20080
	v_readfirstlane_b32 s63, v158
	s_addc_u32 s25, s25, 0
	s_mov_b32 m0, s63
	s_nop 0
	global_load_lds_dwordx4 v131, s[24:25]
	v_readfirstlane_b32 s63, v159
	s_add_i32 s63, s63, 0
	s_add_i32 s63, s63, 0xe000
	s_mov_b32 m0, s63
	s_nop 0
	global_load_lds_dwordx4 v145, s[24:25]
	s_waitcnt vmcnt(8)
	s_waitcnt lgkmcnt(0)
	s_barrier
	s_setprio 1
	s_waitcnt lgkmcnt(7)
	v_mfma_f32_16x16x32_bf16 v[126:129], v[174:177], v[210:213], v[126:129]
	v_mfma_f32_16x16x32_bf16 v[122:125], v[182:185], v[210:213], v[122:125]
	s_waitcnt lgkmcnt(5)
	v_mfma_f32_16x16x32_bf16 v[110:113], v[174:177], v[218:221], v[110:113]
	v_mfma_f32_16x16x32_bf16 v[106:109], v[182:185], v[218:221], v[106:109]
	s_waitcnt lgkmcnt(3)
	v_mfma_f32_16x16x32_bf16 v[94:97], v[174:177], v[226:229], v[94:97]
	v_mfma_f32_16x16x32_bf16 v[90:93], v[182:185], v[226:229], v[90:93]
	s_waitcnt lgkmcnt(1)
	v_mfma_f32_16x16x32_bf16 v[78:81], v[174:177], v[234:237], v[78:81]
	v_mfma_f32_16x16x32_bf16 v[74:77], v[182:185], v[234:237], v[74:77]
	v_mfma_f32_16x16x32_bf16 v[126:129], v[178:181], v[214:217], v[126:129]
	v_mfma_f32_16x16x32_bf16 v[122:125], v[186:189], v[214:217], v[122:125]
	v_mfma_f32_16x16x32_bf16 v[110:113], v[178:181], v[222:225], v[110:113]
	v_mfma_f32_16x16x32_bf16 v[106:109], v[186:189], v[222:225], v[106:109]
	v_mfma_f32_16x16x32_bf16 v[94:97], v[178:181], v[230:233], v[94:97]
	v_mfma_f32_16x16x32_bf16 v[90:93], v[186:189], v[230:233], v[90:93]
	s_waitcnt lgkmcnt(0)
	v_mfma_f32_16x16x32_bf16 v[78:81], v[178:181], v[238:241], v[78:81]
	v_mfma_f32_16x16x32_bf16 v[74:77], v[186:189], v[238:241], v[74:77]
	s_setprio 0
	s_setprio 1
	v_mfma_f32_16x16x32_bf16 v[118:121], v[190:193], v[210:213], v[118:121]
	v_mfma_f32_16x16x32_bf16 v[114:117], v[202:205], v[210:213], v[114:117]
	v_mfma_f32_16x16x32_bf16 v[102:105], v[190:193], v[218:221], v[102:105]
	v_mfma_f32_16x16x32_bf16 v[98:101], v[202:205], v[218:221], v[98:101]
	v_mfma_f32_16x16x32_bf16 v[86:89], v[190:193], v[226:229], v[86:89]
	v_mfma_f32_16x16x32_bf16 v[82:85], v[202:205], v[226:229], v[82:85]
	v_mfma_f32_16x16x32_bf16 v[70:73], v[190:193], v[234:237], v[70:73]
	v_mfma_f32_16x16x32_bf16 v[66:69], v[202:205], v[234:237], v[66:69]
	v_mfma_f32_16x16x32_bf16 v[118:121], v[194:197], v[214:217], v[118:121]
	v_mfma_f32_16x16x32_bf16 v[114:117], v[206:209], v[214:217], v[114:117]
	v_mfma_f32_16x16x32_bf16 v[102:105], v[194:197], v[222:225], v[102:105]
	v_mfma_f32_16x16x32_bf16 v[98:101], v[206:209], v[222:225], v[98:101]
	v_mfma_f32_16x16x32_bf16 v[86:89], v[194:197], v[230:233], v[86:89]
	v_mfma_f32_16x16x32_bf16 v[82:85], v[206:209], v[230:233], v[82:85]
	v_mfma_f32_16x16x32_bf16 v[70:73], v[194:197], v[238:241], v[70:73]
	v_mfma_f32_16x16x32_bf16 v[66:69], v[206:209], v[238:241], v[66:69]
	s_setprio 0
	s_barrier
	ds_read_b128 v[210:213], v157 offset:16384
	ds_read_b128 v[214:217], v157 offset:17408
	ds_read_b128 v[218:221], v157 offset:18432
	ds_read_b128 v[222:225], v157 offset:19456
	ds_read_b128 v[226:229], v157 offset:20480
	ds_read_b128 v[230:233], v157 offset:21504
	ds_read_b128 v[234:237], v157 offset:22528
	ds_read_b128 v[238:241], v157 offset:23552
	v_readfirstlane_b32 s24, v160
	s_mov_b32 m0, s24
	s_nop 0
	global_load_lds_dwordx4 v144, s[30:31]
	v_readfirstlane_b32 s24, v161
	s_mov_b32 m0, s24
	s_nop 0
	global_load_lds_dwordx4 v146, s[30:31]
	s_add_u32 s24, s30, 0x10000
	s_addc_u32 s25, s31, 0
	v_readfirstlane_b32 s63, v162
	s_mov_b32 m0, s63
	s_nop 0
	global_load_lds_dwordx4 v144, s[24:25]
	v_readfirstlane_b32 s63, v163
	s_mov_b32 m0, s63
	s_nop 0
	global_load_lds_dwordx4 v146, s[24:25]
	v_readfirstlane_b32 s24, v164
	s_mov_b32 m0, s24
	s_nop 0
	global_load_lds_dwordx4 v131, s[34:35]
	v_readfirstlane_b32 s24, v165
	s_mov_b32 m0, s24
	s_nop 0
	global_load_lds_dwordx4 v145, s[34:35]
	s_waitcnt vmcnt(8)
	s_waitcnt lgkmcnt(0)
	s_barrier
; #define PG8_LDA(dst, b, h) do { _Pragma("unroll") for (int m = 0; m < 4; ++m) _Pragma("unroll") for (int k = 0; k < 2; ++k) dst[m][k] = *(const LAS bf16x8*)(lds + PG8_SA(b, h) + aoff + m * 2048 + k * 1024); } while (0)
; #define PG8_LDB(dst, b, h) do { _Pragma("unroll") for (int n = 0; n < 2; ++n) _Pragma("unroll") for (int k = 0; k < 2; ++k) dst[n][k] = *(const LAS bf16x8*)(lds + PG8_SB(b, h) + boff + n * 2048 + k * 1024); } while (0)
; #define PG8_MMA(ai, bj, At, Bt) do { __builtin_amdgcn_s_setprio(1); _Pragma("unroll") for (int m = 0; m < 4; ++m) _Pragma("unroll") for (int n = 0; n < 2; ++n) _Pragma("unroll") for (int k = 0; k < 2; ++k) \
;         acc[ai][bj][m][n] = __builtin_amdgcn_mfma_f32_16x16x32_bf16(Bt[n][k], At[m][k], acc[ai][bj][m][n], 0, 0, 0); __builtin_amdgcn_s_setprio(0); } while (0)
; #define PG8_WAIT_V(n) asm volatile("s_waitcnt vmcnt(" #n ")" ::: "memory")
; #define PG8_WAIT_L(n) asm volatile("s_waitcnt lgkmcnt(" #n ")" ::: "memory")
; #define PG8_BAR __builtin_amdgcn_s_barrier()
; #define PG8_SCHED __builtin_amdgcn_sched_barrier(0)
; template <class Epi, class Sched>
; __device__ __forceinline__ void gemm_phase(LAS unsigned char* lds, const Gemm g, const Sched& S, const Epi& E) {
;     ...
;             PG8_WAIT_V(8); PG8_WAIT_L(0); PG8_BAR; PG8_MMA(1, 0, At, B0); PG8_MMA(1, 1, At, B1); PG8_BAR; PG8_SCHED;
;             PG8_LDB(B0, 1, 0); PG8_LDB(B1, 1, 1); PG8_SCHED; PG8_LDA(At, 1, 0); PG8_STAGE(PG8_SA(0, 1), a2 + hstepA, voffA);
;             PG8_WAIT_V(8); PG8_WAIT_L(0); PG8_BAR; PG8_MMA(0, 0, At, B0); PG8_MMA(0, 1, At, B1); PG8_BAR; PG8_SCHED;
	s_setprio 1
	s_waitcnt lgkmcnt(7)
	v_mfma_f32_16x16x32_bf16 v[62:65], v[174:177], v[210:213], v[62:65]
	v_mfma_f32_16x16x32_bf16 v[58:61], v[182:185], v[210:213], v[58:61]
	s_waitcnt lgkmcnt(5)
	v_mfma_f32_16x16x32_bf16 v[46:49], v[174:177], v[218:221], v[46:49]
	v_mfma_f32_16x16x32_bf16 v[42:45], v[182:185], v[218:221], v[42:45]
	s_waitcnt lgkmcnt(3)
	v_mfma_f32_16x16x32_bf16 v[30:33], v[174:177], v[226:229], v[30:33]
	v_mfma_f32_16x16x32_bf16 v[26:29], v[182:185], v[226:229], v[26:29]
	s_waitcnt lgkmcnt(1)
	v_mfma_f32_16x16x32_bf16 v[14:17], v[174:177], v[234:237], v[14:17]
	v_mfma_f32_16x16x32_bf16 v[10:13], v[182:185], v[234:237], v[10:13]
	v_mfma_f32_16x16x32_bf16 v[62:65], v[178:181], v[214:217], v[62:65]
	v_mfma_f32_16x16x32_bf16 v[58:61], v[186:189], v[214:217], v[58:61]
	v_mfma_f32_16x16x32_bf16 v[46:49], v[178:181], v[222:225], v[46:49]
	v_mfma_f32_16x16x32_bf16 v[42:45], v[186:189], v[222:225], v[42:45]
	v_mfma_f32_16x16x32_bf16 v[30:33], v[178:181], v[230:233], v[30:33]
	v_mfma_f32_16x16x32_bf16 v[26:29], v[186:189], v[230:233], v[26:29]
	s_waitcnt lgkmcnt(0)
	v_mfma_f32_16x16x32_bf16 v[14:17], v[178:181], v[238:241], v[14:17]
	v_mfma_f32_16x16x32_bf16 v[10:13], v[186:189], v[238:241], v[10:13]
	s_setprio 0
	s_setprio 1
	v_mfma_f32_16x16x32_bf16 v[54:57], v[190:193], v[210:213], v[54:57]
	v_mfma_f32_16x16x32_bf16 v[50:53], v[202:205], v[210:213], v[50:53]
	v_mfma_f32_16x16x32_bf16 v[38:41], v[190:193], v[218:221], v[38:41]
	v_mfma_f32_16x16x32_bf16 v[34:37], v[202:205], v[218:221], v[34:37]
	v_mfma_f32_16x16x32_bf16 v[22:25], v[190:193], v[226:229], v[22:25]
	v_mfma_f32_16x16x32_bf16 v[18:21], v[202:205], v[226:229], v[18:21]
	v_mfma_f32_16x16x32_bf16 v[6:9], v[190:193], v[234:237], v[6:9]
	v_mfma_f32_16x16x32_bf16 v[2:5], v[202:205], v[234:237], v[2:5]
	v_mfma_f32_16x16x32_bf16 v[54:57], v[194:197], v[214:217], v[54:57]
	v_mfma_f32_16x16x32_bf16 v[50:53], v[206:209], v[214:217], v[50:53]
	v_mfma_f32_16x16x32_bf16 v[38:41], v[194:197], v[222:225], v[38:41]
	v_mfma_f32_16x16x32_bf16 v[34:37], v[206:209], v[222:225], v[34:37]
	v_mfma_f32_16x16x32_bf16 v[22:25], v[194:197], v[230:233], v[22:25]
	v_mfma_f32_16x16x32_bf16 v[18:21], v[206:209], v[230:233], v[18:21]
	v_mfma_f32_16x16x32_bf16 v[6:9], v[194:197], v[238:241], v[6:9]
	v_mfma_f32_16x16x32_bf16 v[2:5], v[206:209], v[238:241], v[2:5]
	s_setprio 0
	s_barrier
	ds_read_b128 v[174:177], v166
	ds_read_b128 v[178:181], v166 offset:1024
	ds_read_b128 v[182:185], v166 offset:2048
	ds_read_b128 v[186:189], v166 offset:3072
	ds_read_b128 v[190:193], v167
	ds_read_b128 v[194:197], v167 offset:1024
	ds_read_b128 v[202:205], v167 offset:2048
	ds_read_b128 v[206:209], v167 offset:3072
	ds_read_b128 v[210:213], v157 offset:32768
	ds_read_b128 v[214:217], v157 offset:33792
	ds_read_b128 v[218:221], v157 offset:34816
	ds_read_b128 v[222:225], v157 offset:35840
	ds_read_b128 v[226:229], v157 offset:36864
	ds_read_b128 v[230:233], v157 offset:37888
	ds_read_b128 v[234:237], v157 offset:38912
	ds_read_b128 v[238:241], v157 offset:39936
	s_add_u32 s24, s34, 0x20000
	s_addc_u32 s25, s35, 0
	v_readfirstlane_b32 s34, v168
	s_mov_b32 m0, s34
	s_nop 0
	global_load_lds_dwordx4 v131, s[24:25]
	v_readfirstlane_b32 s34, v169
	s_mov_b32 m0, s34
	s_nop 0
	global_load_lds_dwordx4 v145, s[24:25]
	s_waitcnt vmcnt(8)
	s_waitcnt lgkmcnt(0)
	s_barrier
	s_setprio 1
	s_waitcnt lgkmcnt(7)
	v_mfma_f32_16x16x32_bf16 v[126:129], v[174:177], v[210:213], v[126:129]
	v_mfma_f32_16x16x32_bf16 v[122:125], v[182:185], v[210:213], v[122:125]
	s_waitcnt lgkmcnt(5)
	v_mfma_f32_16x16x32_bf16 v[110:113], v[174:177], v[218:221], v[110:113]
	v_mfma_f32_16x16x32_bf16 v[106:109], v[182:185], v[218:221], v[106:109]
	s_waitcnt lgkmcnt(3)
	v_mfma_f32_16x16x32_bf16 v[94:97], v[174:177], v[226:229], v[94:97]
	v_mfma_f32_16x16x32_bf16 v[90:93], v[182:185], v[226:229], v[90:93]
	s_waitcnt lgkmcnt(1)
	v_mfma_f32_16x16x32_bf16 v[78:81], v[174:177], v[234:237], v[78:81]
	v_mfma_f32_16x16x32_bf16 v[74:77], v[182:185], v[234:237], v[74:77]
	v_mfma_f32_16x16x32_bf16 v[126:129], v[178:181], v[214:217], v[126:129]
	v_mfma_f32_16x16x32_bf16 v[122:125], v[186:189], v[214:217], v[122:125]
	v_mfma_f32_16x16x32_bf16 v[110:113], v[178:181], v[222:225], v[110:113]
	v_mfma_f32_16x16x32_bf16 v[106:109], v[186:189], v[222:225], v[106:109]
	v_mfma_f32_16x16x32_bf16 v[94:97], v[178:181], v[230:233], v[94:97]
	v_mfma_f32_16x16x32_bf16 v[90:93], v[186:189], v[230:233], v[90:93]
	s_waitcnt lgkmcnt(0)
	v_mfma_f32_16x16x32_bf16 v[78:81], v[178:181], v[238:241], v[78:81]
	v_mfma_f32_16x16x32_bf16 v[74:77], v[186:189], v[238:241], v[74:77]
	s_setprio 0
	s_setprio 1
	v_mfma_f32_16x16x32_bf16 v[118:121], v[190:193], v[210:213], v[118:121]
	v_mfma_f32_16x16x32_bf16 v[114:117], v[202:205], v[210:213], v[114:117]
	v_mfma_f32_16x16x32_bf16 v[102:105], v[190:193], v[218:221], v[102:105]
	v_mfma_f32_16x16x32_bf16 v[98:101], v[202:205], v[218:221], v[98:101]
	v_mfma_f32_16x16x32_bf16 v[86:89], v[190:193], v[226:229], v[86:89]
	v_mfma_f32_16x16x32_bf16 v[82:85], v[202:205], v[226:229], v[82:85]
	v_mfma_f32_16x16x32_bf16 v[70:73], v[190:193], v[234:237], v[70:73]
	v_mfma_f32_16x16x32_bf16 v[66:69], v[202:205], v[234:237], v[66:69]
	v_mfma_f32_16x16x32_bf16 v[118:121], v[194:197], v[214:217], v[118:121]
	v_mfma_f32_16x16x32_bf16 v[114:117], v[206:209], v[214:217], v[114:117]
	v_mfma_f32_16x16x32_bf16 v[102:105], v[194:197], v[222:225], v[102:105]
	v_mfma_f32_16x16x32_bf16 v[98:101], v[206:209], v[222:225], v[98:101]
	v_mfma_f32_16x16x32_bf16 v[86:89], v[194:197], v[230:233], v[86:89]
	v_mfma_f32_16x16x32_bf16 v[82:85], v[206:209], v[230:233], v[82:85]
	v_mfma_f32_16x16x32_bf16 v[70:73], v[194:197], v[238:241], v[70:73]
	v_mfma_f32_16x16x32_bf16 v[66:69], v[206:209], v[238:241], v[66:69]
	s_setprio 0
	s_barrier
; #define PG8_LDA(dst, b, h) do { _Pragma("unroll") for (int m = 0; m < 4; ++m) _Pragma("unroll") for (int k = 0; k < 2; ++k) dst[m][k] = *(const LAS bf16x8*)(lds + PG8_SA(b, h) + aoff + m * 2048 + k * 1024); } while (0)
; #define PG8_MMA(ai, bj, At, Bt) do { __builtin_amdgcn_s_setprio(1); _Pragma("unroll") for (int m = 0; m < 4; ++m) _Pragma("unroll") for (int n = 0; n < 2; ++n) _Pragma("unroll") for (int k = 0; k < 2; ++k) \
;         acc[ai][bj][m][n] = __builtin_amdgcn_mfma_f32_16x16x32_bf16(Bt[n][k], At[m][k], acc[ai][bj][m][n], 0, 0, 0); __builtin_amdgcn_s_setprio(0); } while (0)
; #define PG8_WAIT_V(n) asm volatile("s_waitcnt vmcnt(" #n ")" ::: "memory")
; #define PG8_WAIT_L(n) asm volatile("s_waitcnt lgkmcnt(" #n ")" ::: "memory")
; #define PG8_BAR __builtin_amdgcn_s_barrier()
; #define PG8_SCHED __builtin_amdgcn_sched_barrier(0)
; template <class Epi, class Sched>
; __device__ __forceinline__ void gemm_phase(LAS unsigned char* lds, const Gemm g, const Sched& S, const Epi& E) {
;     ...
;             PG8_LDA(At, 1, 1); PG8_STAGE(PG8_SB(1, 0), b3, voffB); PG8_STAGE(PG8_SB(1, 1), b3 + hstepB, voffB); PG8_STAGE(PG8_SA(1, 0), a3, voffA);
;             PG8_WAIT_V(8); PG8_WAIT_L(0); PG8_BAR; PG8_MMA(1, 0, At, B0); PG8_MMA(1, 1, At, B1); PG8_BAR; PG8_SCHED;
;         }
;         if (wr == 0) PG8_BAR;
	ds_read_b128 v[210:213], v157 offset:49152
	ds_read_b128 v[214:217], v157 offset:50176
	ds_read_b128 v[218:221], v157 offset:51200
	ds_read_b128 v[222:225], v157 offset:52224
	ds_read_b128 v[226:229], v157 offset:53248
	ds_read_b128 v[230:233], v157 offset:54272
	ds_read_b128 v[234:237], v157 offset:55296
	ds_read_b128 v[238:241], v157 offset:56320
	s_add_u32 s24, s30, 0x80
	s_addc_u32 s25, s31, 0
	v_readfirstlane_b32 s34, v147
	s_mov_b32 m0, s34
	s_nop 0
	global_load_lds_dwordx4 v144, s[24:25]
	v_readfirstlane_b32 s34, v148
	s_mov_b32 m0, s34
	s_nop 0
	global_load_lds_dwordx4 v146, s[24:25]
	s_add_u32 s24, s30, 0x10080
	s_addc_u32 s25, s31, 0
	v_readfirstlane_b32 s30, v151
	s_mov_b32 m0, s30
	s_nop 0
	global_load_lds_dwordx4 v144, s[24:25]
	v_readfirstlane_b32 s30, v152
	s_mov_b32 m0, s30
	s_nop 0
	global_load_lds_dwordx4 v146, s[24:25]
	v_readfirstlane_b32 s24, v149
	s_mov_b32 m0, s24
	s_nop 0
	global_load_lds_dwordx4 v131, s[28:29]
	v_readfirstlane_b32 s24, v150
	s_mov_b32 m0, s24
	s_nop 0
	global_load_lds_dwordx4 v145, s[28:29]
	s_waitcnt vmcnt(8)
	s_waitcnt lgkmcnt(0)
	s_barrier
	s_setprio 1
	s_waitcnt lgkmcnt(7)
	v_mfma_f32_16x16x32_bf16 v[62:65], v[174:177], v[210:213], v[62:65]
	v_mfma_f32_16x16x32_bf16 v[58:61], v[182:185], v[210:213], v[58:61]
	s_waitcnt lgkmcnt(5)
	v_mfma_f32_16x16x32_bf16 v[46:49], v[174:177], v[218:221], v[46:49]
	v_mfma_f32_16x16x32_bf16 v[42:45], v[182:185], v[218:221], v[42:45]
	s_waitcnt lgkmcnt(3)
	v_mfma_f32_16x16x32_bf16 v[30:33], v[174:177], v[226:229], v[30:33]
	v_mfma_f32_16x16x32_bf16 v[26:29], v[182:185], v[226:229], v[26:29]
	s_waitcnt lgkmcnt(1)
	v_mfma_f32_16x16x32_bf16 v[14:17], v[174:177], v[234:237], v[14:17]
	v_mfma_f32_16x16x32_bf16 v[10:13], v[182:185], v[234:237], v[10:13]
	v_mfma_f32_16x16x32_bf16 v[62:65], v[178:181], v[214:217], v[62:65]
	v_mfma_f32_16x16x32_bf16 v[58:61], v[186:189], v[214:217], v[58:61]
	v_mfma_f32_16x16x32_bf16 v[46:49], v[178:181], v[222:225], v[46:49]
	v_mfma_f32_16x16x32_bf16 v[42:45], v[186:189], v[222:225], v[42:45]
	v_mfma_f32_16x16x32_bf16 v[30:33], v[178:181], v[230:233], v[30:33]
	v_mfma_f32_16x16x32_bf16 v[26:29], v[186:189], v[230:233], v[26:29]
	s_waitcnt lgkmcnt(0)
	v_mfma_f32_16x16x32_bf16 v[14:17], v[178:181], v[238:241], v[14:17]
	v_mfma_f32_16x16x32_bf16 v[10:13], v[186:189], v[238:241], v[10:13]
	s_setprio 0
	s_setprio 1
	v_mfma_f32_16x16x32_bf16 v[54:57], v[190:193], v[210:213], v[54:57]
	v_mfma_f32_16x16x32_bf16 v[50:53], v[202:205], v[210:213], v[50:53]
	v_mfma_f32_16x16x32_bf16 v[38:41], v[190:193], v[218:221], v[38:41]
	v_mfma_f32_16x16x32_bf16 v[34:37], v[202:205], v[218:221], v[34:37]
	v_mfma_f32_16x16x32_bf16 v[22:25], v[190:193], v[226:229], v[22:25]
	v_mfma_f32_16x16x32_bf16 v[18:21], v[202:205], v[226:229], v[18:21]
	v_mfma_f32_16x16x32_bf16 v[6:9], v[190:193], v[234:237], v[6:9]
	v_mfma_f32_16x16x32_bf16 v[2:5], v[202:205], v[234:237], v[2:5]
	v_mfma_f32_16x16x32_bf16 v[54:57], v[194:197], v[214:217], v[54:57]
	v_mfma_f32_16x16x32_bf16 v[50:53], v[206:209], v[214:217], v[50:53]
	v_mfma_f32_16x16x32_bf16 v[38:41], v[194:197], v[222:225], v[38:41]
	v_mfma_f32_16x16x32_bf16 v[34:37], v[206:209], v[222:225], v[34:37]
	v_mfma_f32_16x16x32_bf16 v[22:25], v[194:197], v[230:233], v[22:25]
	v_mfma_f32_16x16x32_bf16 v[18:21], v[206:209], v[230:233], v[18:21]
	v_mfma_f32_16x16x32_bf16 v[6:9], v[194:197], v[238:241], v[6:9]
	v_mfma_f32_16x16x32_bf16 v[2:5], v[206:209], v[238:241], v[2:5]
	s_setprio 0
	s_barrier
	s_add_i32 s62, s62, 2
	s_add_u32 s57, s57, 0x100
	s_addc_u32 s61, s61, 0
	s_cmp_gt_u32 s62, 13
	s_mov_b64 s[24:25], s[26:27]
	s_cbranch_scc0 .LBB0_95
	s_and_b64 vcc, exec, s[8:9]
	s_cbranch_vccz .LBB0_98
	s_barrier

; #define LAS __attribute__((address_space(3)))
; __device__ __forceinline__ unsigned pk2(float lo, float hi) { f32x2 v = {lo, hi}; bf16x2_t b = __builtin_convertvector(v, bf16x2_t); return __builtin_bit_cast(unsigned, b); }
; __device__ __forceinline__ void gmlp_unit(const GmlpP& P, int b, int ch, LAS unsigned char* lds, int wave, int lane_in) {
;     ...
;     __syncthreads();
; #pragma unroll
;     for (int nt = 0; nt < 2; ++nt) {
;         const int t = 32 * (nt == 0 ? tt0 : tt1) + r32;
;         const float tot = (ssqg[t] + ssqg[128 + t]) + (ssqg[256 + t] + ssqg[384 + t]);
;         const float r = __builtin_amdgcn_rsqf(tot * (1.0f / GW) + EPS);
;         bf16_t* op = P.MIX + (tok0 + t) * DM + AW + gI * 128 + 4 * h;
; #pragma unroll
;         for (int mt = 0; mt < 4; ++mt)
; #pragma unroll
;             for (int e4 = 0; e4 < 4; ++e4) {
;                 const f32x4 gg = *(const LAS f32x4*)(lds + LDS_GG + (gI * 128 + 32 * mt + 8 * e4 + 4 * h) * 4);
;                 u32x2 w; w.x = pk2(acc[mt][nt][4 * e4] * r * gg[0], acc[mt][nt][4 * e4 + 1] * r * gg[1]); w.y = pk2(acc[mt][nt][4 * e4 + 2] * r * gg[2], acc[mt][nt][4 * e4 + 3] * r * gg[3]);
;                 *(u32x2*)(op + 32 * mt + 8 * e4) = w;
; __global__ void __launch_bounds__(512, 2) mk_fwd(Args args) {
;     ...
;         const GmlpP GP{Ub, Gb, MIX, ln_v_g, ln_v_b, Wsb, b_sp, gmlp_out_g};
;         for (int a = bx; a < 256 * REP_GM; a += G) gmlp_unit(GP, (a & 255) >> 4, a & 15, lds, wave, lane);
.LBB0_535:
	s_add_u32 s0, s84, 0x1b00000
	v_readlane_b32 s4, v243, 24
	s_addc_u32 s1, s85, 0
	s_and_b32 s6, s4, 0xffffff80
	v_readlane_b32 s56, v243, 4
	s_ashr_i32 s7, s6, 31
	v_readlane_b32 s66, v243, 14
	v_readlane_b32 s67, v243, 15
	s_bfe_u32 s14, s4, 0x10006
	s_and_b32 s18, s4, 0xffffffc0
	s_lshl_b64 s[4:5], s[6:7], 2
	s_mov_b64 s[22:23], s[66:67]
	v_readlane_b32 s68, v243, 16
	v_readlane_b32 s69, v243, 17
	s_add_u32 s8, s22, s4
	s_mov_b64 s[24:25], s[68:69]
	s_addc_u32 s9, s23, s5
	s_add_u32 s10, s24, s4
	s_addc_u32 s11, s25, s5
	s_lshl_b32 s20, s14, 6
	s_lshl_b64 s[16:17], s[6:7], 1
	s_add_u32 s15, s84, s16
	s_addc_u32 s19, s85, s17
	s_add_u32 s12, s15, 0xe000000
	s_addc_u32 s13, s19, 0
	s_lshl_b32 s21, s14, 5
	s_xor_b32 s23, s21, 0x60
	s_or_b32 s22, s6, s21
	s_or_b32 s25, s23, s18
	s_add_u32 s14, s15, 0xc000000
	v_mov_b32_e32 v141, 0
	s_addc_u32 s15, s19, 0
	s_or_b32 s28, s18, 0x60
	s_or_b32 s29, s6, 32
	s_or_b32 s30, s18, 64
	s_xor_b32 s31, s21, 32
	v_readlane_b32 s18, v243, 20
	s_movk_i32 s4, 0x80
	v_lshlrev_b32_e32 v138, 4, v0
	v_mov_b32_e32 v139, v141
	v_readlane_b32 s19, v243, 21
	s_add_u32 s16, s18, s16
	v_readlane_b32 s86, v243, 28
	v_readlane_b32 s94, v243, 26
	v_cmp_gt_u32_e64 s[4:5], s4, v0
	v_lshl_add_u64 v[142:143], s[44:45], 0, v[138:139]
	s_addc_u32 s17, s19, s17
	s_lshl_b32 s38, s2, 7
	s_movk_i32 s39, 0x400
	s_mov_b32 s19, 0
	s_movk_i32 s44, 0x1000
	s_movk_i32 s45, 0x2000
	s_movk_i32 s48, 0x110
	s_brev_b32 s24, 60
	v_mov_b32_e32 v1, 0x358637bd
	s_mov_b32 s49, s2
	v_readlane_b32 s67, v243, 30
	v_readlane_b32 s87, v243, 29
	v_readlane_b32 s95, v243, 27
	v_readlane_b32 s57, v243, 5
	v_readlane_b32 s58, v243, 6
	v_readlane_b32 s59, v243, 7
	v_readlane_b32 s60, v243, 8
	v_readlane_b32 s61, v243, 9
	v_readlane_b32 s62, v243, 10
	v_readlane_b32 s63, v243, 11
	v_readlane_b32 s64, v243, 12
	v_readlane_b32 s65, v243, 13
	v_readlane_b32 s70, v243, 18
	v_readlane_b32 s71, v243, 19
	s_add_i32 s101, s2, 8
	s_bitcmp1_b32 s2, 3
	s_cbranch_scc1 .LBB0_545
	s_branch .LBB0_537
.LBB0_536:
	s_or_b64 exec, exec, s[26:27]
	s_add_i32 s18, 0, 0x22000
	v_lshl_add_u32 v4, v157, 2, s18
	s_waitcnt lgkmcnt(0)
	s_barrier
	ds_read2st64_b32 v[2:3], v4 offset1:2
	ds_read2st64_b32 v[4:5], v4 offset0:4 offset1:6
	v_add_u32_e32 v6, s28, v144
	s_add_i32 s26, 0, 0x22800
	v_lshl_add_u32 v153, v6, 2, s26
	s_waitcnt lgkmcnt(1)
	v_mov_b32_e32 v6, v2
	s_waitcnt lgkmcnt(0)
	v_mov_b32_e32 v7, v4
	v_mov_b32_e32 v4, v3
	v_pk_add_f32 v[2:3], v[6:7], v[4:5]
	v_lshlrev_b32_e32 v140, 11, v156
	v_add_f32_e32 v2, v2, v3
	v_fmamk_f32 v2, v2, 0x3b000000, v1
	v_add_u32_e32 v4, s6, v144
	v_rsq_f32_e32 v152, v2
	v_lshl_add_u64 v[2:3], s[16:17], 0, v[140:141]
	v_lshl_add_u32 v140, v4, 2, s26
	ds_read_b128 v[6:9], v140
	v_lshlrev_b64 v[150:151], 1, v[144:145]
	v_lshl_add_u64 v[154:155], v[2:3], 0, v[150:151]
	ds_read_b128 v[2:5], v140 offset:32
	v_pk_mul_f32 v[10:11], v[114:115], v[152:153] op_sel_hi:[1,0]
	v_pk_mul_f32 v[12:13], v[116:117], v[152:153] op_sel_hi:[1,0]
	s_waitcnt lgkmcnt(1)
	v_pk_mul_f32 v[10:11], v[6:7], v[10:11]
	v_pk_mul_f32 v[12:13], v[8:9], v[12:13]
	v_cvt_pk_bf16_f32 v10, v10, v11
	v_cvt_pk_bf16_f32 v11, v12, v13
	global_store_dwordx2 v[154:155], v[10:11], off offset:1024
	v_pk_mul_f32 v[10:11], v[118:119], v[152:153] op_sel_hi:[1,0]
	v_pk_mul_f32 v[118:119], v[122:123], v[152:153] op_sel_hi:[1,0]
	s_waitcnt lgkmcnt(0)
	v_pk_mul_f32 v[10:11], v[2:3], v[10:11]
	v_pk_mul_f32 v[120:121], v[120:121], v[152:153] op_sel_hi:[1,0]
	v_cvt_pk_bf16_f32 v114, v10, v11
	v_pk_mul_f32 v[10:11], v[130:131], v[152:153] op_sel_hi:[1,0]
	v_pk_mul_f32 v[98:99], v[98:99], v[152:153] op_sel_hi:[1,0]
	v_pk_mul_f32 v[116:117], v[4:5], v[10:11]
	ds_read_b128 v[10:13], v140 offset:64
	v_cvt_pk_bf16_f32 v115, v116, v117
	global_store_dwordx2 v[154:155], v[114:115], off offset:1040
	ds_read_b128 v[114:117], v140 offset:96
	v_pk_mul_f32 v[100:101], v[100:101], v[152:153] op_sel_hi:[1,0]
	s_waitcnt lgkmcnt(1)
	v_pk_mul_f32 v[118:119], v[10:11], v[118:119]
	v_pk_mul_f32 v[120:121], v[12:13], v[120:121]
	v_cvt_pk_bf16_f32 v118, v118, v119
	v_cvt_pk_bf16_f32 v119, v120, v121
	global_store_dwordx2 v[154:155], v[118:119], off offset:1056
	v_pk_mul_f32 v[118:119], v[124:125], v[152:153] op_sel_hi:[1,0]
	v_pk_mul_f32 v[104:105], v[104:105], v[152:153] op_sel_hi:[1,0]
	s_waitcnt lgkmcnt(0)
	v_pk_mul_f32 v[118:119], v[118:119], v[114:115]
	v_pk_mul_f32 v[82:83], v[82:83], v[152:153] op_sel_hi:[1,0]
	v_cvt_pk_bf16_f32 v122, v118, v119
	v_pk_mul_f32 v[118:119], v[126:127], v[152:153] op_sel_hi:[1,0]
	v_pk_mul_f32 v[84:85], v[84:85], v[152:153] op_sel_hi:[1,0]
	v_pk_mul_f32 v[124:125], v[118:119], v[116:117]
	v_add_u32_e32 v118, s29, v144
	v_lshl_add_u32 v130, v118, 2, s26
	ds_read_b128 v[118:121], v130
	v_cvt_pk_bf16_f32 v123, v124, v125
	global_store_dwordx2 v[154:155], v[122:123], off offset:1072
	ds_read_b128 v[122:125], v130 offset:32
	v_pk_mul_f32 v[88:89], v[88:89], v[152:153] op_sel_hi:[1,0]
	s_waitcnt lgkmcnt(1)
	v_pk_mul_f32 v[98:99], v[98:99], v[118:119]
	v_pk_mul_f32 v[100:101], v[100:101], v[120:121]
	v_cvt_pk_bf16_f32 v98, v98, v99
	v_cvt_pk_bf16_f32 v99, v100, v101
	global_store_dwordx2 v[154:155], v[98:99], off offset:1088
	v_pk_mul_f32 v[98:99], v[102:103], v[152:153] op_sel_hi:[1,0]
	v_pk_mul_f32 v[66:67], v[66:67], v[152:153] op_sel_hi:[1,0]
	s_waitcnt lgkmcnt(0)
	v_pk_mul_f32 v[98:99], v[98:99], v[122:123]
	v_pk_mul_f32 v[68:69], v[68:69], v[152:153] op_sel_hi:[1,0]
	v_cvt_pk_bf16_f32 v102, v98, v99
	v_pk_mul_f32 v[98:99], v[128:129], v[152:153] op_sel_hi:[1,0]
	v_pk_mul_f32 v[72:73], v[72:73], v[152:153] op_sel_hi:[1,0]
	v_pk_mul_f32 v[126:127], v[98:99], v[124:125]
	ds_read_b128 v[98:101], v130 offset:64
	v_cvt_pk_bf16_f32 v103, v126, v127
	ds_read_b128 v[126:129], v130 offset:96
	global_store_dwordx2 v[154:155], v[102:103], off offset:1104
	v_pk_mul_f32 v[102:103], v[106:107], v[152:153] op_sel_hi:[1,0]
	s_waitcnt lgkmcnt(1)
; #define LAS __attribute__((address_space(3)))
; __device__ __forceinline__ unsigned pk2(float lo, float hi) { f32x2 v = {lo, hi}; bf16x2_t b = __builtin_convertvector(v, bf16x2_t); return __builtin_bit_cast(unsigned, b); }
; __device__ __forceinline__ void gmlp_unit(const GmlpP& P, int b, int ch, LAS unsigned char* lds, int wave, int lane_in) {
;     ...
;     __syncthreads();
; #pragma unroll
;     for (int nt = 0; nt < 2; ++nt) {
;         const int t = 32 * (nt == 0 ? tt0 : tt1) + r32;
;         const float tot = (ssqg[t] + ssqg[128 + t]) + (ssqg[256 + t] + ssqg[384 + t]);
;         const float r = __builtin_amdgcn_rsqf(tot * (1.0f / GW) + EPS);
;         bf16_t* op = P.MIX + (tok0 + t) * DM + AW + gI * 128 + 4 * h;
; #pragma unroll
;         for (int mt = 0; mt < 4; ++mt)
; #pragma unroll
;             for (int e4 = 0; e4 < 4; ++e4) {
;                 const f32x4 gg = *(const LAS f32x4*)(lds + LDS_GG + (gI * 128 + 32 * mt + 8 * e4 + 4 * h) * 4);
;                 u32x2 w; w.x = pk2(acc[mt][nt][4 * e4] * r * gg[0], acc[mt][nt][4 * e4 + 1] * r * gg[1]); w.y = pk2(acc[mt][nt][4 * e4 + 2] * r * gg[2], acc[mt][nt][4 * e4 + 3] * r * gg[3]);
;                 *(u32x2*)(op + 32 * mt + 8 * e4) = w;
;             }
;     }
; __global__ void __launch_bounds__(512, 2) mk_fwd(Args args) {
;     ...
;         for (int a = bx; a < 256 * REP_GM; a += G) gmlp_unit(GP, (a & 255) >> 4, a & 15, lds, wave, lane);
	v_pk_mul_f32 v[104:105], v[104:105], v[100:101]
	v_pk_mul_f32 v[102:103], v[102:103], v[98:99]
	v_lshlrev_b32_e32 v140, 11, v139
	v_cvt_pk_bf16_f32 v102, v102, v103
	v_cvt_pk_bf16_f32 v103, v104, v105
	global_store_dwordx2 v[154:155], v[102:103], off offset:1120
	v_pk_mul_f32 v[102:103], v[108:109], v[152:153] op_sel_hi:[1,0]
	s_add_i32 s49, s49, 8
	s_waitcnt lgkmcnt(0)
	v_pk_mul_f32 v[102:103], v[102:103], v[126:127]
	s_add_i32 s38, s38, s39
	v_cvt_pk_bf16_f32 v106, v102, v103
	v_pk_mul_f32 v[102:103], v[110:111], v[152:153] op_sel_hi:[1,0]
	s_cmp_gt_i32 s49, s101
	v_pk_mul_f32 v[108:109], v[102:103], v[128:129]
	v_add_u32_e32 v102, s30, v144
	v_lshl_add_u32 v130, v102, 2, s26
	ds_read_b128 v[102:105], v130
	v_cvt_pk_bf16_f32 v107, v108, v109
	global_store_dwordx2 v[154:155], v[106:107], off offset:1136
	ds_read_b128 v[106:109], v130 offset:32
	s_waitcnt lgkmcnt(1)
	v_pk_mul_f32 v[82:83], v[82:83], v[102:103]
	v_pk_mul_f32 v[84:85], v[84:85], v[104:105]
	v_cvt_pk_bf16_f32 v82, v82, v83
	v_cvt_pk_bf16_f32 v83, v84, v85
	global_store_dwordx2 v[154:155], v[82:83], off offset:1152
	v_pk_mul_f32 v[82:83], v[86:87], v[152:153] op_sel_hi:[1,0]
	s_waitcnt lgkmcnt(0)
	v_pk_mul_f32 v[82:83], v[82:83], v[106:107]
	s_nop 0
	v_cvt_pk_bf16_f32 v86, v82, v83
	v_pk_mul_f32 v[82:83], v[112:113], v[152:153] op_sel_hi:[1,0]
	s_nop 0
	v_pk_mul_f32 v[110:111], v[82:83], v[108:109]
	ds_read_b128 v[82:85], v130 offset:64
	v_cvt_pk_bf16_f32 v87, v110, v111
	ds_read_b128 v[110:113], v130 offset:96
	global_store_dwordx2 v[154:155], v[86:87], off offset:1168
	v_pk_mul_f32 v[86:87], v[90:91], v[152:153] op_sel_hi:[1,0]
	s_waitcnt lgkmcnt(1)
	v_pk_mul_f32 v[88:89], v[88:89], v[84:85]
	v_pk_mul_f32 v[86:87], v[86:87], v[82:83]
	s_nop 0
	v_cvt_pk_bf16_f32 v86, v86, v87
	v_cvt_pk_bf16_f32 v87, v88, v89
	global_store_dwordx2 v[154:155], v[86:87], off offset:1184
	v_pk_mul_f32 v[86:87], v[92:93], v[152:153] op_sel_hi:[1,0]
	s_waitcnt lgkmcnt(0)
	v_pk_mul_f32 v[86:87], v[86:87], v[110:111]
	s_nop 0
	v_cvt_pk_bf16_f32 v90, v86, v87
	v_pk_mul_f32 v[86:87], v[94:95], v[152:153] op_sel_hi:[1,0]
	s_nop 0
	v_pk_mul_f32 v[92:93], v[86:87], v[112:113]
	ds_read_b128 v[86:89], v153
	v_cvt_pk_bf16_f32 v91, v92, v93
	global_store_dwordx2 v[154:155], v[90:91], off offset:1200
	ds_read_b128 v[90:93], v153 offset:32
	s_waitcnt lgkmcnt(1)
	v_pk_mul_f32 v[66:67], v[66:67], v[86:87]
	v_pk_mul_f32 v[68:69], v[68:69], v[88:89]
	v_cvt_pk_bf16_f32 v66, v66, v67
	v_cvt_pk_bf16_f32 v67, v68, v69
	global_store_dwordx2 v[154:155], v[66:67], off offset:1216
	v_pk_mul_f32 v[66:67], v[70:71], v[152:153] op_sel_hi:[1,0]
	s_waitcnt lgkmcnt(0)
	v_pk_mul_f32 v[66:67], v[66:67], v[90:91]
	s_nop 0
	v_cvt_pk_bf16_f32 v70, v66, v67
	v_pk_mul_f32 v[66:67], v[96:97], v[152:153] op_sel_hi:[1,0]
	s_nop 0
	v_pk_mul_f32 v[94:95], v[66:67], v[92:93]
	ds_read_b128 v[66:69], v153 offset:64
	v_cvt_pk_bf16_f32 v71, v94, v95
	ds_read_b128 v[94:97], v153 offset:96
	global_store_dwordx2 v[154:155], v[70:71], off offset:1232
	v_pk_mul_f32 v[70:71], v[74:75], v[152:153] op_sel_hi:[1,0]
	s_waitcnt lgkmcnt(1)
	v_pk_mul_f32 v[72:73], v[72:73], v[68:69]
	v_pk_mul_f32 v[70:71], v[70:71], v[66:67]
	s_nop 0
	v_cvt_pk_bf16_f32 v70, v70, v71
	v_cvt_pk_bf16_f32 v71, v72, v73
	global_store_dwordx2 v[154:155], v[70:71], off offset:1248
	v_pk_mul_f32 v[70:71], v[76:77], v[152:153] op_sel_hi:[1,0]
	v_pk_mul_f32 v[72:73], v[78:79], v[152:153] op_sel_hi:[1,0]
	s_waitcnt lgkmcnt(0)
	v_pk_mul_f32 v[70:71], v[70:71], v[94:95]
	v_pk_mul_f32 v[72:73], v[72:73], v[96:97]
	v_cvt_pk_bf16_f32 v70, v70, v71
	v_lshl_add_u32 v71, v158, 2, s18
	ds_read2st64_b32 v[74:75], v71 offset1:2
	ds_read2st64_b32 v[76:77], v71 offset0:4 offset1:6
	v_cvt_pk_bf16_f32 v71, v72, v73
	global_store_dwordx2 v[154:155], v[70:71], off offset:1264
	v_lshl_add_u64 v[72:73], s[16:17], 0, v[140:141]
	s_waitcnt lgkmcnt(1)
	v_mov_b32_e32 v70, v74
	s_waitcnt lgkmcnt(0)
; #define LAS __attribute__((address_space(3)))
; __device__ __forceinline__ unsigned pk2(float lo, float hi) { f32x2 v = {lo, hi}; bf16x2_t b = __builtin_convertvector(v, bf16x2_t); return __builtin_bit_cast(unsigned, b); }
; __device__ __forceinline__ void gmlp_unit(const GmlpP& P, int b, int ch, LAS unsigned char* lds, int wave, int lane_in) {
;     ...
;     for (int nt = 0; nt < 2; ++nt) {
;         const int t = 32 * (nt == 0 ? tt0 : tt1) + r32;
;         const float tot = (ssqg[t] + ssqg[128 + t]) + (ssqg[256 + t] + ssqg[384 + t]);
;         const float r = __builtin_amdgcn_rsqf(tot * (1.0f / GW) + EPS);
;         bf16_t* op = P.MIX + (tok0 + t) * DM + AW + gI * 128 + 4 * h;
; #pragma unroll
;         for (int mt = 0; mt < 4; ++mt)
; #pragma unroll
;             for (int e4 = 0; e4 < 4; ++e4) {
;                 const f32x4 gg = *(const LAS f32x4*)(lds + LDS_GG + (gI * 128 + 32 * mt + 8 * e4 + 4 * h) * 4);
;                 u32x2 w; w.x = pk2(acc[mt][nt][4 * e4] * r * gg[0], acc[mt][nt][4 * e4 + 1] * r * gg[1]); w.y = pk2(acc[mt][nt][4 * e4 + 2] * r * gg[2], acc[mt][nt][4 * e4 + 3] * r * gg[3]);
;                 *(u32x2*)(op + 32 * mt + 8 * e4) = w;
;             }
;     }
	v_mov_b32_e32 v71, v76
	v_mov_b32_e32 v76, v75
	v_pk_add_f32 v[70:71], v[70:71], v[76:77]
	v_lshl_add_u64 v[72:73], v[72:73], 0, v[150:151]
	v_add_f32_e32 v70, v70, v71
	v_fmamk_f32 v70, v70, 0x3b000000, v1
	v_rsq_f32_e32 v70, v70
	s_nop 0
	v_pk_mul_f32 v[64:65], v[64:65], v[70:71] op_sel_hi:[1,0]
	v_pk_mul_f32 v[62:63], v[62:63], v[70:71] op_sel_hi:[1,0]
	v_pk_mul_f32 v[6:7], v[6:7], v[64:65]
	v_pk_mul_f32 v[8:9], v[8:9], v[62:63]
	v_cvt_pk_bf16_f32 v6, v6, v7
	v_cvt_pk_bf16_f32 v7, v8, v9
	global_store_dwordx2 v[72:73], v[6:7], off offset:1024
	v_pk_mul_f32 v[6:7], v[60:61], v[70:71] op_sel_hi:[1,0]
	s_nop 0
	v_pk_mul_f32 v[2:3], v[2:3], v[6:7]
	v_pk_mul_f32 v[6:7], v[58:59], v[70:71] op_sel_hi:[1,0]
	v_cvt_pk_bf16_f32 v2, v2, v3
	v_pk_mul_f32 v[4:5], v[4:5], v[6:7]
	s_nop 0
	v_cvt_pk_bf16_f32 v3, v4, v5
	global_store_dwordx2 v[72:73], v[2:3], off offset:1040
	v_pk_mul_f32 v[2:3], v[56:57], v[70:71] op_sel_hi:[1,0]
	v_pk_mul_f32 v[4:5], v[54:55], v[70:71] op_sel_hi:[1,0]
	v_pk_mul_f32 v[2:3], v[10:11], v[2:3]
	v_pk_mul_f32 v[4:5], v[12:13], v[4:5]
	v_cvt_pk_bf16_f32 v2, v2, v3
	v_cvt_pk_bf16_f32 v3, v4, v5
	global_store_dwordx2 v[72:73], v[2:3], off offset:1056
	v_pk_mul_f32 v[2:3], v[52:53], v[70:71] op_sel_hi:[1,0]
	v_pk_mul_f32 v[4:5], v[50:51], v[70:71] op_sel_hi:[1,0]
	v_pk_mul_f32 v[2:3], v[114:115], v[2:3]
	v_pk_mul_f32 v[4:5], v[116:117], v[4:5]
	v_cvt_pk_bf16_f32 v2, v2, v3
	v_cvt_pk_bf16_f32 v3, v4, v5
	global_store_dwordx2 v[72:73], v[2:3], off offset:1072
	v_pk_mul_f32 v[2:3], v[36:37], v[70:71] op_sel_hi:[1,0]
	v_pk_mul_f32 v[4:5], v[34:35], v[70:71] op_sel_hi:[1,0]
	v_pk_mul_f32 v[2:3], v[118:119], v[2:3]
	v_pk_mul_f32 v[4:5], v[120:121], v[4:5]
	v_cvt_pk_bf16_f32 v2, v2, v3
	v_cvt_pk_bf16_f32 v3, v4, v5
	global_store_dwordx2 v[72:73], v[2:3], off offset:1088
	v_pk_mul_f32 v[2:3], v[38:39], v[70:71] op_sel_hi:[1,0]
	v_pk_mul_f32 v[4:5], v[40:41], v[70:71] op_sel_hi:[1,0]
	v_pk_mul_f32 v[2:3], v[122:123], v[2:3]
	v_pk_mul_f32 v[4:5], v[124:125], v[4:5]
	v_cvt_pk_bf16_f32 v2, v2, v3
	v_cvt_pk_bf16_f32 v3, v4, v5
	global_store_dwordx2 v[72:73], v[2:3], off offset:1104
	v_pk_mul_f32 v[2:3], v[42:43], v[70:71] op_sel_hi:[1,0]
	v_pk_mul_f32 v[4:5], v[44:45], v[70:71] op_sel_hi:[1,0]
	v_pk_mul_f32 v[2:3], v[98:99], v[2:3]
	v_pk_mul_f32 v[4:5], v[100:101], v[4:5]
	v_cvt_pk_bf16_f32 v2, v2, v3
	v_cvt_pk_bf16_f32 v3, v4, v5
	global_store_dwordx2 v[72:73], v[2:3], off offset:1120
	v_pk_mul_f32 v[2:3], v[46:47], v[70:71] op_sel_hi:[1,0]
	v_pk_mul_f32 v[4:5], v[48:49], v[70:71] op_sel_hi:[1,0]
	v_pk_mul_f32 v[2:3], v[126:127], v[2:3]
	v_pk_mul_f32 v[4:5], v[128:129], v[4:5]
	v_cvt_pk_bf16_f32 v2, v2, v3
	v_cvt_pk_bf16_f32 v3, v4, v5
	global_store_dwordx2 v[72:73], v[2:3], off offset:1136
	v_pk_mul_f32 v[2:3], v[18:19], v[70:71] op_sel_hi:[1,0]
	v_pk_mul_f32 v[4:5], v[20:21], v[70:71] op_sel_hi:[1,0]
	v_pk_mul_f32 v[2:3], v[102:103], v[2:3]
	v_pk_mul_f32 v[4:5], v[104:105], v[4:5]
	v_cvt_pk_bf16_f32 v2, v2, v3
	v_cvt_pk_bf16_f32 v3, v4, v5
	global_store_dwordx2 v[72:73], v[2:3], off offset:1152
	v_pk_mul_f32 v[2:3], v[22:23], v[70:71] op_sel_hi:[1,0]
	v_pk_mul_f32 v[4:5], v[24:25], v[70:71] op_sel_hi:[1,0]
	v_pk_mul_f32 v[2:3], v[106:107], v[2:3]
	v_pk_mul_f32 v[4:5], v[108:109], v[4:5]
	v_cvt_pk_bf16_f32 v2, v2, v3
	v_cvt_pk_bf16_f32 v3, v4, v5
	global_store_dwordx2 v[72:73], v[2:3], off offset:1168
	v_pk_mul_f32 v[2:3], v[26:27], v[70:71] op_sel_hi:[1,0]
	v_pk_mul_f32 v[4:5], v[28:29], v[70:71] op_sel_hi:[1,0]
	v_pk_mul_f32 v[2:3], v[82:83], v[2:3]
	v_pk_mul_f32 v[4:5], v[84:85], v[4:5]
	v_cvt_pk_bf16_f32 v2, v2, v3
	v_cvt_pk_bf16_f32 v3, v4, v5
	global_store_dwordx2 v[72:73], v[2:3], off offset:1184
	v_pk_mul_f32 v[2:3], v[30:31], v[70:71] op_sel_hi:[1,0]
	v_pk_mul_f32 v[4:5], v[32:33], v[70:71] op_sel_hi:[1,0]
	v_pk_mul_f32 v[2:3], v[110:111], v[2:3]
	v_pk_mul_f32 v[4:5], v[112:113], v[4:5]
	v_cvt_pk_bf16_f32 v2, v2, v3
	v_cvt_pk_bf16_f32 v3, v4, v5
	global_store_dwordx2 v[72:73], v[2:3], off offset:1200
	v_pk_mul_f32 v[2:3], v[80:81], v[70:71] op_sel_hi:[1,0]
	v_pk_mul_f32 v[4:5], v[132:133], v[70:71] op_sel_hi:[1,0]
	v_pk_mul_f32 v[2:3], v[86:87], v[2:3]
	v_pk_mul_f32 v[4:5], v[88:89], v[4:5]
	v_cvt_pk_bf16_f32 v2, v2, v3
	v_cvt_pk_bf16_f32 v3, v4, v5
	global_store_dwordx2 v[72:73], v[2:3], off offset:1216
	v_pk_mul_f32 v[2:3], v[134:135], v[70:71] op_sel_hi:[1,0]
	v_pk_mul_f32 v[4:5], v[136:137], v[70:71] op_sel_hi:[1,0]
	v_pk_mul_f32 v[2:3], v[90:91], v[2:3]
	v_pk_mul_f32 v[4:5], v[92:93], v[4:5]
	v_cvt_pk_bf16_f32 v2, v2, v3
	v_cvt_pk_bf16_f32 v3, v4, v5
	global_store_dwordx2 v[72:73], v[2:3], off offset:1232
	v_pk_mul_f32 v[2:3], v[146:147], v[70:71] op_sel_hi:[1,0]
	v_pk_mul_f32 v[4:5], v[148:149], v[70:71] op_sel_hi:[1,0]
	v_pk_mul_f32 v[2:3], v[66:67], v[2:3]
	v_pk_mul_f32 v[4:5], v[68:69], v[4:5]
	v_cvt_pk_bf16_f32 v2, v2, v3
	v_cvt_pk_bf16_f32 v3, v4, v5
	global_store_dwordx2 v[72:73], v[2:3], off offset:1248
	v_pk_mul_f32 v[2:3], v[14:15], v[70:71] op_sel_hi:[1,0]
	v_pk_mul_f32 v[4:5], v[16:17], v[70:71] op_sel_hi:[1,0]
	v_pk_mul_f32 v[2:3], v[94:95], v[2:3]
	v_pk_mul_f32 v[4:5], v[96:97], v[4:5]
	v_cvt_pk_bf16_f32 v2, v2, v3
	v_cvt_pk_bf16_f32 v3, v4, v5
	global_store_dwordx2 v[72:73], v[2:3], off offset:1264
	s_cbranch_scc1 .LBB0_545

; #define PG8_WAIT_V(n) asm volatile("s_waitcnt vmcnt(" #n ")" ::: "memory")
; #define PG8_BAR __builtin_amdgcn_s_barrier()
; template <class Epi, class Sched>
; __device__ __forceinline__ void gemm_phase(LAS unsigned char* lds, const Gemm g, const Sched& S, const Epi& E) {
;     int tid_ = threadIdx.x; asm volatile("" : "+v"(tid_));
;     const int tid = tid_, wid = __builtin_amdgcn_readfirstlane(tid >> 6), lane = tid & 63, wr = wid >> 2, wc = wid & 3, fr = lane & 15, fq = lane >> 4;
;     const int K = g.K, nt = K / BK;
;     unsigned voffA[2], voffB[2];
; #pragma unroll
;     for (int i = 0; i < 2; ++i) { int R, C; stage_rc(tid * 16 + i * 8192, R, C);
;         const int Ra = 128 * (R >> 6) + (R & 63);
;         const int Rb = Epi::HEADPERM ? (64 * (R >> 5) + perm32(R & 31)) : ((R & ~31) + perm32(R & 31));
;         voffA[i] = (unsigned)(Ra * g.lda + C) * 2u; voffB[i] = (unsigned)(Rb * K + C) * 2u; }
;     const size_t kstep = (size_t)(BK * 2);
;     const size_t hstepA = (size_t)64 * g.lda * 2, kstepA = (size_t)g.kstepA;
;     const size_t hstepB = (size_t)(Epi::HEADPERM ? 32 : 128) * K * 2;
;     const size_t tstep = (size_t)256 * K * 2;
;     const unsigned ldsw = (unsigned)wid * 1024u;
;     const unsigned lds_u32 = (unsigned)(size_t)lds;
;     const int aoff = lds_byte(wr * 64 + fr, fq * 8), boff = lds_byte(wc * 32 + fr, fq * 8);
;     ...
;     Unit cur, nxt; int ui = 0;
;     if (!S.next(0, cur)) return;
;     f32x4 acc[2][2][4][2];
; #pragma unroll
;     for (int a = 0; a < 2; ++a)
; #pragma unroll
;         for (int b = 0; b < 2; ++b)
; #pragma unroll
;             for (int m = 0; m < 4; ++m)
; #pragma unroll
;                 for (int n = 0; n < 2; ++n) acc[a][b][m][n] = (f32x4){0.f, 0.f, 0.f, 0.f};
;     bf16x8 At[4][2], B0[2][2], B1[2][2];
;     const char* cA = (const char*)g.A + (size_t)cur.pm * tstep; const char* cB = (const char*)g.Bt + (size_t)cur.pn * tstep;
;     PG8_STAGE(PG8_SB(0, 0), cB, voffB); PG8_STAGE(PG8_SB(0, 1), cB + hstepB, voffB); PG8_STAGE(PG8_SA(0, 0), cA, voffA); PG8_STAGE(PG8_SA(0, 1), cA + hstepA, voffA);
;     if (wr == 1) PG8_BAR;
;     PG8_WAIT_V(2); PG8_BAR;
;     PG8_STAGE(PG8_SB(1, 0), cB + kstep, voffB); PG8_STAGE(PG8_SA(1, 0), cA + kstepA, voffA); PG8_STAGE(PG8_SB(1, 1), cB + hstepB + kstep, voffB);
;     PG8_WAIT_V(6); PG8_BAR;
.LBB0_603:
	s_add_u32 s40, s84, 0x1800000
	s_addc_u32 s41, s85, 0
	s_andn2_b64 vcc, exec, s[4:5]
	s_cbranch_vccnz .LBB0_641
	v_bfe_i32 v4, v2, 27, 1
	v_lshlrev_b32_e32 v3, 4, v2
	v_lshrrev_b32_e32 v4, 22, v4
	v_add_u32_e32 v4, v3, v4
	v_and_b32_e32 v4, 0xfffffc00, v4
	v_sub_u32_e32 v4, v3, v4
	v_ashrrev_i32_e32 v1, 31, v2
	v_lshrrev_b32_e32 v5, 4, v4
	v_lshrrev_b32_e32 v1, 26, v1
	v_bitop3_b32 v4, v5, v4, 32 bitop3:0x6c
	v_add_u32_e32 v1, v2, v1
	v_ashrrev_i32_e32 v6, 31, v4
	v_ashrrev_i32_e32 v1, 6, v1
	v_lshrrev_b32_e32 v6, 26, v6
	v_lshlrev_b32_e32 v5, 3, v1
	v_add_u32_e32 v6, v4, v6
	v_and_b32_e32 v5, -16, v5
	v_ashrrev_i32_e32 v7, 6, v6
	v_and_b32_e32 v6, 0xc0, v6
	v_add_u32_e32 v5, v7, v5
	v_sub_u32_e32 v4, v4, v6
	v_mov_b32_e32 v6, 1
	v_lshlrev_b32_e32 v1, 5, v1
	v_ashrrev_i16_sdwa v4, v6, sext(v4) dst_sel:DWORD dst_unused:UNUSED_PAD src0_sel:DWORD src1_sel:BYTE_0
	v_lshlrev_b32_e32 v8, 1, v5
	v_and_b32_e32 v9, 63, v5
	s_mov_b32 s1, 0x1fff80
	v_lshrrev_b32_e32 v10, 2, v5
	v_and_b32_e32 v7, 3, v7
	s_mov_b32 s5, 0x1fffe0
	v_and_b32_e32 v1, 32, v1
	v_bfe_i32 v4, v4, 0, 16
	v_and_or_b32 v9, v8, s1, v9
	v_and_b32_e32 v8, 24, v8
	v_and_b32_e32 v10, 4, v10
	v_and_or_b32 v5, v5, s5, v7
	v_or3_b32 v5, v5, v10, v8
	v_add_lshl_u32 v4, v1, v4, 1
	v_add_u32_e32 v3, 0x2000, v3
	v_lshl_add_u32 v1, v9, 11, v4
	v_lshl_add_u32 v163, v5, 11, v4
	v_ashrrev_i32_e32 v4, 31, v3
	v_lshrrev_b32_e32 v4, 22, v4
	v_add_u32_e32 v4, v3, v4
	v_ashrrev_i32_e32 v4, 10, v4
	v_mul_i32_i24_e32 v5, 0x400, v4
	v_sub_u32_e32 v3, v3, v5
	v_lshrrev_b32_e32 v5, 4, v3
	v_bitop3_b32 v3, v5, v3, 32 bitop3:0x6c
	v_ashrrev_i32_e32 v7, 31, v3
	v_lshrrev_b32_e32 v7, 26, v7
	v_lshlrev_b32_e32 v5, 3, v4
	v_add_u32_e32 v7, v3, v7
	v_and_b32_e32 v5, -16, v5
	v_ashrrev_i32_e32 v8, 6, v7
	v_and_b32_e32 v7, 0xc0, v7
	v_add_u32_e32 v5, v8, v5
	v_sub_u32_e32 v3, v3, v7
	v_ashrrev_i16_sdwa v3, v6, sext(v3) dst_sel:DWORD dst_unused:UNUSED_PAD src0_sel:DWORD src1_sel:BYTE_0
	v_lshlrev_b32_e32 v6, 1, v5
	v_and_b32_e32 v7, 63, v5
	s_ashr_i32 s4, s6, 6
	v_and_or_b32 v7, v6, s1, v7
	v_and_b32_e32 v8, 3, v8
	s_ashr_i32 s27, s26, 31
	s_ashr_i32 s1, s0, 31
	v_lshrrev_b32_e32 v9, 2, v5
	v_and_or_b32 v5, v5, s5, v8
	s_ashr_i32 s5, s6, 8
	s_lshl_b32 s7, s4, 10
	s_lshl_b64 s[8:9], s[26:27], 19
	s_lshl_b64 s[10:11], s[0:1], 19
	v_lshlrev_b32_e32 v4, 5, v4
	s_add_u32 s28, s94, s10
	v_and_b32_e32 v4, 32, v4
	v_bfe_i32 v3, v3, 0, 16
	v_and_b32_e32 v6, 24, v6
	v_and_b32_e32 v9, 4, v9
	s_addc_u32 s29, s95, s11
	s_add_i32 s20, s7, 0
	v_or3_b32 v5, v5, v9, v6
	v_add_lshl_u32 v3, v4, v3, 1
	s_add_i32 s21, s20, 0x10000
	s_mov_b32 m0, s21
	s_nop 0
	global_load_lds_dwordx4 v163, s[28:29]
	s_add_i32 s22, s20, 0x12000
	s_add_i32 s23, s20, 0x14000
	v_lshl_add_u32 v181, v5, 11, v3
	s_mov_b32 m0, s22
	s_nop 0
	global_load_lds_dwordx4 v181, s[28:29]
	s_add_u32 s10, s28, 0x40000
	s_addc_u32 s11, s29, 0
	s_mov_b32 m0, s23
	s_nop 0
	global_load_lds_dwordx4 v163, s[10:11]
	s_add_i32 s38, s20, 0x16000
	s_mov_b32 m0, s38
	s_nop 0
	global_load_lds_dwordx4 v181, s[10:11]
	v_readlane_b32 s10, v243, 20
	v_readlane_b32 s11, v243, 21
	s_add_u32 s24, s10, s8
	s_addc_u32 s25, s11, s9
	s_mov_b32 m0, s20
	s_nop 0
	global_load_lds_dwordx4 v1, s[24:25]
	s_add_i32 s39, s20, 0x2000
	s_add_i32 s48, s20, 0x4000
	v_lshl_add_u32 v180, v7, 11, v3
	s_mov_b32 m0, s39
	s_nop 0
	global_load_lds_dwordx4 v180, s[24:25]
	s_add_u32 s10, s24, 0x20000
	s_addc_u32 s11, s25, 0
	s_mov_b32 m0, s48
	s_nop 0
	global_load_lds_dwordx4 v1, s[10:11]
	s_add_i32 s49, s20, 0x6000
	s_mov_b32 m0, s49
	s_nop 0
	global_load_lds_dwordx4 v180, s[10:11]
	s_cmp_eq_u32 s5, 1
	s_mov_b32 s1, 0
	s_cselect_b64 s[8:9], -1, 0
	s_cmp_lg_u32 s5, 1
	s_cbranch_scc1 .LBB0_606
	s_barrier
.LBB0_606:
	v_and_b32_e32 v3, 15, v2
	v_bfe_u32 v4, v2, 4, 2
	v_lshlrev_b32_e32 v6, 6, v3
	v_lshlrev_b32_e32 v2, 2, v2
	s_and_b32 s50, s4, 3
	v_lshl_or_b32 v6, v4, 4, v6
	s_lshl_b32 s4, s5, 13
	v_and_b32_e32 v2, 32, v2
	v_bitop3_b32 v7, v6, s4, v2 bitop3:0xde
	s_lshl_b32 s4, s50, 12
	s_add_i32 s51, s20, 0x18000
	s_add_u32 s10, s28, 0x80
	v_bitop3_b32 v6, v6, s4, v2 bitop3:0xde
	s_waitcnt vmcnt(2)
	s_barrier
	s_addc_u32 s11, s29, 0
	s_mov_b32 m0, s51
	s_nop 0
	global_load_lds_dwordx4 v163, s[10:11]
	s_add_i32 s52, s20, 0x1a000
	s_add_i32 s53, s20, 0x8000
	s_mov_b32 m0, s52
	s_nop 0
	global_load_lds_dwordx4 v181, s[10:11]
	s_add_u32 s10, s24, 0x80
	s_addc_u32 s11, s25, 0
	s_mov_b32 m0, s53
	s_nop 0
	global_load_lds_dwordx4 v1, s[10:11]
	s_add_i32 s56, s20, 0xa000
	s_add_i32 s57, s20, 0x1c000
	s_mov_b32 m0, s56
	s_nop 0
	global_load_lds_dwordx4 v180, s[10:11]
	s_add_u32 s10, s28, 0x40080
	s_addc_u32 s11, s29, 0
	s_mov_b32 m0, s57
	s_nop 0
	global_load_lds_dwordx4 v163, s[10:11]
	s_add_i32 s58, s20, 0x1e000
	s_mov_b32 m0, s58
	s_nop 0
	global_load_lds_dwordx4 v181, s[10:11]
	s_lshl_b32 s4, s5, 7
	s_waitcnt vmcnt(6)
	s_add_i32 s59, s20, 0xc000
	s_ashr_i32 s5, s4, 31
	v_lshlrev_b32_e32 v5, 3, v4
	v_or_b32_e32 v158, s4, v3
	s_cmpk_lt_u32 s6, 0x100
	v_mov_b32_e32 v159, s5
	v_or_b32_e32 v160, 64, v158
	v_mov_b32_e32 v161, s5
	s_cselect_b64 s[10:11], -1, 0
	v_lshl_or_b32 v162, s50, 5, v5
	v_mov_b32_e32 v2, 0
	v_cmp_eq_u32_e64 s[4:5], 0, v4
	s_ashr_i32 s60, s3, 31
	v_mov_b64_e32 v[164:165], 0x200
	v_mov_b64_e32 v[166:167], 0x1ff
	v_mov_b32_e32 v182, 0x358637bd
	v_add_u32_e32 v183, 0, v6
	v_add_u32_e32 v184, 0, v7
	s_mov_b32 s61, 0
	s_barrier
	s_branch .LBB0_609

; #define PG8_LDA(dst, b, h) do { _Pragma("unroll") for (int m = 0; m < 4; ++m) _Pragma("unroll") for (int k = 0; k < 2; ++k) dst[m][k] = *(const LAS bf16x8*)(lds + PG8_SA(b, h) + aoff + m * 2048 + k * 1024); } while (0)
; #define PG8_LDB(dst, b, h) do { _Pragma("unroll") for (int n = 0; n < 2; ++n) _Pragma("unroll") for (int k = 0; k < 2; ++k) dst[n][k] = *(const LAS bf16x8*)(lds + PG8_SB(b, h) + boff + n * 2048 + k * 1024); } while (0)
; #define PG8_MMA(ai, bj, At, Bt) do { __builtin_amdgcn_s_setprio(1); _Pragma("unroll") for (int m = 0; m < 4; ++m) _Pragma("unroll") for (int n = 0; n < 2; ++n) _Pragma("unroll") for (int k = 0; k < 2; ++k) \
;         acc[ai][bj][m][n] = __builtin_amdgcn_mfma_f32_16x16x32_bf16(Bt[n][k], At[m][k], acc[ai][bj][m][n], 0, 0, 0); __builtin_amdgcn_s_setprio(0); } while (0)
; #define PG8_WAIT_V(n) asm volatile("s_waitcnt vmcnt(" #n ")" ::: "memory")
; #define PG8_WAIT_L(n) asm volatile("s_waitcnt lgkmcnt(" #n ")" ::: "memory")
; #define PG8_BAR __builtin_amdgcn_s_barrier()
; #define PG8_SCHED __builtin_amdgcn_sched_barrier(0)
; template <class Epi, class Sched>
; __device__ __forceinline__ void gemm_phase(LAS unsigned char* lds, const Gemm g, const Sched& S, const Epi& E) {
;     ...
;             const char* a1 = cA + (size_t)(t + 1) * kstepA;
;             const char* a2 = last ? nA : cA + (size_t)(t + 2) * kstepA; const char* b2 = last ? nB : cB + (size_t)(t + 2) * kstep;
;             const char* a3 = a2 + kstepA; const char* b3 = b2 + kstep;
;             PG8_LDB(B0, 0, 0); PG8_LDB(B1, 0, 1); PG8_SCHED; PG8_LDA(At, 0, 0); PG8_STAGE(PG8_SA(1, 1), a1 + hstepA, voffA);
;             PG8_WAIT_V(8); PG8_WAIT_L(0); PG8_BAR; PG8_MMA(0, 0, At, B0); PG8_MMA(0, 1, At, B1); PG8_BAR; PG8_SCHED;
;             PG8_LDA(At, 0, 1); PG8_STAGE(PG8_SB(0, 0), b2, voffB); PG8_STAGE(PG8_SB(0, 1), b2 + hstepB, voffB); PG8_STAGE(PG8_SA(0, 0), a2, voffA);
;             PG8_WAIT_V(8); PG8_WAIT_L(0); PG8_BAR; PG8_MMA(1, 0, At, B0); PG8_MMA(1, 1, At, B1); PG8_BAR; PG8_SCHED;
.LBB0_618:
	v_add_u32_e32 v3, 0x10000, v183
	ds_read_b128 v[134:137], v3
	ds_read_b128 v[138:141], v3 offset:1024
	ds_read_b128 v[142:145], v3 offset:2048
	ds_read_b128 v[146:149], v3 offset:3072
	v_add_u32_e32 v3, 0x14000, v183
	ds_read_b128 v[150:153], v3
	ds_read_b128 v[154:157], v3 offset:1024
	ds_read_b128 v[186:189], v3 offset:2048
	ds_read_b128 v[190:193], v3 offset:3072
	s_add_u32 s26, s24, 0x100
	s_addc_u32 s27, s25, 0
	s_cmp_eq_u32 s66, 12
	s_cselect_b32 s44, s62, s26
	s_cselect_b32 s45, s13, s27
	s_cselect_b32 s30, s63, s64
	s_cselect_b32 s31, s15, s65
	s_add_u32 s28, s44, 0x80
	s_addc_u32 s29, s45, 0
	ds_read_b128 v[194:197], v184
	ds_read_b128 v[198:201], v184 offset:1024
	ds_read_b128 v[202:205], v184 offset:2048
	ds_read_b128 v[206:209], v184 offset:3072
	ds_read_b128 v[210:213], v184 offset:4096
	ds_read_b128 v[214:217], v184 offset:5120
	ds_read_b128 v[218:221], v184 offset:6144
	ds_read_b128 v[222:225], v184 offset:7168
	s_add_u32 s24, s24, 0x20080
	s_addc_u32 s25, s25, 0
	s_mov_b32 m0, s59
	s_nop 0
	global_load_lds_dwordx4 v1, s[24:25]
	s_add_i32 s36, s20, 0xe000
	s_mov_b32 m0, s36
	s_nop 0
	global_load_lds_dwordx4 v180, s[24:25]
	s_waitcnt vmcnt(8)
	s_waitcnt lgkmcnt(0)
	s_barrier
	s_setprio 1
	s_waitcnt lgkmcnt(7)
	v_mfma_f32_16x16x32_bf16 v[130:133], v[134:137], v[194:197], v[130:133]
	v_mfma_f32_16x16x32_bf16 v[126:129], v[142:145], v[194:197], v[126:129]
	s_waitcnt lgkmcnt(5)
	v_mfma_f32_16x16x32_bf16 v[114:117], v[134:137], v[202:205], v[114:117]
	v_mfma_f32_16x16x32_bf16 v[110:113], v[142:145], v[202:205], v[110:113]
	s_waitcnt lgkmcnt(3)
	v_mfma_f32_16x16x32_bf16 v[98:101], v[134:137], v[210:213], v[98:101]
	v_mfma_f32_16x16x32_bf16 v[94:97], v[142:145], v[210:213], v[94:97]
	s_waitcnt lgkmcnt(1)
	v_mfma_f32_16x16x32_bf16 v[82:85], v[134:137], v[218:221], v[82:85]
	v_mfma_f32_16x16x32_bf16 v[78:81], v[142:145], v[218:221], v[78:81]
	v_mfma_f32_16x16x32_bf16 v[130:133], v[138:141], v[198:201], v[130:133]
	v_mfma_f32_16x16x32_bf16 v[126:129], v[146:149], v[198:201], v[126:129]
	v_mfma_f32_16x16x32_bf16 v[114:117], v[138:141], v[206:209], v[114:117]
	v_mfma_f32_16x16x32_bf16 v[110:113], v[146:149], v[206:209], v[110:113]
	v_mfma_f32_16x16x32_bf16 v[98:101], v[138:141], v[214:217], v[98:101]
	v_mfma_f32_16x16x32_bf16 v[94:97], v[146:149], v[214:217], v[94:97]
	s_waitcnt lgkmcnt(0)
	v_mfma_f32_16x16x32_bf16 v[82:85], v[138:141], v[222:225], v[82:85]
	v_mfma_f32_16x16x32_bf16 v[78:81], v[146:149], v[222:225], v[78:81]
	s_setprio 0
	s_setprio 1
	v_mfma_f32_16x16x32_bf16 v[122:125], v[150:153], v[194:197], v[122:125]
	v_mfma_f32_16x16x32_bf16 v[118:121], v[186:189], v[194:197], v[118:121]
	v_mfma_f32_16x16x32_bf16 v[106:109], v[150:153], v[202:205], v[106:109]
	v_mfma_f32_16x16x32_bf16 v[102:105], v[186:189], v[202:205], v[102:105]
	v_mfma_f32_16x16x32_bf16 v[90:93], v[150:153], v[210:213], v[90:93]
	v_mfma_f32_16x16x32_bf16 v[86:89], v[186:189], v[210:213], v[86:89]
	v_mfma_f32_16x16x32_bf16 v[74:77], v[150:153], v[218:221], v[74:77]
	v_mfma_f32_16x16x32_bf16 v[70:73], v[186:189], v[218:221], v[70:73]
	v_mfma_f32_16x16x32_bf16 v[122:125], v[154:157], v[198:201], v[122:125]
	v_mfma_f32_16x16x32_bf16 v[118:121], v[190:193], v[198:201], v[118:121]
	v_mfma_f32_16x16x32_bf16 v[106:109], v[154:157], v[206:209], v[106:109]
	v_mfma_f32_16x16x32_bf16 v[102:105], v[190:193], v[206:209], v[102:105]
	v_mfma_f32_16x16x32_bf16 v[90:93], v[154:157], v[214:217], v[90:93]
	v_mfma_f32_16x16x32_bf16 v[86:89], v[190:193], v[214:217], v[86:89]
	v_mfma_f32_16x16x32_bf16 v[74:77], v[154:157], v[222:225], v[74:77]
	v_mfma_f32_16x16x32_bf16 v[70:73], v[190:193], v[222:225], v[70:73]
	s_setprio 0
	s_barrier
	ds_read_b128 v[194:197], v184 offset:16384
	ds_read_b128 v[198:201], v184 offset:17408
	ds_read_b128 v[202:205], v184 offset:18432
	ds_read_b128 v[206:209], v184 offset:19456
	ds_read_b128 v[210:213], v184 offset:20480
	ds_read_b128 v[214:217], v184 offset:21504
	ds_read_b128 v[218:221], v184 offset:22528
	ds_read_b128 v[222:225], v184 offset:23552
	s_mov_b32 m0, s21
	s_nop 0
	global_load_lds_dwordx4 v163, s[30:31]
	s_nop 0
	s_mov_b32 m0, s22
	s_nop 0
	global_load_lds_dwordx4 v181, s[30:31]
	s_add_u32 s24, s30, 0x40000
	s_addc_u32 s25, s31, 0
	s_mov_b32 m0, s23
	s_nop 0
	global_load_lds_dwordx4 v163, s[24:25]
	s_nop 0
	s_mov_b32 m0, s38
	s_nop 0
	global_load_lds_dwordx4 v181, s[24:25]
	s_mov_b32 m0, s20
	s_nop 0
	global_load_lds_dwordx4 v1, s[44:45]
	s_nop 0
	s_mov_b32 m0, s39
	s_nop 0
	global_load_lds_dwordx4 v180, s[44:45]
	s_waitcnt vmcnt(8)
	s_waitcnt lgkmcnt(0)
	s_barrier
; #define PG8_LDA(dst, b, h) do { _Pragma("unroll") for (int m = 0; m < 4; ++m) _Pragma("unroll") for (int k = 0; k < 2; ++k) dst[m][k] = *(const LAS bf16x8*)(lds + PG8_SA(b, h) + aoff + m * 2048 + k * 1024); } while (0)
; #define PG8_LDB(dst, b, h) do { _Pragma("unroll") for (int n = 0; n < 2; ++n) _Pragma("unroll") for (int k = 0; k < 2; ++k) dst[n][k] = *(const LAS bf16x8*)(lds + PG8_SB(b, h) + boff + n * 2048 + k * 1024); } while (0)
; #define PG8_MMA(ai, bj, At, Bt) do { __builtin_amdgcn_s_setprio(1); _Pragma("unroll") for (int m = 0; m < 4; ++m) _Pragma("unroll") for (int n = 0; n < 2; ++n) _Pragma("unroll") for (int k = 0; k < 2; ++k) \
;         acc[ai][bj][m][n] = __builtin_amdgcn_mfma_f32_16x16x32_bf16(Bt[n][k], At[m][k], acc[ai][bj][m][n], 0, 0, 0); __builtin_amdgcn_s_setprio(0); } while (0)
; #define PG8_WAIT_V(n) asm volatile("s_waitcnt vmcnt(" #n ")" ::: "memory")
; #define PG8_WAIT_L(n) asm volatile("s_waitcnt lgkmcnt(" #n ")" ::: "memory")
; #define PG8_BAR __builtin_amdgcn_s_barrier()
; #define PG8_SCHED __builtin_amdgcn_sched_barrier(0)
; template <class Epi, class Sched>
; __device__ __forceinline__ void gemm_phase(LAS unsigned char* lds, const Gemm g, const Sched& S, const Epi& E) {
;     ...
;             PG8_WAIT_V(8); PG8_WAIT_L(0); PG8_BAR; PG8_MMA(1, 0, At, B0); PG8_MMA(1, 1, At, B1); PG8_BAR; PG8_SCHED;
;             PG8_LDB(B0, 1, 0); PG8_LDB(B1, 1, 1); PG8_SCHED; PG8_LDA(At, 1, 0); PG8_STAGE(PG8_SA(0, 1), a2 + hstepA, voffA);
;             PG8_WAIT_V(8); PG8_WAIT_L(0); PG8_BAR; PG8_MMA(0, 0, At, B0); PG8_MMA(0, 1, At, B1); PG8_BAR; PG8_SCHED;
	s_setprio 1
	s_waitcnt lgkmcnt(7)
	v_mfma_f32_16x16x32_bf16 v[66:69], v[134:137], v[194:197], v[66:69]
	v_mfma_f32_16x16x32_bf16 v[62:65], v[142:145], v[194:197], v[62:65]
	s_waitcnt lgkmcnt(5)
	v_mfma_f32_16x16x32_bf16 v[50:53], v[134:137], v[202:205], v[50:53]
	v_mfma_f32_16x16x32_bf16 v[46:49], v[142:145], v[202:205], v[46:49]
	s_waitcnt lgkmcnt(3)
	v_mfma_f32_16x16x32_bf16 v[34:37], v[134:137], v[210:213], v[34:37]
	v_mfma_f32_16x16x32_bf16 v[30:33], v[142:145], v[210:213], v[30:33]
	s_waitcnt lgkmcnt(1)
	v_mfma_f32_16x16x32_bf16 v[18:21], v[134:137], v[218:221], v[18:21]
	v_mfma_f32_16x16x32_bf16 v[14:17], v[142:145], v[218:221], v[14:17]
	v_mfma_f32_16x16x32_bf16 v[66:69], v[138:141], v[198:201], v[66:69]
	v_mfma_f32_16x16x32_bf16 v[62:65], v[146:149], v[198:201], v[62:65]
	v_mfma_f32_16x16x32_bf16 v[50:53], v[138:141], v[206:209], v[50:53]
	v_mfma_f32_16x16x32_bf16 v[46:49], v[146:149], v[206:209], v[46:49]
	v_mfma_f32_16x16x32_bf16 v[34:37], v[138:141], v[214:217], v[34:37]
	v_mfma_f32_16x16x32_bf16 v[30:33], v[146:149], v[214:217], v[30:33]
	s_waitcnt lgkmcnt(0)
	v_mfma_f32_16x16x32_bf16 v[18:21], v[138:141], v[222:225], v[18:21]
	v_mfma_f32_16x16x32_bf16 v[14:17], v[146:149], v[222:225], v[14:17]
	s_setprio 0
	s_setprio 1
	v_mfma_f32_16x16x32_bf16 v[58:61], v[150:153], v[194:197], v[58:61]
	v_mfma_f32_16x16x32_bf16 v[54:57], v[186:189], v[194:197], v[54:57]
	v_mfma_f32_16x16x32_bf16 v[42:45], v[150:153], v[202:205], v[42:45]
	v_mfma_f32_16x16x32_bf16 v[38:41], v[186:189], v[202:205], v[38:41]
	v_mfma_f32_16x16x32_bf16 v[26:29], v[150:153], v[210:213], v[26:29]
	v_mfma_f32_16x16x32_bf16 v[22:25], v[186:189], v[210:213], v[22:25]
	v_mfma_f32_16x16x32_bf16 v[10:13], v[150:153], v[218:221], v[10:13]
	v_mfma_f32_16x16x32_bf16 v[4:7], v[186:189], v[218:221], v[6:9]
	v_mfma_f32_16x16x32_bf16 v[58:61], v[154:157], v[198:201], v[58:61]
	v_mfma_f32_16x16x32_bf16 v[54:57], v[190:193], v[198:201], v[54:57]
	v_mfma_f32_16x16x32_bf16 v[42:45], v[154:157], v[206:209], v[42:45]
	v_mfma_f32_16x16x32_bf16 v[38:41], v[190:193], v[206:209], v[38:41]
	v_mfma_f32_16x16x32_bf16 v[26:29], v[154:157], v[214:217], v[26:29]
	v_mfma_f32_16x16x32_bf16 v[22:25], v[190:193], v[214:217], v[22:25]
	v_mfma_f32_16x16x32_bf16 v[10:13], v[154:157], v[222:225], v[10:13]
	v_mfma_f32_16x16x32_bf16 v[4:7], v[190:193], v[222:225], v[4:7]
	s_setprio 0
	s_barrier
	v_add_u32_e32 v3, 0x18000, v183
	ds_read_b128 v[134:137], v3
	ds_read_b128 v[138:141], v3 offset:1024
	ds_read_b128 v[142:145], v3 offset:2048
	ds_read_b128 v[146:149], v3 offset:3072
	v_add_u32_e32 v3, 0x1c000, v183
	ds_read_b128 v[150:153], v3
	ds_read_b128 v[154:157], v3 offset:1024
	ds_read_b128 v[186:189], v3 offset:2048
	ds_read_b128 v[190:193], v3 offset:3072
	ds_read_b128 v[194:197], v184 offset:32768
	ds_read_b128 v[198:201], v184 offset:33792
	ds_read_b128 v[202:205], v184 offset:34816
	ds_read_b128 v[206:209], v184 offset:35840
	ds_read_b128 v[210:213], v184 offset:36864
	ds_read_b128 v[214:217], v184 offset:37888
	ds_read_b128 v[218:221], v184 offset:38912
	ds_read_b128 v[222:225], v184 offset:39936
	s_add_u32 s24, s44, 0x20000
	s_addc_u32 s25, s45, 0
	s_mov_b32 m0, s48
	s_nop 0
	global_load_lds_dwordx4 v1, s[24:25]
	s_nop 0
	s_mov_b32 m0, s49
	s_nop 0
	global_load_lds_dwordx4 v180, s[24:25]
	s_waitcnt vmcnt(8)
	s_waitcnt lgkmcnt(0)
	s_barrier
	s_setprio 1
	s_waitcnt lgkmcnt(7)
	v_mfma_f32_16x16x32_bf16 v[130:133], v[134:137], v[194:197], v[130:133]
	v_mfma_f32_16x16x32_bf16 v[126:129], v[142:145], v[194:197], v[126:129]
	s_waitcnt lgkmcnt(5)
	v_mfma_f32_16x16x32_bf16 v[114:117], v[134:137], v[202:205], v[114:117]
	v_mfma_f32_16x16x32_bf16 v[110:113], v[142:145], v[202:205], v[110:113]
	s_waitcnt lgkmcnt(3)
	v_mfma_f32_16x16x32_bf16 v[98:101], v[134:137], v[210:213], v[98:101]
	v_mfma_f32_16x16x32_bf16 v[94:97], v[142:145], v[210:213], v[94:97]
	s_waitcnt lgkmcnt(1)
	v_mfma_f32_16x16x32_bf16 v[82:85], v[134:137], v[218:221], v[82:85]
	v_mfma_f32_16x16x32_bf16 v[78:81], v[142:145], v[218:221], v[78:81]
	v_mfma_f32_16x16x32_bf16 v[130:133], v[138:141], v[198:201], v[130:133]
	v_mfma_f32_16x16x32_bf16 v[126:129], v[146:149], v[198:201], v[126:129]
	v_mfma_f32_16x16x32_bf16 v[114:117], v[138:141], v[206:209], v[114:117]
	v_mfma_f32_16x16x32_bf16 v[110:113], v[146:149], v[206:209], v[110:113]
	v_mfma_f32_16x16x32_bf16 v[98:101], v[138:141], v[214:217], v[98:101]
	v_mfma_f32_16x16x32_bf16 v[94:97], v[146:149], v[214:217], v[94:97]
	s_waitcnt lgkmcnt(0)
	v_mfma_f32_16x16x32_bf16 v[82:85], v[138:141], v[222:225], v[82:85]
	v_mfma_f32_16x16x32_bf16 v[78:81], v[146:149], v[222:225], v[78:81]
	s_setprio 0
	s_setprio 1
	v_mfma_f32_16x16x32_bf16 v[122:125], v[150:153], v[194:197], v[122:125]
	v_mfma_f32_16x16x32_bf16 v[118:121], v[186:189], v[194:197], v[118:121]
	v_mfma_f32_16x16x32_bf16 v[106:109], v[150:153], v[202:205], v[106:109]
	v_mfma_f32_16x16x32_bf16 v[102:105], v[186:189], v[202:205], v[102:105]
	v_mfma_f32_16x16x32_bf16 v[90:93], v[150:153], v[210:213], v[90:93]
	v_mfma_f32_16x16x32_bf16 v[86:89], v[186:189], v[210:213], v[86:89]
	v_mfma_f32_16x16x32_bf16 v[74:77], v[150:153], v[218:221], v[74:77]
	v_mfma_f32_16x16x32_bf16 v[70:73], v[186:189], v[218:221], v[70:73]
	v_mfma_f32_16x16x32_bf16 v[122:125], v[154:157], v[198:201], v[122:125]
	v_mfma_f32_16x16x32_bf16 v[118:121], v[190:193], v[198:201], v[118:121]
	v_mfma_f32_16x16x32_bf16 v[106:109], v[154:157], v[206:209], v[106:109]
	v_mfma_f32_16x16x32_bf16 v[102:105], v[190:193], v[206:209], v[102:105]
	v_mfma_f32_16x16x32_bf16 v[90:93], v[154:157], v[214:217], v[90:93]
	v_mfma_f32_16x16x32_bf16 v[86:89], v[190:193], v[214:217], v[86:89]
	v_mfma_f32_16x16x32_bf16 v[74:77], v[154:157], v[222:225], v[74:77]
	v_mfma_f32_16x16x32_bf16 v[70:73], v[190:193], v[222:225], v[70:73]
	s_setprio 0
	s_barrier
; #define PG8_LDA(dst, b, h) do { _Pragma("unroll") for (int m = 0; m < 4; ++m) _Pragma("unroll") for (int k = 0; k < 2; ++k) dst[m][k] = *(const LAS bf16x8*)(lds + PG8_SA(b, h) + aoff + m * 2048 + k * 1024); } while (0)
; #define PG8_MMA(ai, bj, At, Bt) do { __builtin_amdgcn_s_setprio(1); _Pragma("unroll") for (int m = 0; m < 4; ++m) _Pragma("unroll") for (int n = 0; n < 2; ++n) _Pragma("unroll") for (int k = 0; k < 2; ++k) \
;         acc[ai][bj][m][n] = __builtin_amdgcn_mfma_f32_16x16x32_bf16(Bt[n][k], At[m][k], acc[ai][bj][m][n], 0, 0, 0); __builtin_amdgcn_s_setprio(0); } while (0)
; #define PG8_WAIT_V(n) asm volatile("s_waitcnt vmcnt(" #n ")" ::: "memory")
; #define PG8_WAIT_L(n) asm volatile("s_waitcnt lgkmcnt(" #n ")" ::: "memory")
; #define PG8_BAR __builtin_amdgcn_s_barrier()
; #define PG8_SCHED __builtin_amdgcn_sched_barrier(0)
; template <class Epi, class Sched>
; __device__ __forceinline__ void gemm_phase(LAS unsigned char* lds, const Gemm g, const Sched& S, const Epi& E) {
;     ...
;             PG8_LDA(At, 1, 1); PG8_STAGE(PG8_SB(1, 0), b3, voffB); PG8_STAGE(PG8_SB(1, 1), b3 + hstepB, voffB); PG8_STAGE(PG8_SA(1, 0), a3, voffA);
;             PG8_WAIT_V(8); PG8_WAIT_L(0); PG8_BAR; PG8_MMA(1, 0, At, B0); PG8_MMA(1, 1, At, B1); PG8_BAR; PG8_SCHED;
;         }
;         if (wr == 0) PG8_BAR;
	ds_read_b128 v[194:197], v184 offset:49152
	ds_read_b128 v[198:201], v184 offset:50176
	ds_read_b128 v[202:205], v184 offset:51200
	ds_read_b128 v[206:209], v184 offset:52224
	ds_read_b128 v[210:213], v184 offset:53248
	ds_read_b128 v[214:217], v184 offset:54272
	ds_read_b128 v[218:221], v184 offset:55296
	ds_read_b128 v[222:225], v184 offset:56320
	s_add_u32 s24, s30, 0x80
	s_addc_u32 s25, s31, 0
	s_mov_b32 m0, s51
	s_nop 0
	global_load_lds_dwordx4 v163, s[24:25]
	s_nop 0
	s_mov_b32 m0, s52
	s_nop 0
	global_load_lds_dwordx4 v181, s[24:25]
	s_add_u32 s24, s30, 0x40080
	s_addc_u32 s25, s31, 0
	s_mov_b32 m0, s57
	s_nop 0
	global_load_lds_dwordx4 v163, s[24:25]
	s_nop 0
	s_mov_b32 m0, s58
	s_nop 0
	global_load_lds_dwordx4 v181, s[24:25]
	s_mov_b32 m0, s53
	s_nop 0
	global_load_lds_dwordx4 v1, s[28:29]
	s_nop 0
	s_mov_b32 m0, s56
	s_nop 0
	global_load_lds_dwordx4 v180, s[28:29]
	s_waitcnt vmcnt(8)
	s_waitcnt lgkmcnt(0)
	s_barrier
	s_setprio 1
	s_waitcnt lgkmcnt(7)
	v_mfma_f32_16x16x32_bf16 v[66:69], v[134:137], v[194:197], v[66:69]
	v_mfma_f32_16x16x32_bf16 v[62:65], v[142:145], v[194:197], v[62:65]
	s_waitcnt lgkmcnt(5)
	v_mfma_f32_16x16x32_bf16 v[50:53], v[134:137], v[202:205], v[50:53]
	v_mfma_f32_16x16x32_bf16 v[46:49], v[142:145], v[202:205], v[46:49]
	s_waitcnt lgkmcnt(3)
	v_mfma_f32_16x16x32_bf16 v[34:37], v[134:137], v[210:213], v[34:37]
	v_mfma_f32_16x16x32_bf16 v[30:33], v[142:145], v[210:213], v[30:33]
	s_waitcnt lgkmcnt(1)
	v_mfma_f32_16x16x32_bf16 v[18:21], v[134:137], v[218:221], v[18:21]
	v_mfma_f32_16x16x32_bf16 v[14:17], v[142:145], v[218:221], v[14:17]
	v_mfma_f32_16x16x32_bf16 v[66:69], v[138:141], v[198:201], v[66:69]
	v_mfma_f32_16x16x32_bf16 v[62:65], v[146:149], v[198:201], v[62:65]
	v_mfma_f32_16x16x32_bf16 v[50:53], v[138:141], v[206:209], v[50:53]
	v_mfma_f32_16x16x32_bf16 v[46:49], v[146:149], v[206:209], v[46:49]
	v_mfma_f32_16x16x32_bf16 v[34:37], v[138:141], v[214:217], v[34:37]
	v_mfma_f32_16x16x32_bf16 v[30:33], v[146:149], v[214:217], v[30:33]
	s_waitcnt lgkmcnt(0)
	v_mfma_f32_16x16x32_bf16 v[18:21], v[138:141], v[222:225], v[18:21]
	v_mfma_f32_16x16x32_bf16 v[14:17], v[146:149], v[222:225], v[14:17]
	s_setprio 0
	s_setprio 1
	v_mfma_f32_16x16x32_bf16 v[58:61], v[150:153], v[194:197], v[58:61]
	v_mfma_f32_16x16x32_bf16 v[54:57], v[186:189], v[194:197], v[54:57]
	v_mfma_f32_16x16x32_bf16 v[42:45], v[150:153], v[202:205], v[42:45]
	v_mfma_f32_16x16x32_bf16 v[38:41], v[186:189], v[202:205], v[38:41]
	v_mfma_f32_16x16x32_bf16 v[26:29], v[150:153], v[210:213], v[26:29]
	v_mfma_f32_16x16x32_bf16 v[22:25], v[186:189], v[210:213], v[22:25]
	v_mfma_f32_16x16x32_bf16 v[8:11], v[150:153], v[218:221], v[10:13]
	v_mfma_f32_16x16x32_bf16 v[4:7], v[186:189], v[218:221], v[4:7]
	v_mfma_f32_16x16x32_bf16 v[58:61], v[154:157], v[198:201], v[58:61]
	v_mfma_f32_16x16x32_bf16 v[54:57], v[190:193], v[198:201], v[54:57]
	v_mfma_f32_16x16x32_bf16 v[42:45], v[154:157], v[206:209], v[42:45]
	v_mfma_f32_16x16x32_bf16 v[38:41], v[190:193], v[206:209], v[38:41]
	v_mfma_f32_16x16x32_bf16 v[26:29], v[154:157], v[214:217], v[26:29]
	v_mfma_f32_16x16x32_bf16 v[22:25], v[190:193], v[214:217], v[22:25]
	v_mfma_f32_16x16x32_bf16 v[10:13], v[154:157], v[222:225], v[8:11]
	v_mfma_f32_16x16x32_bf16 v[6:9], v[190:193], v[222:225], v[4:7]
	s_setprio 0
	s_barrier
	s_add_i32 s66, s66, 2
	s_add_u32 s64, s64, 0x100
	s_addc_u32 s65, s65, 0
	s_cmp_gt_u32 s66, 13
	s_cbranch_scc0 .LBB0_616
	s_and_b64 vcc, exec, s[10:11]
	s_cbranch_vccz .LBB0_621
	s_barrier

; #define PG8_WAIT_V(n) asm volatile("s_waitcnt vmcnt(" #n ")" ::: "memory")
; #define PG8_BAR __builtin_amdgcn_s_barrier()
; template <class Epi, class Sched>
; __device__ __forceinline__ void gemm_phase(LAS unsigned char* lds, const Gemm g, const Sched& S, const Epi& E) {
;     int tid_ = threadIdx.x; asm volatile("" : "+v"(tid_));
;     const int tid = tid_, wid = __builtin_amdgcn_readfirstlane(tid >> 6), lane = tid & 63, wr = wid >> 2, wc = wid & 3, fr = lane & 15, fq = lane >> 4;
;     const int K = g.K, nt = K / BK;
;     unsigned voffA[2], voffB[2];
; #pragma unroll
;     for (int i = 0; i < 2; ++i) { int R, C; stage_rc(tid * 16 + i * 8192, R, C);
;         const int Ra = 128 * (R >> 6) + (R & 63);
;         const int Rb = Epi::HEADPERM ? (64 * (R >> 5) + perm32(R & 31)) : ((R & ~31) + perm32(R & 31));
;         voffA[i] = (unsigned)(Ra * g.lda + C) * 2u; voffB[i] = (unsigned)(Rb * K + C) * 2u; }
;     const size_t kstep = (size_t)(BK * 2);
;     const size_t hstepA = (size_t)64 * g.lda * 2, kstepA = (size_t)g.kstepA;
;     const size_t hstepB = (size_t)(Epi::HEADPERM ? 32 : 128) * K * 2;
;     const size_t tstep = (size_t)256 * K * 2;
;     const unsigned ldsw = (unsigned)wid * 1024u;
;     const unsigned lds_u32 = (unsigned)(size_t)lds;
;     const int aoff = lds_byte(wr * 64 + fr, fq * 8), boff = lds_byte(wc * 32 + fr, fq * 8);
;     ...
;     Unit cur, nxt; int ui = 0;
;     if (!S.next(0, cur)) return;
;     f32x4 acc[2][2][4][2];
; #pragma unroll
;     for (int a = 0; a < 2; ++a)
; #pragma unroll
;         for (int b = 0; b < 2; ++b)
; #pragma unroll
;             for (int m = 0; m < 4; ++m)
; #pragma unroll
;                 for (int n = 0; n < 2; ++n) acc[a][b][m][n] = (f32x4){0.f, 0.f, 0.f, 0.f};
;     bf16x8 At[4][2], B0[2][2], B1[2][2];
;     const char* cA = (const char*)g.A + (size_t)cur.pm * tstep; const char* cB = (const char*)g.Bt + (size_t)cur.pn * tstep;
;     PG8_STAGE(PG8_SB(0, 0), cB, voffB); PG8_STAGE(PG8_SB(0, 1), cB + hstepB, voffB); PG8_STAGE(PG8_SA(0, 0), cA, voffA); PG8_STAGE(PG8_SA(0, 1), cA + hstepA, voffA);
;     if (wr == 1) PG8_BAR;
;     PG8_WAIT_V(2); PG8_BAR;
;     PG8_STAGE(PG8_SB(1, 0), cB + kstep, voffB); PG8_STAGE(PG8_SA(1, 0), cA + kstepA, voffA); PG8_STAGE(PG8_SB(1, 1), cB + hstepB + kstep, voffB);
;     PG8_WAIT_V(6); PG8_BAR;
.LBB0_699:
	v_readlane_b32 s0, v243, 4
	v_mov_b32_e32 v2, v0
	v_readlane_b32 s1, v243, 5
	s_andn2_b64 vcc, exec, s[0:1]
	v_readfirstlane_b32 s1, v2
	s_cbranch_vccnz .LBB0_719
	s_mov_b32 s100, -1
	v_bfe_i32 v5, v2, 27, 1
	v_lshlrev_b32_e32 v3, 4, v2
	v_lshrrev_b32_e32 v5, 22, v5
	v_add_u32_e32 v5, v3, v5
	v_and_b32_e32 v5, 0xfffffc00, v5
	v_sub_u32_e32 v5, v3, v5
	v_ashrrev_i32_e32 v4, 31, v2
	v_lshrrev_b32_e32 v6, 4, v5
	v_lshrrev_b32_e32 v4, 26, v4
	v_bitop3_b32 v5, v6, v5, 32 bitop3:0x6c
	v_add_u32_e32 v4, v2, v4
	v_ashrrev_i32_e32 v7, 31, v5
	v_ashrrev_i32_e32 v4, 6, v4
	v_lshrrev_b32_e32 v7, 26, v7
	v_lshlrev_b32_e32 v6, 3, v4
	v_add_u32_e32 v7, v5, v7
	v_and_b32_e32 v6, -16, v6
	v_ashrrev_i32_e32 v8, 6, v7
	v_and_b32_e32 v7, 0xc0, v7
	v_add_u32_e32 v6, v8, v6
	v_sub_u32_e32 v5, v5, v7
	v_lshlrev_b32_e32 v4, 5, v4
	v_ashrrev_i16_sdwa v5, v164, sext(v5) dst_sel:DWORD dst_unused:UNUSED_PAD src0_sel:DWORD src1_sel:BYTE_0
	v_lshlrev_b32_e32 v7, 1, v6
	v_and_b32_e32 v9, 63, v6
	s_mov_b32 s4, 0x1fff80
	v_lshrrev_b32_e32 v10, 2, v6
	v_and_b32_e32 v8, 3, v8
	s_mov_b32 s5, 0x1fffe0
	v_and_b32_e32 v4, 32, v4
	v_bfe_i32 v5, v5, 0, 16
	v_and_or_b32 v9, v7, s4, v9
	v_and_b32_e32 v7, 24, v7
	v_and_b32_e32 v10, 4, v10
	v_and_or_b32 v6, v6, s5, v8
	v_or3_b32 v6, v6, v10, v7
	v_add_lshl_u32 v4, v4, v5, 1
	v_add_u32_e32 v3, 0x2000, v3
	v_lshl_add_u32 v165, v9, 11, v4
	v_lshl_add_u32 v166, v6, 11, v4
	v_ashrrev_i32_e32 v4, 31, v3
	v_lshrrev_b32_e32 v4, 22, v4
	v_add_u32_e32 v4, v3, v4
	v_ashrrev_i32_e32 v4, 10, v4
	v_mul_i32_i24_e32 v5, 0x400, v4
	v_sub_u32_e32 v3, v3, v5
	v_lshrrev_b32_e32 v5, 4, v3
	v_bitop3_b32 v3, v5, v3, 32 bitop3:0x6c
	v_ashrrev_i32_e32 v6, 31, v3
	v_lshrrev_b32_e32 v6, 26, v6
	v_lshlrev_b32_e32 v5, 3, v4
	v_add_u32_e32 v6, v3, v6
	v_and_b32_e32 v5, -16, v5
	v_ashrrev_i32_e32 v7, 6, v6
	v_and_b32_e32 v6, 0xc0, v6
	s_ashr_i32 s0, s1, 6
	v_add_u32_e32 v5, v7, v5
	v_sub_u32_e32 v3, v3, v6
	v_and_b32_e32 v7, 3, v7
	v_lshlrev_b32_e32 v4, 5, v4
	v_ashrrev_i16_sdwa v3, v164, sext(v3) dst_sel:DWORD dst_unused:UNUSED_PAD src0_sel:DWORD src1_sel:BYTE_0
	v_lshlrev_b32_e32 v6, 1, v5
	v_and_b32_e32 v8, 63, v5
	v_lshrrev_b32_e32 v9, 2, v5
	v_and_or_b32 v5, v5, s5, v7
	s_lshl_b32 s5, s0, 10
	v_and_b32_e32 v4, 32, v4
	v_bfe_i32 v3, v3, 0, 16
	v_and_or_b32 v8, v6, s4, v8
	v_and_b32_e32 v6, 24, v6
	v_and_b32_e32 v9, 4, v9
	v_readlane_b32 s6, v243, 28
	s_add_i32 s35, s5, 0
	v_or3_b32 v5, v5, v9, v6
	v_add_lshl_u32 v3, v4, v3, 1
	s_add_i32 s10, s34, s6
	s_add_i32 s64, s35, 0x10000
	s_mov_b32 m0, s64
	s_nop 0
	global_load_lds_dwordx4 v166, s[70:71]
	v_lshl_add_u32 v168, v5, 11, v3
	s_ashr_i32 s11, s10, 31
	s_add_i32 s65, s35, 0x12000
	s_mov_b32 m0, s65
	s_nop 0
	global_load_lds_dwordx4 v168, s[70:71]
	v_readlane_b32 s8, v243, 24
	s_ashr_i32 s4, s1, 8
	s_lshl_b64 s[6:7], s[10:11], 19
	s_add_i32 s38, s35, 0x14000
	v_readlane_b32 s9, v243, 25
	s_mov_b32 m0, s38
	s_nop 0
	global_load_lds_dwordx4 v166, s[8:9]
	s_add_i32 s39, s35, 0x16000
	s_mov_b32 m0, s39
	s_nop 0
	global_load_lds_dwordx4 v168, s[8:9]
	s_add_u32 s6, s42, s6
	s_addc_u32 s7, s43, s7
	s_mov_b32 m0, s35
	s_nop 0
	global_load_lds_dwordx4 v165, s[6:7]
	s_add_i32 s48, s35, 0x2000
	s_add_i32 s49, s35, 0x4000
	v_lshl_add_u32 v167, v8, 11, v3
	s_mov_b32 m0, s48
	s_nop 0
	global_load_lds_dwordx4 v167, s[6:7]
	s_add_u32 s8, s6, 0x20000
	s_addc_u32 s9, s7, 0
	s_mov_b32 m0, s49
	s_nop 0
	global_load_lds_dwordx4 v165, s[8:9]
	s_add_i32 s25, s35, 0x6000
	s_mov_b32 m0, s25
	s_nop 0
	global_load_lds_dwordx4 v167, s[8:9]
	s_cmp_eq_u32 s4, 1
	s_cselect_b64 s[96:97], -1, 0
	s_cmp_lg_u32 s4, 1
	s_cbranch_scc1 .LBB0_702
	s_barrier
.LBB0_702:
	v_and_b32_e32 v3, 15, v2
	v_lshrrev_b32_e32 v4, 1, v2
	v_and_b32_e32 v4, 24, v4
	v_lshlrev_b32_e32 v5, 6, v3
	v_lshlrev_b32_e32 v2, 2, v2
	s_and_b32 s5, s0, 3
	v_lshl_or_b32 v5, v4, 1, v5
	s_lshl_b32 s8, s4, 13
	v_and_b32_e32 v2, 32, v2
	v_bitop3_b32 v8, v5, s8, v2 bitop3:0xde
	s_lshl_b32 s5, s5, 12
	v_readlane_b32 s8, v242, 1
	s_lshl_b32 s11, s0, 5
	v_bitop3_b32 v5, v5, s5, v2 bitop3:0xde
	s_waitcnt vmcnt(2)
	s_barrier
	s_add_i32 s26, s35, 0x18000
	v_readlane_b32 s9, v242, 2
	s_mov_b32 m0, s26
	s_nop 0
	global_load_lds_dwordx4 v166, s[8:9]
	s_add_i32 s30, s35, 0x1a000
	s_add_i32 s31, s35, 0x8000
	s_mov_b32 m0, s30
	s_nop 0
	global_load_lds_dwordx4 v168, s[8:9]
	s_add_u32 s8, s6, 0x80
	s_addc_u32 s9, s7, 0
	s_add_i32 s21, s35, 0xa000
	s_add_i32 s23, s35, 0x1c000
	s_add_i32 s22, s35, 0x1e000
	s_add_i32 s24, s35, 0xc000
	s_cmpk_lt_u32 s1, 0x100
	s_cselect_b64 s[98:99], -1, 0
	s_lshl_b32 s1, s4, 7
	v_or_b32_e32 v2, s1, v3
	v_ashrrev_i32_e32 v7, 31, v2
	v_mov_b32_e32 v6, v2
	v_lshlrev_b64 v[144:145], 7, v[6:7]
	v_or_b32_e32 v6, 16, v2
	v_ashrrev_i32_e32 v7, 31, v6
	v_lshlrev_b64 v[146:147], 7, v[6:7]
	v_or_b32_e32 v6, 32, v2
	v_ashrrev_i32_e32 v7, 31, v6
	v_lshlrev_b64 v[148:149], 7, v[6:7]
	v_or_b32_e32 v6, 48, v2
	v_ashrrev_i32_e32 v7, 31, v6
	v_lshlrev_b64 v[150:151], 7, v[6:7]
	v_or_b32_e32 v6, 64, v2
	v_ashrrev_i32_e32 v7, 31, v6
	s_mov_b32 m0, s31
	s_nop 0
	global_load_lds_dwordx4 v165, s[8:9]
	v_lshlrev_b64 v[152:153], 7, v[6:7]
	v_or_b32_e32 v6, 0x50, v2
	s_mov_b32 m0, s21
	s_nop 0
	global_load_lds_dwordx4 v167, s[8:9]
	v_ashrrev_i32_e32 v7, 31, v6
	s_mov_b32 m0, s23
	s_nop 0
	global_load_lds_dwordx4 v166, s[76:77]
	v_lshlrev_b64 v[154:155], 7, v[6:7]
	v_or_b32_e32 v6, 0x60, v2
	s_mov_b32 m0, s22
	s_nop 0
	global_load_lds_dwordx4 v168, s[76:77]
	s_ashr_i32 s4, s1, 31
	v_ashrrev_i32_e32 v7, 31, v6
	s_waitcnt vmcnt(6)
	v_mov_b32_e32 v3, s4
	v_lshlrev_b64 v[156:157], 7, v[6:7]
	v_or_b32_e32 v6, 0x70, v2
	s_bfe_u32 s86, s0, 0x10001
	s_and_b32 s0, s11, 32
	v_ashrrev_i32_e32 v7, 31, v6
	v_lshlrev_b64 v[2:3], 6, v[2:3]
	s_mov_b32 s87, s63
	v_lshlrev_b64 v[158:159], 7, v[6:7]
	v_lshl_add_u64 v[160:161], s[40:41], 0, v[2:3]
	s_mov_b32 s28, 0
	v_add_u32_e32 v169, 0, v5
	v_add_u32_e32 v170, 0, v8
	s_lshl_b32 s62, s0, 1
	v_lshlrev_b32_e32 v134, 1, v4
	v_readlane_b32 s29, v243, 26
	s_mov_b64 s[14:15], s[70:71]
	s_barrier
	s_branch .LBB0_705

; #define PG8_LDA(dst, b, h) do { _Pragma("unroll") for (int m = 0; m < 4; ++m) _Pragma("unroll") for (int k = 0; k < 2; ++k) dst[m][k] = *(const LAS bf16x8*)(lds + PG8_SA(b, h) + aoff + m * 2048 + k * 1024); } while (0)
; #define PG8_LDB(dst, b, h) do { _Pragma("unroll") for (int n = 0; n < 2; ++n) _Pragma("unroll") for (int k = 0; k < 2; ++k) dst[n][k] = *(const LAS bf16x8*)(lds + PG8_SB(b, h) + boff + n * 2048 + k * 1024); } while (0)
; #define PG8_MMA(ai, bj, At, Bt) do { __builtin_amdgcn_s_setprio(1); _Pragma("unroll") for (int m = 0; m < 4; ++m) _Pragma("unroll") for (int n = 0; n < 2; ++n) _Pragma("unroll") for (int k = 0; k < 2; ++k) \
;         acc[ai][bj][m][n] = __builtin_amdgcn_mfma_f32_16x16x32_bf16(Bt[n][k], At[m][k], acc[ai][bj][m][n], 0, 0, 0); __builtin_amdgcn_s_setprio(0); } while (0)
; #define PG8_WAIT_V(n) asm volatile("s_waitcnt vmcnt(" #n ")" ::: "memory")
; #define PG8_WAIT_L(n) asm volatile("s_waitcnt lgkmcnt(" #n ")" ::: "memory")
; #define PG8_BAR __builtin_amdgcn_s_barrier()
; #define PG8_SCHED __builtin_amdgcn_sched_barrier(0)
; template <class Epi, class Sched>
; __device__ __forceinline__ void gemm_phase(LAS unsigned char* lds, const Gemm g, const Sched& S, const Epi& E) {
;     ...
;             const char* a1 = cA + (size_t)(t + 1) * kstepA;
;             const char* a2 = last ? nA : cA + (size_t)(t + 2) * kstepA; const char* b2 = last ? nB : cB + (size_t)(t + 2) * kstep;
;             const char* a3 = a2 + kstepA; const char* b3 = b2 + kstep;
;             PG8_LDB(B0, 0, 0); PG8_LDB(B1, 0, 1); PG8_SCHED; PG8_LDA(At, 0, 0); PG8_STAGE(PG8_SA(1, 1), a1 + hstepA, voffA);
;             PG8_WAIT_V(8); PG8_WAIT_L(0); PG8_BAR; PG8_MMA(0, 0, At, B0); PG8_MMA(0, 1, At, B1); PG8_BAR; PG8_SCHED;
;             PG8_LDA(At, 0, 1); PG8_STAGE(PG8_SB(0, 0), b2, voffB); PG8_STAGE(PG8_SB(0, 1), b2 + hstepB, voffB); PG8_STAGE(PG8_SA(0, 0), a2, voffA);
;             PG8_WAIT_V(8); PG8_WAIT_L(0); PG8_BAR; PG8_MMA(1, 0, At, B0); PG8_MMA(1, 1, At, B1); PG8_BAR; PG8_SCHED;
.LBB0_712:
	v_add_u32_e32 v162, 0x10000, v169
	ds_read_b128 v[172:175], v162
	ds_read_b128 v[176:179], v162 offset:1024
	ds_read_b128 v[180:183], v162 offset:2048
	ds_read_b128 v[184:187], v162 offset:3072
	v_add_u32_e32 v162, 0x14000, v169
	ds_read_b128 v[188:191], v162
	ds_read_b128 v[192:195], v162 offset:1024
	ds_read_b128 v[196:199], v162 offset:2048
	ds_read_b128 v[200:203], v162 offset:3072
	s_add_u32 vcc_lo, s6, 0x100
	s_addc_u32 vcc_hi, s7, 0
	s_cmp_eq_u32 s73, 12
	s_cselect_b32 s18, s11, vcc_lo
	s_cselect_b32 s19, s1, vcc_hi
	s_cselect_b32 s16, s44, s45
	s_cselect_b32 s17, s5, s72
	s_add_u32 s14, s18, 0x80
	s_addc_u32 s15, s19, 0
	ds_read_b128 v[204:207], v170
	ds_read_b128 v[208:211], v170 offset:1024
	ds_read_b128 v[212:215], v170 offset:2048
	ds_read_b128 v[216:219], v170 offset:3072
	ds_read_b128 v[220:223], v170 offset:4096
	ds_read_b128 v[224:227], v170 offset:5120
	ds_read_b128 v[228:231], v170 offset:6144
	ds_read_b128 v[232:235], v170 offset:7168
	s_add_u32 s6, s6, 0x20080
	s_addc_u32 s7, s7, 0
	s_mov_b32 m0, s24
	s_nop 0
	global_load_lds_dwordx4 v165, s[6:7]
	s_add_i32 s74, s35, 0xe000
	s_mov_b32 m0, s74
	s_nop 0
	global_load_lds_dwordx4 v167, s[6:7]
	s_waitcnt vmcnt(8)
	s_waitcnt lgkmcnt(0)
	s_barrier
	s_setprio 1
	s_waitcnt lgkmcnt(7)
	v_mfma_f32_16x16x32_bf16 v[126:129], v[172:175], v[204:207], v[126:129]
	v_mfma_f32_16x16x32_bf16 v[122:125], v[180:183], v[204:207], v[122:125]
	s_waitcnt lgkmcnt(5)
	v_mfma_f32_16x16x32_bf16 v[110:113], v[172:175], v[212:215], v[110:113]
	v_mfma_f32_16x16x32_bf16 v[106:109], v[180:183], v[212:215], v[106:109]
	s_waitcnt lgkmcnt(3)
	v_mfma_f32_16x16x32_bf16 v[94:97], v[172:175], v[220:223], v[94:97]
	v_mfma_f32_16x16x32_bf16 v[90:93], v[180:183], v[220:223], v[90:93]
	s_waitcnt lgkmcnt(1)
	v_mfma_f32_16x16x32_bf16 v[78:81], v[172:175], v[228:231], v[78:81]
	v_mfma_f32_16x16x32_bf16 v[74:77], v[180:183], v[228:231], v[74:77]
	v_mfma_f32_16x16x32_bf16 v[126:129], v[176:179], v[208:211], v[126:129]
	v_mfma_f32_16x16x32_bf16 v[122:125], v[184:187], v[208:211], v[122:125]
	v_mfma_f32_16x16x32_bf16 v[110:113], v[176:179], v[216:219], v[110:113]
	v_mfma_f32_16x16x32_bf16 v[106:109], v[184:187], v[216:219], v[106:109]
	v_mfma_f32_16x16x32_bf16 v[94:97], v[176:179], v[224:227], v[94:97]
	v_mfma_f32_16x16x32_bf16 v[90:93], v[184:187], v[224:227], v[90:93]
	s_waitcnt lgkmcnt(0)
	v_mfma_f32_16x16x32_bf16 v[78:81], v[176:179], v[232:235], v[78:81]
	v_mfma_f32_16x16x32_bf16 v[74:77], v[184:187], v[232:235], v[74:77]
	s_setprio 0
	s_setprio 1
	v_mfma_f32_16x16x32_bf16 v[118:121], v[188:191], v[204:207], v[118:121]
	v_mfma_f32_16x16x32_bf16 v[114:117], v[196:199], v[204:207], v[114:117]
	v_mfma_f32_16x16x32_bf16 v[102:105], v[188:191], v[212:215], v[102:105]
	v_mfma_f32_16x16x32_bf16 v[98:101], v[196:199], v[212:215], v[98:101]
	v_mfma_f32_16x16x32_bf16 v[86:89], v[188:191], v[220:223], v[86:89]
	v_mfma_f32_16x16x32_bf16 v[82:85], v[196:199], v[220:223], v[82:85]
	v_mfma_f32_16x16x32_bf16 v[70:73], v[188:191], v[228:231], v[70:73]
	v_mfma_f32_16x16x32_bf16 v[66:69], v[196:199], v[228:231], v[66:69]
	v_mfma_f32_16x16x32_bf16 v[118:121], v[192:195], v[208:211], v[118:121]
	v_mfma_f32_16x16x32_bf16 v[114:117], v[200:203], v[208:211], v[114:117]
	v_mfma_f32_16x16x32_bf16 v[102:105], v[192:195], v[216:219], v[102:105]
	v_mfma_f32_16x16x32_bf16 v[98:101], v[200:203], v[216:219], v[98:101]
	v_mfma_f32_16x16x32_bf16 v[86:89], v[192:195], v[224:227], v[86:89]
	v_mfma_f32_16x16x32_bf16 v[82:85], v[200:203], v[224:227], v[82:85]
	v_mfma_f32_16x16x32_bf16 v[70:73], v[192:195], v[232:235], v[70:73]
	v_mfma_f32_16x16x32_bf16 v[66:69], v[200:203], v[232:235], v[66:69]
	s_setprio 0
	s_barrier
	ds_read_b128 v[204:207], v170 offset:16384
	ds_read_b128 v[208:211], v170 offset:17408
	ds_read_b128 v[212:215], v170 offset:18432
	ds_read_b128 v[216:219], v170 offset:19456
	ds_read_b128 v[220:223], v170 offset:20480
	ds_read_b128 v[224:227], v170 offset:21504
	ds_read_b128 v[228:231], v170 offset:22528
	ds_read_b128 v[232:235], v170 offset:23552
	s_mov_b32 m0, s64
	s_nop 0
	global_load_lds_dwordx4 v166, s[16:17]
	s_nop 0
	s_mov_b32 m0, s65
	s_nop 0
	global_load_lds_dwordx4 v168, s[16:17]
	s_add_u32 s6, s16, 0x40000
	s_addc_u32 s7, s17, 0
	s_mov_b32 m0, s38
	s_nop 0
	global_load_lds_dwordx4 v166, s[6:7]
	s_nop 0
	s_mov_b32 m0, s39
	s_nop 0
	global_load_lds_dwordx4 v168, s[6:7]
	s_mov_b32 m0, s35
	s_nop 0
	global_load_lds_dwordx4 v165, s[18:19]
	s_nop 0
	s_mov_b32 m0, s48
	s_nop 0
	global_load_lds_dwordx4 v167, s[18:19]
	s_waitcnt vmcnt(8)
	s_waitcnt lgkmcnt(0)
	s_barrier
; #define PG8_LDA(dst, b, h) do { _Pragma("unroll") for (int m = 0; m < 4; ++m) _Pragma("unroll") for (int k = 0; k < 2; ++k) dst[m][k] = *(const LAS bf16x8*)(lds + PG8_SA(b, h) + aoff + m * 2048 + k * 1024); } while (0)
; #define PG8_LDB(dst, b, h) do { _Pragma("unroll") for (int n = 0; n < 2; ++n) _Pragma("unroll") for (int k = 0; k < 2; ++k) dst[n][k] = *(const LAS bf16x8*)(lds + PG8_SB(b, h) + boff + n * 2048 + k * 1024); } while (0)
; #define PG8_MMA(ai, bj, At, Bt) do { __builtin_amdgcn_s_setprio(1); _Pragma("unroll") for (int m = 0; m < 4; ++m) _Pragma("unroll") for (int n = 0; n < 2; ++n) _Pragma("unroll") for (int k = 0; k < 2; ++k) \
;         acc[ai][bj][m][n] = __builtin_amdgcn_mfma_f32_16x16x32_bf16(Bt[n][k], At[m][k], acc[ai][bj][m][n], 0, 0, 0); __builtin_amdgcn_s_setprio(0); } while (0)
; #define PG8_WAIT_V(n) asm volatile("s_waitcnt vmcnt(" #n ")" ::: "memory")
; #define PG8_WAIT_L(n) asm volatile("s_waitcnt lgkmcnt(" #n ")" ::: "memory")
; #define PG8_BAR __builtin_amdgcn_s_barrier()
; #define PG8_SCHED __builtin_amdgcn_sched_barrier(0)
; template <class Epi, class Sched>
; __device__ __forceinline__ void gemm_phase(LAS unsigned char* lds, const Gemm g, const Sched& S, const Epi& E) {
;     ...
;             PG8_WAIT_V(8); PG8_WAIT_L(0); PG8_BAR; PG8_MMA(1, 0, At, B0); PG8_MMA(1, 1, At, B1); PG8_BAR; PG8_SCHED;
;             PG8_LDB(B0, 1, 0); PG8_LDB(B1, 1, 1); PG8_SCHED; PG8_LDA(At, 1, 0); PG8_STAGE(PG8_SA(0, 1), a2 + hstepA, voffA);
;             PG8_WAIT_V(8); PG8_WAIT_L(0); PG8_BAR; PG8_MMA(0, 0, At, B0); PG8_MMA(0, 1, At, B1); PG8_BAR; PG8_SCHED;
	s_setprio 1
	s_waitcnt lgkmcnt(7)
	v_mfma_f32_16x16x32_bf16 v[62:65], v[172:175], v[204:207], v[62:65]
	v_mfma_f32_16x16x32_bf16 v[58:61], v[180:183], v[204:207], v[58:61]
	s_waitcnt lgkmcnt(5)
	v_mfma_f32_16x16x32_bf16 v[46:49], v[172:175], v[212:215], v[46:49]
	v_mfma_f32_16x16x32_bf16 v[42:45], v[180:183], v[212:215], v[42:45]
	s_waitcnt lgkmcnt(3)
	v_mfma_f32_16x16x32_bf16 v[30:33], v[172:175], v[220:223], v[30:33]
	v_mfma_f32_16x16x32_bf16 v[26:29], v[180:183], v[220:223], v[26:29]
	s_waitcnt lgkmcnt(1)
	v_mfma_f32_16x16x32_bf16 v[14:17], v[172:175], v[228:231], v[14:17]
	v_mfma_f32_16x16x32_bf16 v[10:13], v[180:183], v[228:231], v[10:13]
	v_mfma_f32_16x16x32_bf16 v[62:65], v[176:179], v[208:211], v[62:65]
	v_mfma_f32_16x16x32_bf16 v[58:61], v[184:187], v[208:211], v[58:61]
	v_mfma_f32_16x16x32_bf16 v[46:49], v[176:179], v[216:219], v[46:49]
	v_mfma_f32_16x16x32_bf16 v[42:45], v[184:187], v[216:219], v[42:45]
	v_mfma_f32_16x16x32_bf16 v[30:33], v[176:179], v[224:227], v[30:33]
	v_mfma_f32_16x16x32_bf16 v[26:29], v[184:187], v[224:227], v[26:29]
	s_waitcnt lgkmcnt(0)
	v_mfma_f32_16x16x32_bf16 v[14:17], v[176:179], v[232:235], v[14:17]
	v_mfma_f32_16x16x32_bf16 v[10:13], v[184:187], v[232:235], v[10:13]
	s_setprio 0
	s_setprio 1
	v_mfma_f32_16x16x32_bf16 v[54:57], v[188:191], v[204:207], v[54:57]
	v_mfma_f32_16x16x32_bf16 v[50:53], v[196:199], v[204:207], v[50:53]
	v_mfma_f32_16x16x32_bf16 v[38:41], v[188:191], v[212:215], v[38:41]
	v_mfma_f32_16x16x32_bf16 v[34:37], v[196:199], v[212:215], v[34:37]
	v_mfma_f32_16x16x32_bf16 v[22:25], v[188:191], v[220:223], v[22:25]
	v_mfma_f32_16x16x32_bf16 v[18:21], v[196:199], v[220:223], v[18:21]
	v_mfma_f32_16x16x32_bf16 v[6:9], v[188:191], v[228:231], v[6:9]
	v_mfma_f32_16x16x32_bf16 v[2:5], v[196:199], v[228:231], v[2:5]
	v_mfma_f32_16x16x32_bf16 v[54:57], v[192:195], v[208:211], v[54:57]
	v_mfma_f32_16x16x32_bf16 v[50:53], v[200:203], v[208:211], v[50:53]
	v_mfma_f32_16x16x32_bf16 v[38:41], v[192:195], v[216:219], v[38:41]
	v_mfma_f32_16x16x32_bf16 v[34:37], v[200:203], v[216:219], v[34:37]
	v_mfma_f32_16x16x32_bf16 v[22:25], v[192:195], v[224:227], v[22:25]
	v_mfma_f32_16x16x32_bf16 v[18:21], v[200:203], v[224:227], v[18:21]
	v_mfma_f32_16x16x32_bf16 v[6:9], v[192:195], v[232:235], v[6:9]
	v_mfma_f32_16x16x32_bf16 v[2:5], v[200:203], v[232:235], v[2:5]
	s_setprio 0
	s_barrier
	v_add_u32_e32 v162, 0x18000, v169
	ds_read_b128 v[172:175], v162
	ds_read_b128 v[176:179], v162 offset:1024
	ds_read_b128 v[180:183], v162 offset:2048
	ds_read_b128 v[184:187], v162 offset:3072
	v_add_u32_e32 v162, 0x1c000, v169
	ds_read_b128 v[188:191], v162
	ds_read_b128 v[192:195], v162 offset:1024
	ds_read_b128 v[196:199], v162 offset:2048
	ds_read_b128 v[200:203], v162 offset:3072
	ds_read_b128 v[204:207], v170 offset:32768
	ds_read_b128 v[208:211], v170 offset:33792
	ds_read_b128 v[212:215], v170 offset:34816
	ds_read_b128 v[216:219], v170 offset:35840
	ds_read_b128 v[220:223], v170 offset:36864
	ds_read_b128 v[224:227], v170 offset:37888
	ds_read_b128 v[228:231], v170 offset:38912
	ds_read_b128 v[232:235], v170 offset:39936
	s_add_u32 s6, s18, 0x20000
	s_addc_u32 s7, s19, 0
	s_mov_b32 m0, s49
	s_nop 0
	global_load_lds_dwordx4 v165, s[6:7]
	s_nop 0
	s_mov_b32 m0, s25
	s_nop 0
	global_load_lds_dwordx4 v167, s[6:7]
	s_waitcnt vmcnt(8)
	s_waitcnt lgkmcnt(0)
	s_barrier
	s_setprio 1
	s_waitcnt lgkmcnt(7)
	v_mfma_f32_16x16x32_bf16 v[126:129], v[172:175], v[204:207], v[126:129]
	v_mfma_f32_16x16x32_bf16 v[122:125], v[180:183], v[204:207], v[122:125]
	s_waitcnt lgkmcnt(5)
	v_mfma_f32_16x16x32_bf16 v[110:113], v[172:175], v[212:215], v[110:113]
	v_mfma_f32_16x16x32_bf16 v[106:109], v[180:183], v[212:215], v[106:109]
	s_waitcnt lgkmcnt(3)
	v_mfma_f32_16x16x32_bf16 v[94:97], v[172:175], v[220:223], v[94:97]
	v_mfma_f32_16x16x32_bf16 v[90:93], v[180:183], v[220:223], v[90:93]
	s_waitcnt lgkmcnt(1)
	v_mfma_f32_16x16x32_bf16 v[78:81], v[172:175], v[228:231], v[78:81]
	v_mfma_f32_16x16x32_bf16 v[74:77], v[180:183], v[228:231], v[74:77]
	v_mfma_f32_16x16x32_bf16 v[126:129], v[176:179], v[208:211], v[126:129]
	v_mfma_f32_16x16x32_bf16 v[122:125], v[184:187], v[208:211], v[122:125]
	v_mfma_f32_16x16x32_bf16 v[110:113], v[176:179], v[216:219], v[110:113]
	v_mfma_f32_16x16x32_bf16 v[106:109], v[184:187], v[216:219], v[106:109]
	v_mfma_f32_16x16x32_bf16 v[94:97], v[176:179], v[224:227], v[94:97]
	v_mfma_f32_16x16x32_bf16 v[90:93], v[184:187], v[224:227], v[90:93]
	s_waitcnt lgkmcnt(0)
	v_mfma_f32_16x16x32_bf16 v[78:81], v[176:179], v[232:235], v[78:81]
	v_mfma_f32_16x16x32_bf16 v[74:77], v[184:187], v[232:235], v[74:77]
	s_setprio 0
	s_setprio 1
	v_mfma_f32_16x16x32_bf16 v[118:121], v[188:191], v[204:207], v[118:121]
	v_mfma_f32_16x16x32_bf16 v[114:117], v[196:199], v[204:207], v[114:117]
	v_mfma_f32_16x16x32_bf16 v[102:105], v[188:191], v[212:215], v[102:105]
	v_mfma_f32_16x16x32_bf16 v[98:101], v[196:199], v[212:215], v[98:101]
	v_mfma_f32_16x16x32_bf16 v[86:89], v[188:191], v[220:223], v[86:89]
	v_mfma_f32_16x16x32_bf16 v[82:85], v[196:199], v[220:223], v[82:85]
	v_mfma_f32_16x16x32_bf16 v[70:73], v[188:191], v[228:231], v[70:73]
	v_mfma_f32_16x16x32_bf16 v[66:69], v[196:199], v[228:231], v[66:69]
	v_mfma_f32_16x16x32_bf16 v[118:121], v[192:195], v[208:211], v[118:121]
	v_mfma_f32_16x16x32_bf16 v[114:117], v[200:203], v[208:211], v[114:117]
	v_mfma_f32_16x16x32_bf16 v[102:105], v[192:195], v[216:219], v[102:105]
	v_mfma_f32_16x16x32_bf16 v[98:101], v[200:203], v[216:219], v[98:101]
	v_mfma_f32_16x16x32_bf16 v[86:89], v[192:195], v[224:227], v[86:89]
	v_mfma_f32_16x16x32_bf16 v[82:85], v[200:203], v[224:227], v[82:85]
	v_mfma_f32_16x16x32_bf16 v[70:73], v[192:195], v[232:235], v[70:73]
	v_mfma_f32_16x16x32_bf16 v[66:69], v[200:203], v[232:235], v[66:69]
	s_setprio 0
	s_barrier
; #define PG8_LDA(dst, b, h) do { _Pragma("unroll") for (int m = 0; m < 4; ++m) _Pragma("unroll") for (int k = 0; k < 2; ++k) dst[m][k] = *(const LAS bf16x8*)(lds + PG8_SA(b, h) + aoff + m * 2048 + k * 1024); } while (0)
; #define PG8_MMA(ai, bj, At, Bt) do { __builtin_amdgcn_s_setprio(1); _Pragma("unroll") for (int m = 0; m < 4; ++m) _Pragma("unroll") for (int n = 0; n < 2; ++n) _Pragma("unroll") for (int k = 0; k < 2; ++k) \
;         acc[ai][bj][m][n] = __builtin_amdgcn_mfma_f32_16x16x32_bf16(Bt[n][k], At[m][k], acc[ai][bj][m][n], 0, 0, 0); __builtin_amdgcn_s_setprio(0); } while (0)
; #define PG8_WAIT_V(n) asm volatile("s_waitcnt vmcnt(" #n ")" ::: "memory")
; #define PG8_WAIT_L(n) asm volatile("s_waitcnt lgkmcnt(" #n ")" ::: "memory")
; #define PG8_BAR __builtin_amdgcn_s_barrier()
; #define PG8_SCHED __builtin_amdgcn_sched_barrier(0)
; template <class Epi, class Sched>
; __device__ __forceinline__ void gemm_phase(LAS unsigned char* lds, const Gemm g, const Sched& S, const Epi& E) {
;     ...
;             PG8_LDA(At, 1, 1); PG8_STAGE(PG8_SB(1, 0), b3, voffB); PG8_STAGE(PG8_SB(1, 1), b3 + hstepB, voffB); PG8_STAGE(PG8_SA(1, 0), a3, voffA);
;             PG8_WAIT_V(8); PG8_WAIT_L(0); PG8_BAR; PG8_MMA(1, 0, At, B0); PG8_MMA(1, 1, At, B1); PG8_BAR; PG8_SCHED;
;         }
;         if (wr == 0) PG8_BAR;
	ds_read_b128 v[204:207], v170 offset:49152
	ds_read_b128 v[208:211], v170 offset:50176
	ds_read_b128 v[212:215], v170 offset:51200
	ds_read_b128 v[216:219], v170 offset:52224
	ds_read_b128 v[220:223], v170 offset:53248
	ds_read_b128 v[224:227], v170 offset:54272
	ds_read_b128 v[228:231], v170 offset:55296
	ds_read_b128 v[232:235], v170 offset:56320
	s_add_u32 s6, s16, 0x80
	s_addc_u32 s7, s17, 0
	s_mov_b32 m0, s26
	s_nop 0
	global_load_lds_dwordx4 v166, s[6:7]
	s_nop 0
	s_mov_b32 m0, s30
	s_nop 0
	global_load_lds_dwordx4 v168, s[6:7]
	s_add_u32 s6, s16, 0x40080
	s_addc_u32 s7, s17, 0
	s_mov_b32 m0, s23
	s_nop 0
	global_load_lds_dwordx4 v166, s[6:7]
	s_nop 0
	s_mov_b32 m0, s22
	s_nop 0
	global_load_lds_dwordx4 v168, s[6:7]
	s_mov_b32 m0, s31
	s_nop 0
	global_load_lds_dwordx4 v165, s[14:15]
	s_nop 0
	s_mov_b32 m0, s21
	s_nop 0
	global_load_lds_dwordx4 v167, s[14:15]
	s_waitcnt vmcnt(8)
	s_waitcnt lgkmcnt(0)
	s_barrier
	s_setprio 1
	s_waitcnt lgkmcnt(7)
	v_mfma_f32_16x16x32_bf16 v[62:65], v[172:175], v[204:207], v[62:65]
	v_mfma_f32_16x16x32_bf16 v[58:61], v[180:183], v[204:207], v[58:61]
	s_waitcnt lgkmcnt(5)
	v_mfma_f32_16x16x32_bf16 v[46:49], v[172:175], v[212:215], v[46:49]
	v_mfma_f32_16x16x32_bf16 v[42:45], v[180:183], v[212:215], v[42:45]
	s_waitcnt lgkmcnt(3)
	v_mfma_f32_16x16x32_bf16 v[30:33], v[172:175], v[220:223], v[30:33]
	v_mfma_f32_16x16x32_bf16 v[26:29], v[180:183], v[220:223], v[26:29]
	s_waitcnt lgkmcnt(1)
	v_mfma_f32_16x16x32_bf16 v[14:17], v[172:175], v[228:231], v[14:17]
	v_mfma_f32_16x16x32_bf16 v[10:13], v[180:183], v[228:231], v[10:13]
	v_mfma_f32_16x16x32_bf16 v[62:65], v[176:179], v[208:211], v[62:65]
	v_mfma_f32_16x16x32_bf16 v[58:61], v[184:187], v[208:211], v[58:61]
	v_mfma_f32_16x16x32_bf16 v[46:49], v[176:179], v[216:219], v[46:49]
	v_mfma_f32_16x16x32_bf16 v[42:45], v[184:187], v[216:219], v[42:45]
	v_mfma_f32_16x16x32_bf16 v[30:33], v[176:179], v[224:227], v[30:33]
	v_mfma_f32_16x16x32_bf16 v[26:29], v[184:187], v[224:227], v[26:29]
	s_waitcnt lgkmcnt(0)
	v_mfma_f32_16x16x32_bf16 v[14:17], v[176:179], v[232:235], v[14:17]
	v_mfma_f32_16x16x32_bf16 v[10:13], v[184:187], v[232:235], v[10:13]
	s_setprio 0
	s_setprio 1
	v_mfma_f32_16x16x32_bf16 v[54:57], v[188:191], v[204:207], v[54:57]
	v_mfma_f32_16x16x32_bf16 v[50:53], v[196:199], v[204:207], v[50:53]
	v_mfma_f32_16x16x32_bf16 v[38:41], v[188:191], v[212:215], v[38:41]
	v_mfma_f32_16x16x32_bf16 v[34:37], v[196:199], v[212:215], v[34:37]
	v_mfma_f32_16x16x32_bf16 v[22:25], v[188:191], v[220:223], v[22:25]
	v_mfma_f32_16x16x32_bf16 v[18:21], v[196:199], v[220:223], v[18:21]
	v_mfma_f32_16x16x32_bf16 v[6:9], v[188:191], v[228:231], v[6:9]
	v_mfma_f32_16x16x32_bf16 v[2:5], v[196:199], v[228:231], v[2:5]
	v_mfma_f32_16x16x32_bf16 v[54:57], v[192:195], v[208:211], v[54:57]
	v_mfma_f32_16x16x32_bf16 v[50:53], v[200:203], v[208:211], v[50:53]
	v_mfma_f32_16x16x32_bf16 v[38:41], v[192:195], v[216:219], v[38:41]
	v_mfma_f32_16x16x32_bf16 v[34:37], v[200:203], v[216:219], v[34:37]
	v_mfma_f32_16x16x32_bf16 v[22:25], v[192:195], v[224:227], v[22:25]
	v_mfma_f32_16x16x32_bf16 v[18:21], v[200:203], v[224:227], v[18:21]
	v_mfma_f32_16x16x32_bf16 v[6:9], v[192:195], v[232:235], v[6:9]
	v_mfma_f32_16x16x32_bf16 v[2:5], v[200:203], v[232:235], v[2:5]
	s_setprio 0
	s_barrier
	s_add_i32 s73, s73, 2
	s_add_u32 s45, s45, 0x100
	s_addc_u32 s72, s72, 0
	s_cmp_gt_u32 s73, 13
	s_mov_b64 s[6:7], vcc
	s_cbranch_scc0 .LBB0_712
	s_and_b64 vcc, exec, s[98:99]
	s_cbranch_vccz .LBB0_715
	s_barrier

; #define PG8_WAIT_V(n) asm volatile("s_waitcnt vmcnt(" #n ")" ::: "memory")
; #define PG8_BAR __builtin_amdgcn_s_barrier()
; template <class Epi, class Sched>
; __device__ __forceinline__ void gemm_phase(LAS unsigned char* lds, const Gemm g, const Sched& S, const Epi& E) {
;     int tid_ = threadIdx.x; asm volatile("" : "+v"(tid_));
;     const int tid = tid_, wid = __builtin_amdgcn_readfirstlane(tid >> 6), lane = tid & 63, wr = wid >> 2, wc = wid & 3, fr = lane & 15, fq = lane >> 4;
;     const int K = g.K, nt = K / BK;
;     unsigned voffA[2], voffB[2];
; #pragma unroll
;     for (int i = 0; i < 2; ++i) { int R, C; stage_rc(tid * 16 + i * 8192, R, C);
;         const int Ra = 128 * (R >> 6) + (R & 63);
;         const int Rb = Epi::HEADPERM ? (64 * (R >> 5) + perm32(R & 31)) : ((R & ~31) + perm32(R & 31));
;         voffA[i] = (unsigned)(Ra * g.lda + C) * 2u; voffB[i] = (unsigned)(Rb * K + C) * 2u; }
;     const size_t kstep = (size_t)(BK * 2);
;     const size_t hstepA = (size_t)64 * g.lda * 2, kstepA = (size_t)g.kstepA;
;     const size_t hstepB = (size_t)(Epi::HEADPERM ? 32 : 128) * K * 2;
;     const size_t tstep = (size_t)256 * K * 2;
;     const unsigned ldsw = (unsigned)wid * 1024u;
;     const unsigned lds_u32 = (unsigned)(size_t)lds;
;     const int aoff = lds_byte(wr * 64 + fr, fq * 8), boff = lds_byte(wc * 32 + fr, fq * 8);
;     ...
;     Unit cur, nxt; int ui = 0;
;     if (!S.next(0, cur)) return;
;     f32x4 acc[2][2][4][2];
; #pragma unroll
;     for (int a = 0; a < 2; ++a)
; #pragma unroll
;         for (int b = 0; b < 2; ++b)
; #pragma unroll
;             for (int m = 0; m < 4; ++m)
; #pragma unroll
;                 for (int n = 0; n < 2; ++n) acc[a][b][m][n] = (f32x4){0.f, 0.f, 0.f, 0.f};
;     bf16x8 At[4][2], B0[2][2], B1[2][2];
;     const char* cA = (const char*)g.A + (size_t)cur.pm * tstep; const char* cB = (const char*)g.Bt + (size_t)cur.pn * tstep;
;     PG8_STAGE(PG8_SB(0, 0), cB, voffB); PG8_STAGE(PG8_SB(0, 1), cB + hstepB, voffB); PG8_STAGE(PG8_SA(0, 0), cA, voffA); PG8_STAGE(PG8_SA(0, 1), cA + hstepA, voffA);
;     if (wr == 1) PG8_BAR;
;     PG8_WAIT_V(2); PG8_BAR;
;     PG8_STAGE(PG8_SB(1, 0), cB + kstep, voffB); PG8_STAGE(PG8_SA(1, 0), cA + kstepA, voffA); PG8_STAGE(PG8_SB(1, 1), cB + hstepB + kstep, voffB);
;     PG8_WAIT_V(6); PG8_BAR;
.LBB0_767:
	s_or_b64 exec, exec, s[0:1]
	v_readlane_b32 s4, v243, 22
	s_waitcnt lgkmcnt(0)
	v_mov_b32_e32 v2, v0
	v_readlane_b32 s5, v243, 23
	s_xor_b64 s[0:1], s[94:95], -1
	s_barrier
	s_andn2_b64 vcc, exec, s[4:5]
	v_readfirstlane_b32 s6, v2
	s_cbranch_vccnz .LBB0_698
	v_bfe_i32 v5, v2, 27, 1
	v_lshlrev_b32_e32 v3, 4, v2
	v_lshrrev_b32_e32 v5, 22, v5
	v_add_u32_e32 v5, v3, v5
	v_and_b32_e32 v5, 0xfffffc00, v5
	v_sub_u32_e32 v5, v3, v5
	v_ashrrev_i32_e32 v4, 31, v2
	v_lshrrev_b32_e32 v6, 4, v5
	v_lshrrev_b32_e32 v4, 26, v4
	v_bitop3_b32 v5, v6, v5, 32 bitop3:0x6c
	v_add_u32_e32 v4, v2, v4
	v_ashrrev_i32_e32 v7, 31, v5
	v_ashrrev_i32_e32 v4, 6, v4
	v_lshrrev_b32_e32 v7, 26, v7
	v_lshlrev_b32_e32 v6, 3, v4
	v_add_u32_e32 v7, v5, v7
	v_and_b32_e32 v6, -16, v6
	v_ashrrev_i32_e32 v8, 6, v7
	v_and_b32_e32 v7, 0xc0, v7
	v_add_u32_e32 v6, v8, v6
	v_sub_u32_e32 v5, v5, v7
	v_lshlrev_b32_e32 v4, 5, v4
	v_ashrrev_i16_sdwa v5, v164, sext(v5) dst_sel:DWORD dst_unused:UNUSED_PAD src0_sel:DWORD src1_sel:BYTE_0
	v_lshlrev_b32_e32 v7, 1, v6
	v_and_b32_e32 v9, 63, v6
	s_mov_b32 s4, 0x1ffff80
	v_lshrrev_b32_e32 v10, 2, v6
	v_and_b32_e32 v8, 3, v8
	s_mov_b32 s5, 0x7ffe0
	v_and_b32_e32 v4, 32, v4
	v_bfe_i32 v5, v5, 0, 16
	v_and_or_b32 v9, v7, s4, v9
	v_and_b32_e32 v7, 24, v7
	v_and_b32_e32 v10, 4, v10
	v_and_or_b32 v6, v6, s5, v8
	v_or3_b32 v6, v6, v10, v7
	v_add_lshl_u32 v4, v4, v5, 1
	v_add_u32_e32 v3, 0x2000, v3
	v_lshl_add_u32 v148, v9, 7, v4
	v_lshl_add_u32 v149, v6, 13, v4
	v_ashrrev_i32_e32 v4, 31, v3
	v_lshrrev_b32_e32 v4, 22, v4
	v_add_u32_e32 v4, v3, v4
	v_ashrrev_i32_e32 v4, 10, v4
	v_mul_i32_i24_e32 v5, 0x400, v4
	v_sub_u32_e32 v3, v3, v5
	v_lshrrev_b32_e32 v5, 4, v3
	v_bitop3_b32 v3, v5, v3, 32 bitop3:0x6c
	v_ashrrev_i32_e32 v6, 31, v3
	v_lshrrev_b32_e32 v6, 26, v6
	v_lshlrev_b32_e32 v5, 3, v4
	v_add_u32_e32 v6, v3, v6
	v_and_b32_e32 v5, -16, v5
	v_ashrrev_i32_e32 v7, 6, v6
	v_and_b32_e32 v6, 0xc0, v6
	v_add_u32_e32 v5, v7, v5
	v_sub_u32_e32 v3, v3, v6
	s_ashr_i32 s7, s6, 6
	v_lshlrev_b32_e32 v4, 5, v4
	v_ashrrev_i16_sdwa v3, v164, sext(v3) dst_sel:DWORD dst_unused:UNUSED_PAD src0_sel:DWORD src1_sel:BYTE_0
	v_lshlrev_b32_e32 v6, 1, v5
	v_and_b32_e32 v8, 63, v5
	v_lshrrev_b32_e32 v9, 2, v5
	v_and_b32_e32 v7, 3, v7
	s_lshl_b32 s9, s7, 10
	v_and_b32_e32 v4, 32, v4
	v_bfe_i32 v3, v3, 0, 16
	v_and_or_b32 v8, v6, s4, v8
	v_and_b32_e32 v6, 24, v6
	v_and_b32_e32 v9, 4, v9
	v_and_or_b32 v5, v5, s5, v7
	v_readlane_b32 s4, v242, 3
	s_add_i32 s21, s9, 0
	v_or3_b32 v5, v5, v9, v6
	v_add_lshl_u32 v3, v4, v3, 1
	s_add_i32 s96, s34, s4
	s_add_i32 s22, s21, 0x10000
	s_mov_b32 m0, s22
	s_nop 0
	global_load_lds_dwordx4 v149, s[78:79]
	v_lshl_add_u32 v151, v5, 13, v3
	s_ashr_i32 s97, s96, 31
	s_add_i32 s23, s21, 0x12000
	s_mov_b32 m0, s23
	s_nop 0
	global_load_lds_dwordx4 v151, s[78:79]
	s_ashr_i32 s8, s6, 8
	s_lshl_b64 s[4:5], s[96:97], 21
	s_add_i32 s24, s21, 0x14000
	s_mov_b32 m0, s24
	s_nop 0
	global_load_lds_dwordx4 v149, s[80:81]
	s_add_i32 s25, s21, 0x16000
	s_mov_b32 m0, s25
	s_nop 0
	global_load_lds_dwordx4 v151, s[80:81]
	s_add_u32 s12, s46, s4
	s_addc_u32 s13, s47, s5
	s_mov_b32 m0, s21
	s_nop 0
	global_load_lds_dwordx4 v148, s[12:13]
	v_lshl_add_u32 v150, v8, 7, v3
	s_add_i32 s26, s21, 0x2000
	s_mov_b32 m0, s26
	s_nop 0
	global_load_lds_dwordx4 v150, s[12:13]
	s_add_i32 s28, s21, 0x4000
	s_add_u32 s4, s12, 0x2000
	s_addc_u32 s5, s13, 0
	s_mov_b32 m0, s28
	s_nop 0
	global_load_lds_dwordx4 v148, s[4:5]
	s_add_i32 s30, s21, 0x6000
	s_mov_b32 m0, s30
	s_nop 0
	global_load_lds_dwordx4 v150, s[4:5]
	s_cmp_eq_u32 s8, 1
	s_cselect_b64 s[4:5], -1, 0
	s_cmp_lg_u32 s8, 1
	s_cbranch_scc1 .LBB0_770
	s_barrier
.LBB0_770:
	v_and_b32_e32 v3, 15, v2
	v_lshrrev_b32_e32 v4, 1, v2
	v_and_b32_e32 v4, 24, v4
	v_lshlrev_b32_e32 v5, 6, v3
	v_lshlrev_b32_e32 v2, 2, v2
	v_lshl_or_b32 v5, v4, 1, v5
	s_lshl_b32 s9, s8, 13
	v_and_b32_e32 v2, 32, v2
	s_lshl_b32 s7, s7, 5
	v_bitop3_b32 v6, v5, s9, v2 bitop3:0xde
	s_and_b32 s9, s7, 0x60
	s_lshl_b32 s7, s9, 7
	v_bitop3_b32 v5, v5, s7, v2 bitop3:0xde
	s_waitcnt vmcnt(2)
	s_barrier
	s_add_i32 s31, s21, 0x18000
	s_mov_b32 m0, s31
	s_nop 0
	global_load_lds_dwordx4 v149, s[82:83]
	s_add_i32 s35, s21, 0x1a000
	s_add_i32 s38, s21, 0x8000
	s_mov_b32 m0, s35
	s_nop 0
	global_load_lds_dwordx4 v151, s[82:83]
	s_add_u32 s10, s12, 0x8000
	s_addc_u32 s11, s13, 0
	s_mov_b32 m0, s38
	s_nop 0
	global_load_lds_dwordx4 v148, s[10:11]
	s_add_i32 s39, s21, 0xa000
	s_mov_b32 m0, s39
	s_nop 0
	global_load_lds_dwordx4 v150, s[10:11]
	s_add_i32 s48, s21, 0x1c000
	s_mov_b32 m0, s48
	s_nop 0
	global_load_lds_dwordx4 v149, s[92:93]
	s_add_i32 s49, s21, 0x1e000
	s_add_i32 s62, s21, 0xc000
	s_mov_b32 m0, s49
	s_nop 0
	global_load_lds_dwordx4 v151, s[92:93]
	s_cmpk_lt_u32 s6, 0x100
	s_cselect_b64 s[6:7], -1, 0
	s_lshl_b32 s8, s8, 7
	s_waitcnt vmcnt(6)
	s_ashr_i32 s10, s8, 31
	v_or_b32_e32 v2, s8, v3
	v_mov_b32_e32 v3, s10
	v_or_b32_e32 v134, s9, v4
	v_lshlrev_b64 v[144:145], 10, v[2:3]
	s_mov_b32 s64, 0
	v_add_u32_e32 v152, 0, v5
	v_add_u32_e32 v153, 0, v6
	v_readlane_b32 s29, v242, 4
	s_mov_b64 s[14:15], s[78:79]
	s_barrier
	s_branch .LBB0_773

; #define PG8_LDA(dst, b, h) do { _Pragma("unroll") for (int m = 0; m < 4; ++m) _Pragma("unroll") for (int k = 0; k < 2; ++k) dst[m][k] = *(const LAS bf16x8*)(lds + PG8_SA(b, h) + aoff + m * 2048 + k * 1024); } while (0)
; #define PG8_LDB(dst, b, h) do { _Pragma("unroll") for (int n = 0; n < 2; ++n) _Pragma("unroll") for (int k = 0; k < 2; ++k) dst[n][k] = *(const LAS bf16x8*)(lds + PG8_SB(b, h) + boff + n * 2048 + k * 1024); } while (0)
; #define PG8_MMA(ai, bj, At, Bt) do { __builtin_amdgcn_s_setprio(1); _Pragma("unroll") for (int m = 0; m < 4; ++m) _Pragma("unroll") for (int n = 0; n < 2; ++n) _Pragma("unroll") for (int k = 0; k < 2; ++k) \
;         acc[ai][bj][m][n] = __builtin_amdgcn_mfma_f32_16x16x32_bf16(Bt[n][k], At[m][k], acc[ai][bj][m][n], 0, 0, 0); __builtin_amdgcn_s_setprio(0); } while (0)
; #define PG8_WAIT_V(n) asm volatile("s_waitcnt vmcnt(" #n ")" ::: "memory")
; #define PG8_WAIT_L(n) asm volatile("s_waitcnt lgkmcnt(" #n ")" ::: "memory")
; #define PG8_BAR __builtin_amdgcn_s_barrier()
; #define PG8_SCHED __builtin_amdgcn_sched_barrier(0)
; template <class Epi, class Sched>
; __device__ __forceinline__ void gemm_phase(LAS unsigned char* lds, const Gemm g, const Sched& S, const Epi& E) {
;     ...
;             const char* a1 = cA + (size_t)(t + 1) * kstepA;
;             const char* a2 = last ? nA : cA + (size_t)(t + 2) * kstepA; const char* b2 = last ? nB : cB + (size_t)(t + 2) * kstep;
;             const char* a3 = a2 + kstepA; const char* b3 = b2 + kstep;
;             PG8_LDB(B0, 0, 0); PG8_LDB(B1, 0, 1); PG8_SCHED; PG8_LDA(At, 0, 0); PG8_STAGE(PG8_SA(1, 1), a1 + hstepA, voffA);
;             PG8_WAIT_V(8); PG8_WAIT_L(0); PG8_BAR; PG8_MMA(0, 0, At, B0); PG8_MMA(0, 1, At, B1); PG8_BAR; PG8_SCHED;
;             PG8_LDA(At, 0, 1); PG8_STAGE(PG8_SB(0, 0), b2, voffB); PG8_STAGE(PG8_SB(0, 1), b2 + hstepB, voffB); PG8_STAGE(PG8_SA(0, 0), a2, voffA);
;             PG8_WAIT_V(8); PG8_WAIT_L(0); PG8_BAR; PG8_MMA(1, 0, At, B0); PG8_MMA(1, 1, At, B1); PG8_BAR; PG8_SCHED;
.LBB0_780:
	v_add_u32_e32 v146, 0x10000, v152
	ds_read_b128 v[154:157], v146
	ds_read_b128 v[158:161], v146 offset:1024
	ds_read_b128 v[166:169], v146 offset:2048
	ds_read_b128 v[170:173], v146 offset:3072
	v_add_u32_e32 v146, 0x14000, v152
	ds_read_b128 v[174:177], v146
	ds_read_b128 v[178:181], v146 offset:1024
	ds_read_b128 v[182:185], v146 offset:2048
	ds_read_b128 v[186:189], v146 offset:3072
	s_add_u32 s98, s12, 0x10000
	s_addc_u32 s99, s13, 0
	s_cmp_eq_u32 s73, 60
	s_cselect_b32 s18, s65, s98
	s_cselect_b32 s19, s9, s99
	s_cselect_b32 s16, s44, s45
	s_cselect_b32 s17, s11, s72
	s_add_u32 s14, s18, 0x8000
	s_addc_u32 s15, s19, 0
	ds_read_b128 v[190:193], v153
	ds_read_b128 v[194:197], v153 offset:1024
	ds_read_b128 v[198:201], v153 offset:2048
	ds_read_b128 v[202:205], v153 offset:3072
	ds_read_b128 v[206:209], v153 offset:4096
	ds_read_b128 v[210:213], v153 offset:5120
	ds_read_b128 v[214:217], v153 offset:6144
	ds_read_b128 v[218:221], v153 offset:7168
	s_add_u32 s12, s12, 0xa000
	s_addc_u32 s13, s13, 0
	s_mov_b32 m0, s62
	s_nop 0
	global_load_lds_dwordx4 v148, s[12:13]
	s_add_i32 s74, s21, 0xe000
	s_mov_b32 m0, s74
	s_nop 0
	global_load_lds_dwordx4 v150, s[12:13]
	s_waitcnt vmcnt(8)
	s_waitcnt lgkmcnt(0)
	s_barrier
	s_setprio 1
	s_waitcnt lgkmcnt(7)
	v_mfma_f32_16x16x32_bf16 v[126:129], v[154:157], v[190:193], v[126:129]
	v_mfma_f32_16x16x32_bf16 v[122:125], v[166:169], v[190:193], v[122:125]
	s_waitcnt lgkmcnt(5)
	v_mfma_f32_16x16x32_bf16 v[110:113], v[154:157], v[198:201], v[110:113]
	v_mfma_f32_16x16x32_bf16 v[106:109], v[166:169], v[198:201], v[106:109]
	s_waitcnt lgkmcnt(3)
	v_mfma_f32_16x16x32_bf16 v[94:97], v[154:157], v[206:209], v[94:97]
	v_mfma_f32_16x16x32_bf16 v[90:93], v[166:169], v[206:209], v[90:93]
	s_waitcnt lgkmcnt(1)
	v_mfma_f32_16x16x32_bf16 v[78:81], v[154:157], v[214:217], v[78:81]
	v_mfma_f32_16x16x32_bf16 v[74:77], v[166:169], v[214:217], v[74:77]
	v_mfma_f32_16x16x32_bf16 v[126:129], v[158:161], v[194:197], v[126:129]
	v_mfma_f32_16x16x32_bf16 v[122:125], v[170:173], v[194:197], v[122:125]
	v_mfma_f32_16x16x32_bf16 v[110:113], v[158:161], v[202:205], v[110:113]
	v_mfma_f32_16x16x32_bf16 v[106:109], v[170:173], v[202:205], v[106:109]
	v_mfma_f32_16x16x32_bf16 v[94:97], v[158:161], v[210:213], v[94:97]
	v_mfma_f32_16x16x32_bf16 v[90:93], v[170:173], v[210:213], v[90:93]
	s_waitcnt lgkmcnt(0)
	v_mfma_f32_16x16x32_bf16 v[78:81], v[158:161], v[218:221], v[78:81]
	v_mfma_f32_16x16x32_bf16 v[74:77], v[170:173], v[218:221], v[74:77]
	s_setprio 0
	s_setprio 1
	v_mfma_f32_16x16x32_bf16 v[118:121], v[174:177], v[190:193], v[118:121]
	v_mfma_f32_16x16x32_bf16 v[114:117], v[182:185], v[190:193], v[114:117]
	v_mfma_f32_16x16x32_bf16 v[102:105], v[174:177], v[198:201], v[102:105]
	v_mfma_f32_16x16x32_bf16 v[98:101], v[182:185], v[198:201], v[98:101]
	v_mfma_f32_16x16x32_bf16 v[86:89], v[174:177], v[206:209], v[86:89]
	v_mfma_f32_16x16x32_bf16 v[82:85], v[182:185], v[206:209], v[82:85]
	v_mfma_f32_16x16x32_bf16 v[70:73], v[174:177], v[214:217], v[70:73]
	v_mfma_f32_16x16x32_bf16 v[66:69], v[182:185], v[214:217], v[66:69]
	v_mfma_f32_16x16x32_bf16 v[118:121], v[178:181], v[194:197], v[118:121]
	v_mfma_f32_16x16x32_bf16 v[114:117], v[186:189], v[194:197], v[114:117]
	v_mfma_f32_16x16x32_bf16 v[102:105], v[178:181], v[202:205], v[102:105]
	v_mfma_f32_16x16x32_bf16 v[98:101], v[186:189], v[202:205], v[98:101]
	v_mfma_f32_16x16x32_bf16 v[86:89], v[178:181], v[210:213], v[86:89]
	v_mfma_f32_16x16x32_bf16 v[82:85], v[186:189], v[210:213], v[82:85]
	v_mfma_f32_16x16x32_bf16 v[70:73], v[178:181], v[218:221], v[70:73]
	v_mfma_f32_16x16x32_bf16 v[66:69], v[186:189], v[218:221], v[66:69]
	s_setprio 0
	s_barrier
	ds_read_b128 v[190:193], v153 offset:16384
	ds_read_b128 v[194:197], v153 offset:17408
	ds_read_b128 v[198:201], v153 offset:18432
	ds_read_b128 v[202:205], v153 offset:19456
	ds_read_b128 v[206:209], v153 offset:20480
	ds_read_b128 v[210:213], v153 offset:21504
	ds_read_b128 v[214:217], v153 offset:22528
	ds_read_b128 v[218:221], v153 offset:23552
	s_mov_b32 m0, s22
	s_nop 0
	global_load_lds_dwordx4 v149, s[16:17]
	s_nop 0
	s_mov_b32 m0, s23
	s_nop 0
	global_load_lds_dwordx4 v151, s[16:17]
	s_add_u32 s12, s16, 0x100000
	s_addc_u32 s13, s17, 0
	s_mov_b32 m0, s24
	s_nop 0
	global_load_lds_dwordx4 v149, s[12:13]
	s_nop 0
	s_mov_b32 m0, s25
	s_nop 0
	global_load_lds_dwordx4 v151, s[12:13]
	s_mov_b32 m0, s21
	s_nop 0
	global_load_lds_dwordx4 v148, s[18:19]
	s_nop 0
	s_mov_b32 m0, s26
	s_nop 0
	global_load_lds_dwordx4 v150, s[18:19]
	s_waitcnt vmcnt(8)
	s_waitcnt lgkmcnt(0)
	s_barrier
; #define PG8_LDA(dst, b, h) do { _Pragma("unroll") for (int m = 0; m < 4; ++m) _Pragma("unroll") for (int k = 0; k < 2; ++k) dst[m][k] = *(const LAS bf16x8*)(lds + PG8_SA(b, h) + aoff + m * 2048 + k * 1024); } while (0)
; #define PG8_LDB(dst, b, h) do { _Pragma("unroll") for (int n = 0; n < 2; ++n) _Pragma("unroll") for (int k = 0; k < 2; ++k) dst[n][k] = *(const LAS bf16x8*)(lds + PG8_SB(b, h) + boff + n * 2048 + k * 1024); } while (0)
; #define PG8_MMA(ai, bj, At, Bt) do { __builtin_amdgcn_s_setprio(1); _Pragma("unroll") for (int m = 0; m < 4; ++m) _Pragma("unroll") for (int n = 0; n < 2; ++n) _Pragma("unroll") for (int k = 0; k < 2; ++k) \
;         acc[ai][bj][m][n] = __builtin_amdgcn_mfma_f32_16x16x32_bf16(Bt[n][k], At[m][k], acc[ai][bj][m][n], 0, 0, 0); __builtin_amdgcn_s_setprio(0); } while (0)
; #define PG8_WAIT_V(n) asm volatile("s_waitcnt vmcnt(" #n ")" ::: "memory")
; #define PG8_WAIT_L(n) asm volatile("s_waitcnt lgkmcnt(" #n ")" ::: "memory")
; #define PG8_BAR __builtin_amdgcn_s_barrier()
; #define PG8_SCHED __builtin_amdgcn_sched_barrier(0)
; template <class Epi, class Sched>
; __device__ __forceinline__ void gemm_phase(LAS unsigned char* lds, const Gemm g, const Sched& S, const Epi& E) {
;     ...
;             PG8_WAIT_V(8); PG8_WAIT_L(0); PG8_BAR; PG8_MMA(1, 0, At, B0); PG8_MMA(1, 1, At, B1); PG8_BAR; PG8_SCHED;
;             PG8_LDB(B0, 1, 0); PG8_LDB(B1, 1, 1); PG8_SCHED; PG8_LDA(At, 1, 0); PG8_STAGE(PG8_SA(0, 1), a2 + hstepA, voffA);
;             PG8_WAIT_V(8); PG8_WAIT_L(0); PG8_BAR; PG8_MMA(0, 0, At, B0); PG8_MMA(0, 1, At, B1); PG8_BAR; PG8_SCHED;
	s_setprio 1
	s_waitcnt lgkmcnt(7)
	v_mfma_f32_16x16x32_bf16 v[62:65], v[154:157], v[190:193], v[62:65]
	v_mfma_f32_16x16x32_bf16 v[58:61], v[166:169], v[190:193], v[58:61]
	s_waitcnt lgkmcnt(5)
	v_mfma_f32_16x16x32_bf16 v[46:49], v[154:157], v[198:201], v[46:49]
	v_mfma_f32_16x16x32_bf16 v[42:45], v[166:169], v[198:201], v[42:45]
	s_waitcnt lgkmcnt(3)
	v_mfma_f32_16x16x32_bf16 v[30:33], v[154:157], v[206:209], v[30:33]
	v_mfma_f32_16x16x32_bf16 v[26:29], v[166:169], v[206:209], v[26:29]
	s_waitcnt lgkmcnt(1)
	v_mfma_f32_16x16x32_bf16 v[14:17], v[154:157], v[214:217], v[14:17]
	v_mfma_f32_16x16x32_bf16 v[10:13], v[166:169], v[214:217], v[10:13]
	v_mfma_f32_16x16x32_bf16 v[62:65], v[158:161], v[194:197], v[62:65]
	v_mfma_f32_16x16x32_bf16 v[58:61], v[170:173], v[194:197], v[58:61]
	v_mfma_f32_16x16x32_bf16 v[46:49], v[158:161], v[202:205], v[46:49]
	v_mfma_f32_16x16x32_bf16 v[42:45], v[170:173], v[202:205], v[42:45]
	v_mfma_f32_16x16x32_bf16 v[30:33], v[158:161], v[210:213], v[30:33]
	v_mfma_f32_16x16x32_bf16 v[26:29], v[170:173], v[210:213], v[26:29]
	s_waitcnt lgkmcnt(0)
	v_mfma_f32_16x16x32_bf16 v[14:17], v[158:161], v[218:221], v[14:17]
	v_mfma_f32_16x16x32_bf16 v[10:13], v[170:173], v[218:221], v[10:13]
	s_setprio 0
	s_setprio 1
	v_mfma_f32_16x16x32_bf16 v[54:57], v[174:177], v[190:193], v[54:57]
	v_mfma_f32_16x16x32_bf16 v[50:53], v[182:185], v[190:193], v[50:53]
	v_mfma_f32_16x16x32_bf16 v[38:41], v[174:177], v[198:201], v[38:41]
	v_mfma_f32_16x16x32_bf16 v[34:37], v[182:185], v[198:201], v[34:37]
	v_mfma_f32_16x16x32_bf16 v[22:25], v[174:177], v[206:209], v[22:25]
	v_mfma_f32_16x16x32_bf16 v[18:21], v[182:185], v[206:209], v[18:21]
	v_mfma_f32_16x16x32_bf16 v[6:9], v[174:177], v[214:217], v[6:9]
	v_mfma_f32_16x16x32_bf16 v[2:5], v[182:185], v[214:217], v[2:5]
	v_mfma_f32_16x16x32_bf16 v[54:57], v[178:181], v[194:197], v[54:57]
	v_mfma_f32_16x16x32_bf16 v[50:53], v[186:189], v[194:197], v[50:53]
	v_mfma_f32_16x16x32_bf16 v[38:41], v[178:181], v[202:205], v[38:41]
	v_mfma_f32_16x16x32_bf16 v[34:37], v[186:189], v[202:205], v[34:37]
	v_mfma_f32_16x16x32_bf16 v[22:25], v[178:181], v[210:213], v[22:25]
	v_mfma_f32_16x16x32_bf16 v[18:21], v[186:189], v[210:213], v[18:21]
	v_mfma_f32_16x16x32_bf16 v[6:9], v[178:181], v[218:221], v[6:9]
	v_mfma_f32_16x16x32_bf16 v[2:5], v[186:189], v[218:221], v[2:5]
	s_setprio 0
	s_barrier
	v_add_u32_e32 v146, 0x18000, v152
	ds_read_b128 v[154:157], v146
	ds_read_b128 v[158:161], v146 offset:1024
	ds_read_b128 v[166:169], v146 offset:2048
	ds_read_b128 v[170:173], v146 offset:3072
	v_add_u32_e32 v146, 0x1c000, v152
	ds_read_b128 v[174:177], v146
	ds_read_b128 v[178:181], v146 offset:1024
	ds_read_b128 v[182:185], v146 offset:2048
	ds_read_b128 v[186:189], v146 offset:3072
	ds_read_b128 v[190:193], v153 offset:32768
	ds_read_b128 v[194:197], v153 offset:33792
	ds_read_b128 v[198:201], v153 offset:34816
	ds_read_b128 v[202:205], v153 offset:35840
	ds_read_b128 v[206:209], v153 offset:36864
	ds_read_b128 v[210:213], v153 offset:37888
	ds_read_b128 v[214:217], v153 offset:38912
	ds_read_b128 v[218:221], v153 offset:39936
	s_add_u32 s12, s18, 0x2000
	s_addc_u32 s13, s19, 0
	s_mov_b32 m0, s28
	s_nop 0
	global_load_lds_dwordx4 v148, s[12:13]
	s_nop 0
	s_mov_b32 m0, s30
	s_nop 0
	global_load_lds_dwordx4 v150, s[12:13]
	s_waitcnt vmcnt(8)
	s_waitcnt lgkmcnt(0)
	s_barrier
	s_setprio 1
	s_waitcnt lgkmcnt(7)
	v_mfma_f32_16x16x32_bf16 v[126:129], v[154:157], v[190:193], v[126:129]
	v_mfma_f32_16x16x32_bf16 v[122:125], v[166:169], v[190:193], v[122:125]
	s_waitcnt lgkmcnt(5)
	v_mfma_f32_16x16x32_bf16 v[110:113], v[154:157], v[198:201], v[110:113]
	v_mfma_f32_16x16x32_bf16 v[106:109], v[166:169], v[198:201], v[106:109]
	s_waitcnt lgkmcnt(3)
	v_mfma_f32_16x16x32_bf16 v[94:97], v[154:157], v[206:209], v[94:97]
	v_mfma_f32_16x16x32_bf16 v[90:93], v[166:169], v[206:209], v[90:93]
	s_waitcnt lgkmcnt(1)
	v_mfma_f32_16x16x32_bf16 v[78:81], v[154:157], v[214:217], v[78:81]
	v_mfma_f32_16x16x32_bf16 v[74:77], v[166:169], v[214:217], v[74:77]
	v_mfma_f32_16x16x32_bf16 v[126:129], v[158:161], v[194:197], v[126:129]
	v_mfma_f32_16x16x32_bf16 v[122:125], v[170:173], v[194:197], v[122:125]
	v_mfma_f32_16x16x32_bf16 v[110:113], v[158:161], v[202:205], v[110:113]
	v_mfma_f32_16x16x32_bf16 v[106:109], v[170:173], v[202:205], v[106:109]
	v_mfma_f32_16x16x32_bf16 v[94:97], v[158:161], v[210:213], v[94:97]
	v_mfma_f32_16x16x32_bf16 v[90:93], v[170:173], v[210:213], v[90:93]
	s_waitcnt lgkmcnt(0)
	v_mfma_f32_16x16x32_bf16 v[78:81], v[158:161], v[218:221], v[78:81]
	v_mfma_f32_16x16x32_bf16 v[74:77], v[170:173], v[218:221], v[74:77]
	s_setprio 0
	s_setprio 1
	v_mfma_f32_16x16x32_bf16 v[118:121], v[174:177], v[190:193], v[118:121]
	v_mfma_f32_16x16x32_bf16 v[114:117], v[182:185], v[190:193], v[114:117]
	v_mfma_f32_16x16x32_bf16 v[102:105], v[174:177], v[198:201], v[102:105]
	v_mfma_f32_16x16x32_bf16 v[98:101], v[182:185], v[198:201], v[98:101]
	v_mfma_f32_16x16x32_bf16 v[86:89], v[174:177], v[206:209], v[86:89]
	v_mfma_f32_16x16x32_bf16 v[82:85], v[182:185], v[206:209], v[82:85]
	v_mfma_f32_16x16x32_bf16 v[70:73], v[174:177], v[214:217], v[70:73]
	v_mfma_f32_16x16x32_bf16 v[66:69], v[182:185], v[214:217], v[66:69]
	v_mfma_f32_16x16x32_bf16 v[118:121], v[178:181], v[194:197], v[118:121]
	v_mfma_f32_16x16x32_bf16 v[114:117], v[186:189], v[194:197], v[114:117]
	v_mfma_f32_16x16x32_bf16 v[102:105], v[178:181], v[202:205], v[102:105]
	v_mfma_f32_16x16x32_bf16 v[98:101], v[186:189], v[202:205], v[98:101]
	v_mfma_f32_16x16x32_bf16 v[86:89], v[178:181], v[210:213], v[86:89]
	v_mfma_f32_16x16x32_bf16 v[82:85], v[186:189], v[210:213], v[82:85]
	v_mfma_f32_16x16x32_bf16 v[70:73], v[178:181], v[218:221], v[70:73]
	v_mfma_f32_16x16x32_bf16 v[66:69], v[186:189], v[218:221], v[66:69]
	s_setprio 0
	s_barrier
; #define PG8_LDA(dst, b, h) do { _Pragma("unroll") for (int m = 0; m < 4; ++m) _Pragma("unroll") for (int k = 0; k < 2; ++k) dst[m][k] = *(const LAS bf16x8*)(lds + PG8_SA(b, h) + aoff + m * 2048 + k * 1024); } while (0)
; #define PG8_MMA(ai, bj, At, Bt) do { __builtin_amdgcn_s_setprio(1); _Pragma("unroll") for (int m = 0; m < 4; ++m) _Pragma("unroll") for (int n = 0; n < 2; ++n) _Pragma("unroll") for (int k = 0; k < 2; ++k) \
;         acc[ai][bj][m][n] = __builtin_amdgcn_mfma_f32_16x16x32_bf16(Bt[n][k], At[m][k], acc[ai][bj][m][n], 0, 0, 0); __builtin_amdgcn_s_setprio(0); } while (0)
; #define PG8_WAIT_V(n) asm volatile("s_waitcnt vmcnt(" #n ")" ::: "memory")
; #define PG8_WAIT_L(n) asm volatile("s_waitcnt lgkmcnt(" #n ")" ::: "memory")
; #define PG8_BAR __builtin_amdgcn_s_barrier()
; #define PG8_SCHED __builtin_amdgcn_sched_barrier(0)
; template <class Epi, class Sched>
; __device__ __forceinline__ void gemm_phase(LAS unsigned char* lds, const Gemm g, const Sched& S, const Epi& E) {
;     ...
;             PG8_LDA(At, 1, 1); PG8_STAGE(PG8_SB(1, 0), b3, voffB); PG8_STAGE(PG8_SB(1, 1), b3 + hstepB, voffB); PG8_STAGE(PG8_SA(1, 0), a3, voffA);
;             PG8_WAIT_V(8); PG8_WAIT_L(0); PG8_BAR; PG8_MMA(1, 0, At, B0); PG8_MMA(1, 1, At, B1); PG8_BAR; PG8_SCHED;
;         }
;         if (wr == 0) PG8_BAR;
	ds_read_b128 v[190:193], v153 offset:49152
	ds_read_b128 v[194:197], v153 offset:50176
	ds_read_b128 v[198:201], v153 offset:51200
	ds_read_b128 v[202:205], v153 offset:52224
	ds_read_b128 v[206:209], v153 offset:53248
	ds_read_b128 v[210:213], v153 offset:54272
	ds_read_b128 v[214:217], v153 offset:55296
	ds_read_b128 v[218:221], v153 offset:56320
	s_add_u32 s12, s16, 0x80
	s_addc_u32 s13, s17, 0
	s_mov_b32 m0, s31
	s_nop 0
	global_load_lds_dwordx4 v149, s[12:13]
	s_nop 0
	s_mov_b32 m0, s35
	s_nop 0
	global_load_lds_dwordx4 v151, s[12:13]
	s_add_u32 s12, s16, 0x100080
	s_addc_u32 s13, s17, 0
	s_mov_b32 m0, s48
	s_nop 0
	global_load_lds_dwordx4 v149, s[12:13]
	s_nop 0
	s_mov_b32 m0, s49
	s_nop 0
	global_load_lds_dwordx4 v151, s[12:13]
	s_mov_b32 m0, s38
	s_nop 0
	global_load_lds_dwordx4 v148, s[14:15]
	s_nop 0
	s_mov_b32 m0, s39
	s_nop 0
	global_load_lds_dwordx4 v150, s[14:15]
	s_waitcnt vmcnt(8)
	s_waitcnt lgkmcnt(0)
	s_barrier
	s_setprio 1
	s_waitcnt lgkmcnt(7)
	v_mfma_f32_16x16x32_bf16 v[62:65], v[154:157], v[190:193], v[62:65]
	v_mfma_f32_16x16x32_bf16 v[58:61], v[166:169], v[190:193], v[58:61]
	s_waitcnt lgkmcnt(5)
	v_mfma_f32_16x16x32_bf16 v[46:49], v[154:157], v[198:201], v[46:49]
	v_mfma_f32_16x16x32_bf16 v[42:45], v[166:169], v[198:201], v[42:45]
	s_waitcnt lgkmcnt(3)
	v_mfma_f32_16x16x32_bf16 v[30:33], v[154:157], v[206:209], v[30:33]
	v_mfma_f32_16x16x32_bf16 v[26:29], v[166:169], v[206:209], v[26:29]
	s_waitcnt lgkmcnt(1)
	v_mfma_f32_16x16x32_bf16 v[14:17], v[154:157], v[214:217], v[14:17]
	v_mfma_f32_16x16x32_bf16 v[10:13], v[166:169], v[214:217], v[10:13]
	v_mfma_f32_16x16x32_bf16 v[62:65], v[158:161], v[194:197], v[62:65]
	v_mfma_f32_16x16x32_bf16 v[58:61], v[170:173], v[194:197], v[58:61]
	v_mfma_f32_16x16x32_bf16 v[46:49], v[158:161], v[202:205], v[46:49]
	v_mfma_f32_16x16x32_bf16 v[42:45], v[170:173], v[202:205], v[42:45]
	v_mfma_f32_16x16x32_bf16 v[30:33], v[158:161], v[210:213], v[30:33]
	v_mfma_f32_16x16x32_bf16 v[26:29], v[170:173], v[210:213], v[26:29]
	s_waitcnt lgkmcnt(0)
	v_mfma_f32_16x16x32_bf16 v[14:17], v[158:161], v[218:221], v[14:17]
	v_mfma_f32_16x16x32_bf16 v[10:13], v[170:173], v[218:221], v[10:13]
	s_setprio 0
	s_setprio 1
	v_mfma_f32_16x16x32_bf16 v[54:57], v[174:177], v[190:193], v[54:57]
	v_mfma_f32_16x16x32_bf16 v[50:53], v[182:185], v[190:193], v[50:53]
	v_mfma_f32_16x16x32_bf16 v[38:41], v[174:177], v[198:201], v[38:41]
	v_mfma_f32_16x16x32_bf16 v[34:37], v[182:185], v[198:201], v[34:37]
	v_mfma_f32_16x16x32_bf16 v[22:25], v[174:177], v[206:209], v[22:25]
	v_mfma_f32_16x16x32_bf16 v[18:21], v[182:185], v[206:209], v[18:21]
	v_mfma_f32_16x16x32_bf16 v[6:9], v[174:177], v[214:217], v[6:9]
	v_mfma_f32_16x16x32_bf16 v[2:5], v[182:185], v[214:217], v[2:5]
	v_mfma_f32_16x16x32_bf16 v[54:57], v[178:181], v[194:197], v[54:57]
	v_mfma_f32_16x16x32_bf16 v[50:53], v[186:189], v[194:197], v[50:53]
	v_mfma_f32_16x16x32_bf16 v[38:41], v[178:181], v[202:205], v[38:41]
	v_mfma_f32_16x16x32_bf16 v[34:37], v[186:189], v[202:205], v[34:37]
	v_mfma_f32_16x16x32_bf16 v[22:25], v[178:181], v[210:213], v[22:25]
	v_mfma_f32_16x16x32_bf16 v[18:21], v[186:189], v[210:213], v[18:21]
	v_mfma_f32_16x16x32_bf16 v[6:9], v[178:181], v[218:221], v[6:9]
	v_mfma_f32_16x16x32_bf16 v[2:5], v[186:189], v[218:221], v[2:5]
	s_setprio 0
	s_barrier
	s_add_i32 s73, s73, 2
	s_add_u32 s45, s45, 0x100
	s_addc_u32 s72, s72, 0
	s_cmp_gt_u32 s73, 61
	s_mov_b64 s[12:13], s[98:99]
	s_cbranch_scc0 .LBB0_780
	s_and_b64 vcc, exec, s[6:7]
	s_cbranch_vccz .LBB0_783
	s_barrier
